# DN chunk-local: akk/aqk 64x64x128 products moved from LDS-broadcast VALU loop to f32 matrix cores (v_mfma_f32_32x32x2_f32, operands straight from global), decay/Ls/QK stores rewritten for the MFMA lay
# speedup vs baseline: 1.3029x; 1.0584x over previous
; #define CL_LOAD(d0) do { _Pragma("unroll") for (int i = 0; i < 8; ++i) { const int idx = tid + 256 * i, rr = idx >> 5, dd = idx & 31; \
;       const float* src = CQ + (size_t)(row0 + rstep * rr) * 1536 + hd * 128 + (d0) + dd; pq[i] = src[0]; pk[i] = src[512]; } } while (0)
; NI void dn_chunk_local(const P& p, int dh, int n, char* lds) {
;     ...
;   const int c = tid & 63, sg = tid >> 6;
;   float akk[16], aqk[16];
; #pragma unroll
;   for (int i = 0; i < 16; ++i) { akk[i] = 0.f; aqk[i] = 0.f; }
;   float pq[8], pk[8];
;     ...
;   CL_LOAD(0);
;   for (int d0 = 0; d0 < 128; d0 += 32) {
;     __syncthreads();
; #pragma unroll
;     for (int i = 0; i < 8; ++i) { const int idx = tid + 256 * i, rr = idx >> 5, dd = idx & 31; qS[rr * 33 + dd] = pq[i]; kS[rr * 33 + dd] = pk[i]; }
;     __syncthreads();
;     if (d0 + 32 < 128) CL_LOAD(d0 + 32);
;     for (int d = 0; d < 32; ++d) {
;       const float kc = kS[c * 33 + d], qc = qS[c * 33 + d];
; #pragma unroll
;       for (int i = 0; i < 16; ++i) { const float ks = kS[(sg * 16 + i) * 33 + d]; akk[i] += kc * ks; aqk[i] += qc * ks; }
;     }
;   }
.LBB0_241:
	s_or_b64 exec, exec, s[10:11]
	v_readfirstlane_b32 s1, v4
	v_and_b32_e32 v5, 31, v4
	v_bfe_u32 v90, v4, 5, 1
	s_lshr_b32 s1, s1, 6
	s_and_b32 s10, s1, 1
	s_lshr_b32 s11, s1, 1
	s_lshl_b32 s18, s10, 5
	s_lshl_b32 s74, s16, 9
	s_xor_b32 s22, s11, 1
	s_lshl_b32 s22, s22, 11
	s_add_i32 s22, s22, s74
	s_add_i32 s23, s74, 0x800
	s_movk_i32 s1, 0x1800
	v_add_u32_e32 v91, s18, v5
	v_mul_lo_u32 v91, v91, s26
	v_add_u32_e32 v91, s25, v91
	v_mul_lo_u32 v92, v5, s26
	v_add_u32_e32 v92, s25, v92
	v_add_u32_e32 v93, 32, v5
	v_mul_lo_u32 v93, v93, s26
	v_add_u32_e32 v93, s25, v93
	v_lshlrev_b32_e32 v94, 4, v90
	v_mul_lo_u32 v0, v91, s1
	v_add3_u32 v0, v0, v94, s22
	v_mov_b32_e32 v1, 0
	v_lshl_add_u64 v[0:1], s[30:31], 0, v[0:1]
	v_mul_lo_u32 v2, v92, s1
	v_add3_u32 v2, v2, v94, s23
	v_mov_b32_e32 v3, 0
	v_lshl_add_u64 v[2:3], s[30:31], 0, v[2:3]
	v_mul_lo_u32 v6, v93, s1
	v_add3_u32 v6, v6, v94, s23
	v_mov_b32_e32 v7, 0
	v_lshl_add_u64 v[6:7], s[30:31], 0, v[6:7]
	global_load_dwordx4 v[42:45], v[0:1], off offset:0
	global_load_dwordx4 v[58:61], v[2:3], off offset:0
	global_load_dwordx4 v[74:77], v[6:7], off offset:0
	global_load_dwordx4 v[46:49], v[0:1], off offset:32
	global_load_dwordx4 v[62:65], v[2:3], off offset:32
	global_load_dwordx4 v[78:81], v[6:7], off offset:32
	global_load_dwordx4 v[50:53], v[0:1], off offset:64
	global_load_dwordx4 v[66:69], v[2:3], off offset:64
	global_load_dwordx4 v[82:85], v[6:7], off offset:64
	global_load_dwordx4 v[54:57], v[0:1], off offset:96
	global_load_dwordx4 v[70:73], v[2:3], off offset:96
	global_load_dwordx4 v[86:89], v[6:7], off offset:96
	global_load_dwordx4 v[98:101], v[0:1], off offset:128
	global_load_dwordx4 v[114:117], v[2:3], off offset:128
	global_load_dwordx4 v[130:133], v[6:7], off offset:128
	global_load_dwordx4 v[102:105], v[0:1], off offset:160
	global_load_dwordx4 v[118:121], v[2:3], off offset:160
	global_load_dwordx4 v[134:137], v[6:7], off offset:160
	global_load_dwordx4 v[106:109], v[0:1], off offset:192
	global_load_dwordx4 v[122:125], v[2:3], off offset:192
	global_load_dwordx4 v[138:141], v[6:7], off offset:192
	global_load_dwordx4 v[110:113], v[0:1], off offset:224
	global_load_dwordx4 v[126:129], v[2:3], off offset:224
	global_load_dwordx4 v[142:145], v[6:7], off offset:224
	global_load_dwordx4 v[146:149], v[0:1], off offset:256
	global_load_dwordx4 v[162:165], v[2:3], off offset:256
	global_load_dwordx4 v[178:181], v[6:7], off offset:256
	global_load_dwordx4 v[150:153], v[0:1], off offset:288
	global_load_dwordx4 v[166:169], v[2:3], off offset:288
	global_load_dwordx4 v[182:185], v[6:7], off offset:288
	global_load_dwordx4 v[154:157], v[0:1], off offset:320
	global_load_dwordx4 v[170:173], v[2:3], off offset:320
	global_load_dwordx4 v[190:193], v[6:7], off offset:320
	global_load_dwordx4 v[158:161], v[0:1], off offset:352
	global_load_dwordx4 v[174:177], v[2:3], off offset:352
	global_load_dwordx4 v[194:197], v[6:7], off offset:352
	v_mov_b32_e32 v8, 0
	v_mov_b32_e32 v9, 0
	v_mov_b32_e32 v10, 0
	v_mov_b32_e32 v11, 0
	v_mov_b32_e32 v12, 0
	v_mov_b32_e32 v13, 0
	v_mov_b32_e32 v14, 0
	v_mov_b32_e32 v15, 0
	v_mov_b32_e32 v16, 0
	v_mov_b32_e32 v17, 0
	v_mov_b32_e32 v18, 0
	v_mov_b32_e32 v19, 0
	v_mov_b32_e32 v20, 0
	v_mov_b32_e32 v21, 0
	v_mov_b32_e32 v22, 0
	v_mov_b32_e32 v23, 0
	v_mov_b32_e32 v24, 0
	v_mov_b32_e32 v25, 0
	v_mov_b32_e32 v26, 0
	v_mov_b32_e32 v27, 0
	v_mov_b32_e32 v28, 0
	v_mov_b32_e32 v29, 0
	v_mov_b32_e32 v30, 0
	v_mov_b32_e32 v31, 0
	v_mov_b32_e32 v32, 0
	v_mov_b32_e32 v33, 0
	v_mov_b32_e32 v34, 0
	v_mov_b32_e32 v35, 0
	v_mov_b32_e32 v36, 0
	v_mov_b32_e32 v37, 0
	v_mov_b32_e32 v38, 0
	v_mov_b32_e32 v39, 0
	s_nop 1
	s_waitcnt vmcnt(24)
	v_mfma_f32_32x32x2_f32 v[8:23], v42, v58, v[8:23]
	v_mfma_f32_32x32x2_f32 v[24:39], v42, v74, v[24:39]
	v_mfma_f32_32x32x2_f32 v[8:23], v43, v59, v[8:23]
	v_mfma_f32_32x32x2_f32 v[24:39], v43, v75, v[24:39]
	v_mfma_f32_32x32x2_f32 v[8:23], v44, v60, v[8:23]
	v_mfma_f32_32x32x2_f32 v[24:39], v44, v76, v[24:39]
	v_mfma_f32_32x32x2_f32 v[8:23], v45, v61, v[8:23]
	v_mfma_f32_32x32x2_f32 v[24:39], v45, v77, v[24:39]
	v_mfma_f32_32x32x2_f32 v[8:23], v46, v62, v[8:23]
	v_mfma_f32_32x32x2_f32 v[24:39], v46, v78, v[24:39]
	v_mfma_f32_32x32x2_f32 v[8:23], v47, v63, v[8:23]
	v_mfma_f32_32x32x2_f32 v[24:39], v47, v79, v[24:39]
	v_mfma_f32_32x32x2_f32 v[8:23], v48, v64, v[8:23]
	v_mfma_f32_32x32x2_f32 v[24:39], v48, v80, v[24:39]
	v_mfma_f32_32x32x2_f32 v[8:23], v49, v65, v[8:23]
	v_mfma_f32_32x32x2_f32 v[24:39], v49, v81, v[24:39]
	v_mfma_f32_32x32x2_f32 v[8:23], v50, v66, v[8:23]
	v_mfma_f32_32x32x2_f32 v[24:39], v50, v82, v[24:39]
	v_mfma_f32_32x32x2_f32 v[8:23], v51, v67, v[8:23]
	v_mfma_f32_32x32x2_f32 v[24:39], v51, v83, v[24:39]
	v_mfma_f32_32x32x2_f32 v[8:23], v52, v68, v[8:23]
	v_mfma_f32_32x32x2_f32 v[24:39], v52, v84, v[24:39]
	v_mfma_f32_32x32x2_f32 v[8:23], v53, v69, v[8:23]
	v_mfma_f32_32x32x2_f32 v[24:39], v53, v85, v[24:39]
	v_mfma_f32_32x32x2_f32 v[8:23], v54, v70, v[8:23]
	v_mfma_f32_32x32x2_f32 v[24:39], v54, v86, v[24:39]
	v_mfma_f32_32x32x2_f32 v[8:23], v55, v71, v[8:23]
	v_mfma_f32_32x32x2_f32 v[24:39], v55, v87, v[24:39]
	v_mfma_f32_32x32x2_f32 v[8:23], v56, v72, v[8:23]
	v_mfma_f32_32x32x2_f32 v[24:39], v56, v88, v[24:39]
	v_mfma_f32_32x32x2_f32 v[8:23], v57, v73, v[8:23]
	v_mfma_f32_32x32x2_f32 v[24:39], v57, v89, v[24:39]
	global_load_dwordx4 v[42:45], v[0:1], off offset:384
	global_load_dwordx4 v[58:61], v[2:3], off offset:384
	global_load_dwordx4 v[74:77], v[6:7], off offset:384
	global_load_dwordx4 v[46:49], v[0:1], off offset:416
	global_load_dwordx4 v[62:65], v[2:3], off offset:416
	global_load_dwordx4 v[78:81], v[6:7], off offset:416
	global_load_dwordx4 v[50:53], v[0:1], off offset:448
	global_load_dwordx4 v[66:69], v[2:3], off offset:448
	global_load_dwordx4 v[82:85], v[6:7], off offset:448
	global_load_dwordx4 v[54:57], v[0:1], off offset:480
	global_load_dwordx4 v[70:73], v[2:3], off offset:480
	global_load_dwordx4 v[86:89], v[6:7], off offset:480
	s_waitcnt vmcnt(24)
; NI void dn_chunk_local(const P& p, int dh, int n, char* lds) {
;     ...
;     for (int d = 0; d < 32; ++d) {
;       const float kc = kS[c * 33 + d], qc = qS[c * 33 + d];
; #pragma unroll
;       for (int i = 0; i < 16; ++i) { const float ks = kS[(sg * 16 + i) * 33 + d]; akk[i] += kc * ks; aqk[i] += qc * ks; }
;     }
;   }
;     ...
;   {
;     const float gc_c = gcS[c], beta_c = bS[c];
;     bf16_t* QKo = (bf16_t*)(ws + WS_DQK) + ((size_t)(dh * NCH + n) * 64 + c) * 64;
; #pragma unroll
;     for (int i = 0; i < 16; ++i) {
;       const int s = sg * 16 + i;
;       const float dec = (c >= s) ? expf(gc_c - gcS[s]) : 0.f;
;       Ls[c * 64 + s] = (c > s) ? beta_c * akk[i] * dec : 0.f;
	v_mfma_f32_32x32x2_f32 v[8:23], v98, v114, v[8:23]
	v_mfma_f32_32x32x2_f32 v[24:39], v98, v130, v[24:39]
	v_mfma_f32_32x32x2_f32 v[8:23], v99, v115, v[8:23]
	v_mfma_f32_32x32x2_f32 v[24:39], v99, v131, v[24:39]
	v_mfma_f32_32x32x2_f32 v[8:23], v100, v116, v[8:23]
	v_mfma_f32_32x32x2_f32 v[24:39], v100, v132, v[24:39]
	v_mfma_f32_32x32x2_f32 v[8:23], v101, v117, v[8:23]
	v_mfma_f32_32x32x2_f32 v[24:39], v101, v133, v[24:39]
	v_mfma_f32_32x32x2_f32 v[8:23], v102, v118, v[8:23]
	v_mfma_f32_32x32x2_f32 v[24:39], v102, v134, v[24:39]
	v_mfma_f32_32x32x2_f32 v[8:23], v103, v119, v[8:23]
	v_mfma_f32_32x32x2_f32 v[24:39], v103, v135, v[24:39]
	v_mfma_f32_32x32x2_f32 v[8:23], v104, v120, v[8:23]
	v_mfma_f32_32x32x2_f32 v[24:39], v104, v136, v[24:39]
	v_mfma_f32_32x32x2_f32 v[8:23], v105, v121, v[8:23]
	v_mfma_f32_32x32x2_f32 v[24:39], v105, v137, v[24:39]
	v_mfma_f32_32x32x2_f32 v[8:23], v106, v122, v[8:23]
	v_mfma_f32_32x32x2_f32 v[24:39], v106, v138, v[24:39]
	v_mfma_f32_32x32x2_f32 v[8:23], v107, v123, v[8:23]
	v_mfma_f32_32x32x2_f32 v[24:39], v107, v139, v[24:39]
	v_mfma_f32_32x32x2_f32 v[8:23], v108, v124, v[8:23]
	v_mfma_f32_32x32x2_f32 v[24:39], v108, v140, v[24:39]
	v_mfma_f32_32x32x2_f32 v[8:23], v109, v125, v[8:23]
	v_mfma_f32_32x32x2_f32 v[24:39], v109, v141, v[24:39]
	v_mfma_f32_32x32x2_f32 v[8:23], v110, v126, v[8:23]
	v_mfma_f32_32x32x2_f32 v[24:39], v110, v142, v[24:39]
	v_mfma_f32_32x32x2_f32 v[8:23], v111, v127, v[8:23]
	v_mfma_f32_32x32x2_f32 v[24:39], v111, v143, v[24:39]
	v_mfma_f32_32x32x2_f32 v[8:23], v112, v128, v[8:23]
	v_mfma_f32_32x32x2_f32 v[24:39], v112, v144, v[24:39]
	v_mfma_f32_32x32x2_f32 v[8:23], v113, v129, v[8:23]
	v_mfma_f32_32x32x2_f32 v[24:39], v113, v145, v[24:39]
	s_waitcnt vmcnt(12)
	v_mfma_f32_32x32x2_f32 v[8:23], v146, v162, v[8:23]
	v_mfma_f32_32x32x2_f32 v[24:39], v146, v178, v[24:39]
	v_mfma_f32_32x32x2_f32 v[8:23], v147, v163, v[8:23]
	v_mfma_f32_32x32x2_f32 v[24:39], v147, v179, v[24:39]
	v_mfma_f32_32x32x2_f32 v[8:23], v148, v164, v[8:23]
	v_mfma_f32_32x32x2_f32 v[24:39], v148, v180, v[24:39]
	v_mfma_f32_32x32x2_f32 v[8:23], v149, v165, v[8:23]
	v_mfma_f32_32x32x2_f32 v[24:39], v149, v181, v[24:39]
	v_mfma_f32_32x32x2_f32 v[8:23], v150, v166, v[8:23]
	v_mfma_f32_32x32x2_f32 v[24:39], v150, v182, v[24:39]
	v_mfma_f32_32x32x2_f32 v[8:23], v151, v167, v[8:23]
	v_mfma_f32_32x32x2_f32 v[24:39], v151, v183, v[24:39]
	v_mfma_f32_32x32x2_f32 v[8:23], v152, v168, v[8:23]
	v_mfma_f32_32x32x2_f32 v[24:39], v152, v184, v[24:39]
	v_mfma_f32_32x32x2_f32 v[8:23], v153, v169, v[8:23]
	v_mfma_f32_32x32x2_f32 v[24:39], v153, v185, v[24:39]
	v_mfma_f32_32x32x2_f32 v[8:23], v154, v170, v[8:23]
	v_mfma_f32_32x32x2_f32 v[24:39], v154, v190, v[24:39]
	v_mfma_f32_32x32x2_f32 v[8:23], v155, v171, v[8:23]
	v_mfma_f32_32x32x2_f32 v[24:39], v155, v191, v[24:39]
	v_mfma_f32_32x32x2_f32 v[8:23], v156, v172, v[8:23]
	v_mfma_f32_32x32x2_f32 v[24:39], v156, v192, v[24:39]
	v_mfma_f32_32x32x2_f32 v[8:23], v157, v173, v[8:23]
	v_mfma_f32_32x32x2_f32 v[24:39], v157, v193, v[24:39]
	v_mfma_f32_32x32x2_f32 v[8:23], v158, v174, v[8:23]
	v_mfma_f32_32x32x2_f32 v[24:39], v158, v194, v[24:39]
	v_mfma_f32_32x32x2_f32 v[8:23], v159, v175, v[8:23]
	v_mfma_f32_32x32x2_f32 v[24:39], v159, v195, v[24:39]
	v_mfma_f32_32x32x2_f32 v[8:23], v160, v176, v[8:23]
	v_mfma_f32_32x32x2_f32 v[24:39], v160, v196, v[24:39]
	v_mfma_f32_32x32x2_f32 v[8:23], v161, v177, v[8:23]
	v_mfma_f32_32x32x2_f32 v[24:39], v161, v197, v[24:39]
	s_waitcnt vmcnt(0)
	v_mfma_f32_32x32x2_f32 v[8:23], v42, v58, v[8:23]
	v_mfma_f32_32x32x2_f32 v[24:39], v42, v74, v[24:39]
	v_mfma_f32_32x32x2_f32 v[8:23], v43, v59, v[8:23]
	v_mfma_f32_32x32x2_f32 v[24:39], v43, v75, v[24:39]
	v_mfma_f32_32x32x2_f32 v[8:23], v44, v60, v[8:23]
	v_mfma_f32_32x32x2_f32 v[24:39], v44, v76, v[24:39]
	v_mfma_f32_32x32x2_f32 v[8:23], v45, v61, v[8:23]
	v_mfma_f32_32x32x2_f32 v[24:39], v45, v77, v[24:39]
	v_mfma_f32_32x32x2_f32 v[8:23], v46, v62, v[8:23]
	v_mfma_f32_32x32x2_f32 v[24:39], v46, v78, v[24:39]
	v_mfma_f32_32x32x2_f32 v[8:23], v47, v63, v[8:23]
	v_mfma_f32_32x32x2_f32 v[24:39], v47, v79, v[24:39]
	v_mfma_f32_32x32x2_f32 v[8:23], v48, v64, v[8:23]
	v_mfma_f32_32x32x2_f32 v[24:39], v48, v80, v[24:39]
	v_mfma_f32_32x32x2_f32 v[8:23], v49, v65, v[8:23]
	v_mfma_f32_32x32x2_f32 v[24:39], v49, v81, v[24:39]
	v_mfma_f32_32x32x2_f32 v[8:23], v50, v66, v[8:23]
	v_mfma_f32_32x32x2_f32 v[24:39], v50, v82, v[24:39]
	v_mfma_f32_32x32x2_f32 v[8:23], v51, v67, v[8:23]
	v_mfma_f32_32x32x2_f32 v[24:39], v51, v83, v[24:39]
	v_mfma_f32_32x32x2_f32 v[8:23], v52, v68, v[8:23]
	v_mfma_f32_32x32x2_f32 v[24:39], v52, v84, v[24:39]
	v_mfma_f32_32x32x2_f32 v[8:23], v53, v69, v[8:23]
	v_mfma_f32_32x32x2_f32 v[24:39], v53, v85, v[24:39]
	v_mfma_f32_32x32x2_f32 v[8:23], v54, v70, v[8:23]
	v_mfma_f32_32x32x2_f32 v[24:39], v54, v86, v[24:39]
	v_mfma_f32_32x32x2_f32 v[8:23], v55, v71, v[8:23]
	v_mfma_f32_32x32x2_f32 v[24:39], v55, v87, v[24:39]
	v_mfma_f32_32x32x2_f32 v[8:23], v56, v72, v[8:23]
	v_mfma_f32_32x32x2_f32 v[24:39], v56, v88, v[24:39]
	v_mfma_f32_32x32x2_f32 v[8:23], v57, v73, v[8:23]
	v_mfma_f32_32x32x2_f32 v[24:39], v57, v89, v[24:39]
	v_lshlrev_b32_e32 v91, 2, v90
	v_add_u32_e32 v91, s18, v91
	v_lshlrev_b32_e32 v92, 2, v91
	v_lshlrev_b32_e32 v93, 2, v5
	s_nop 15
	s_nop 3
	ds_read_b128 v[42:45], v92 offset:33280
	ds_read_b128 v[46:49], v92 offset:33312
	ds_read_b128 v[50:53], v92 offset:33344
	ds_read_b128 v[54:57], v92 offset:33376
	ds_read_b128 v[58:61], v92 offset:33536
	ds_read_b128 v[62:65], v92 offset:33568
	ds_read_b128 v[66:69], v92 offset:33600
	ds_read_b128 v[70:73], v92 offset:33632
	ds_read_b32 v74, v93 offset:33280
	ds_read_b32 v75, v93 offset:33408
	v_sub_u32_e32 v76, v91, v5
	v_add_u32_e32 v76, s11, v76
	v_subrev_u32_e32 v77, 32, v76
	s_waitcnt lgkmcnt(0)
	s_cmp_eq_u32 s11, 0
	s_cbranch_scc1 .Ldn_akk_beta_ok
	v_mov_b32_e32 v58, 1.0
	v_mov_b32_e32 v59, 1.0
	v_mov_b32_e32 v60, 1.0
	v_mov_b32_e32 v61, 1.0
	v_mov_b32_e32 v62, 1.0
	v_mov_b32_e32 v63, 1.0
	v_mov_b32_e32 v64, 1.0
	v_mov_b32_e32 v65, 1.0
	v_mov_b32_e32 v66, 1.0
	v_mov_b32_e32 v67, 1.0
	v_mov_b32_e32 v68, 1.0
	v_mov_b32_e32 v69, 1.0
	v_mov_b32_e32 v70, 1.0
	v_mov_b32_e32 v71, 1.0
	v_mov_b32_e32 v72, 1.0
	v_mov_b32_e32 v73, 1.0
; DI bf16_t f2bf(float x) { unsigned u = __float_as_uint(x); u += 0x7fffu + ((u >> 16) & 1u); return (bf16_t)(u >> 16); }
; NI void dn_chunk_local(const P& p, int dh, int n, char* lds) {
;     ...
;   {
;     const float gc_c = gcS[c], beta_c = bS[c];
;     bf16_t* QKo = (bf16_t*)(ws + WS_DQK) + ((size_t)(dh * NCH + n) * 64 + c) * 64;
; #pragma unroll
;     for (int i = 0; i < 16; ++i) {
;       const int s = sg * 16 + i;
;       const float dec = (c >= s) ? expf(gc_c - gcS[s]) : 0.f;
;       Ls[c * 64 + s] = (c > s) ? beta_c * akk[i] * dec : 0.f;
;       QKo[s] = f2bf(aqk[i] * dec);
;     }
;   }
.Ldn_akk_beta_ok:
	s_movk_i32 s1, 0
	v_sub_f32_e32 v78, v42, v74
	v_cmp_lt_i32_e64 s[22:23], s1, v76
	v_mul_f32_e32 v79, 0x3fb8aa3b, v78
	v_fma_f32 v80, v78, s9, -v79
	v_rndne_f32_e32 v81, v79
	v_fmac_f32_e32 v80, 0x32a5705f, v78
	v_sub_f32_e32 v79, v79, v81
	v_add_f32_e32 v79, v79, v80
	v_cvt_i32_f32_e32 v81, v81
	v_exp_f32_e32 v79, v79
	v_cmp_ngt_f32_e32 vcc, s66, v78
	v_mul_f32_e32 v98, v58, v8
	v_ldexp_f32 v79, v79, v81
	s_nop 0
	v_cndmask_b32_e32 v79, 0, v79, vcc
	v_mul_f32_e32 v98, v98, v79
	v_cndmask_b32_e64 v98, 0, v98, s[22:23]
	s_movk_i32 s1, -1
	v_sub_f32_e32 v78, v43, v74
	v_cmp_lt_i32_e64 s[22:23], s1, v76
	v_mul_f32_e32 v79, 0x3fb8aa3b, v78
	v_fma_f32 v80, v78, s9, -v79
	v_rndne_f32_e32 v81, v79
	v_fmac_f32_e32 v80, 0x32a5705f, v78
	v_sub_f32_e32 v79, v79, v81
	v_add_f32_e32 v79, v79, v80
	v_cvt_i32_f32_e32 v81, v81
	v_exp_f32_e32 v79, v79
	v_cmp_ngt_f32_e32 vcc, s66, v78
	v_mul_f32_e32 v99, v59, v9
	v_ldexp_f32 v79, v79, v81
	s_nop 0
	v_cndmask_b32_e32 v79, 0, v79, vcc
	v_mul_f32_e32 v99, v99, v79
	v_cndmask_b32_e64 v99, 0, v99, s[22:23]
	s_movk_i32 s1, -2
	v_sub_f32_e32 v78, v44, v74
	v_cmp_lt_i32_e64 s[22:23], s1, v76
	v_mul_f32_e32 v79, 0x3fb8aa3b, v78
	v_fma_f32 v80, v78, s9, -v79
	v_rndne_f32_e32 v81, v79
	v_fmac_f32_e32 v80, 0x32a5705f, v78
	v_sub_f32_e32 v79, v79, v81
	v_add_f32_e32 v79, v79, v80
	v_cvt_i32_f32_e32 v81, v81
	v_exp_f32_e32 v79, v79
	v_cmp_ngt_f32_e32 vcc, s66, v78
	v_mul_f32_e32 v100, v60, v10
	v_ldexp_f32 v79, v79, v81
	s_nop 0
	v_cndmask_b32_e32 v79, 0, v79, vcc
	v_mul_f32_e32 v100, v100, v79
	v_cndmask_b32_e64 v100, 0, v100, s[22:23]
	s_movk_i32 s1, -3
	v_sub_f32_e32 v78, v45, v74
	v_cmp_lt_i32_e64 s[22:23], s1, v76
	v_mul_f32_e32 v79, 0x3fb8aa3b, v78
	v_fma_f32 v80, v78, s9, -v79
	v_rndne_f32_e32 v81, v79
	v_fmac_f32_e32 v80, 0x32a5705f, v78
	v_sub_f32_e32 v79, v79, v81
	v_add_f32_e32 v79, v79, v80
	v_cvt_i32_f32_e32 v81, v81
	v_exp_f32_e32 v79, v79
	v_cmp_ngt_f32_e32 vcc, s66, v78
	v_mul_f32_e32 v101, v61, v11
	v_ldexp_f32 v79, v79, v81
	s_nop 0
	v_cndmask_b32_e32 v79, 0, v79, vcc
	v_mul_f32_e32 v101, v101, v79
	v_cndmask_b32_e64 v101, 0, v101, s[22:23]
	s_movk_i32 s1, -8
	v_sub_f32_e32 v78, v46, v74
	v_cmp_lt_i32_e64 s[22:23], s1, v76
	v_mul_f32_e32 v79, 0x3fb8aa3b, v78
	v_fma_f32 v80, v78, s9, -v79
	v_rndne_f32_e32 v81, v79
	v_fmac_f32_e32 v80, 0x32a5705f, v78
	v_sub_f32_e32 v79, v79, v81
	v_add_f32_e32 v79, v79, v80
	v_cvt_i32_f32_e32 v81, v81
	v_exp_f32_e32 v79, v79
	v_cmp_ngt_f32_e32 vcc, s66, v78
	v_mul_f32_e32 v102, v62, v12
	v_ldexp_f32 v79, v79, v81
	s_nop 0
	v_cndmask_b32_e32 v79, 0, v79, vcc
	v_mul_f32_e32 v102, v102, v79
	v_cndmask_b32_e64 v102, 0, v102, s[22:23]
	s_movk_i32 s1, -9
	v_sub_f32_e32 v78, v47, v74
	v_cmp_lt_i32_e64 s[22:23], s1, v76
	v_mul_f32_e32 v79, 0x3fb8aa3b, v78
	v_fma_f32 v80, v78, s9, -v79
	v_rndne_f32_e32 v81, v79
	v_fmac_f32_e32 v80, 0x32a5705f, v78
	v_sub_f32_e32 v79, v79, v81
	v_add_f32_e32 v79, v79, v80
	v_cvt_i32_f32_e32 v81, v81
	v_exp_f32_e32 v79, v79
	v_cmp_ngt_f32_e32 vcc, s66, v78
	v_mul_f32_e32 v103, v63, v13
	v_ldexp_f32 v79, v79, v81
	s_nop 0
	v_cndmask_b32_e32 v79, 0, v79, vcc
	v_mul_f32_e32 v103, v103, v79
	v_cndmask_b32_e64 v103, 0, v103, s[22:23]
	s_movk_i32 s1, -10
	v_sub_f32_e32 v78, v48, v74
	v_cmp_lt_i32_e64 s[22:23], s1, v76
	v_mul_f32_e32 v79, 0x3fb8aa3b, v78
	v_fma_f32 v80, v78, s9, -v79
	v_rndne_f32_e32 v81, v79
	v_fmac_f32_e32 v80, 0x32a5705f, v78
	v_sub_f32_e32 v79, v79, v81
	v_add_f32_e32 v79, v79, v80
	v_cvt_i32_f32_e32 v81, v81
	v_exp_f32_e32 v79, v79
	v_cmp_ngt_f32_e32 vcc, s66, v78
	v_mul_f32_e32 v104, v64, v14
	v_ldexp_f32 v79, v79, v81
	s_nop 0
	v_cndmask_b32_e32 v79, 0, v79, vcc
	v_mul_f32_e32 v104, v104, v79
	v_cndmask_b32_e64 v104, 0, v104, s[22:23]
	s_movk_i32 s1, -11
	v_sub_f32_e32 v78, v49, v74
	v_cmp_lt_i32_e64 s[22:23], s1, v76
	v_mul_f32_e32 v79, 0x3fb8aa3b, v78
	v_fma_f32 v80, v78, s9, -v79
	v_rndne_f32_e32 v81, v79
	v_fmac_f32_e32 v80, 0x32a5705f, v78
	v_sub_f32_e32 v79, v79, v81
	v_add_f32_e32 v79, v79, v80
	v_cvt_i32_f32_e32 v81, v81
	v_exp_f32_e32 v79, v79
	v_cmp_ngt_f32_e32 vcc, s66, v78
	v_mul_f32_e32 v105, v65, v15
	v_ldexp_f32 v79, v79, v81
	s_nop 0
	v_cndmask_b32_e32 v79, 0, v79, vcc
	v_mul_f32_e32 v105, v105, v79
	v_cndmask_b32_e64 v105, 0, v105, s[22:23]
	s_movk_i32 s1, -16
	v_sub_f32_e32 v78, v50, v74
	v_cmp_lt_i32_e64 s[22:23], s1, v76
	v_mul_f32_e32 v79, 0x3fb8aa3b, v78
	v_fma_f32 v80, v78, s9, -v79
	v_rndne_f32_e32 v81, v79
	v_fmac_f32_e32 v80, 0x32a5705f, v78
	v_sub_f32_e32 v79, v79, v81
	v_add_f32_e32 v79, v79, v80
	v_cvt_i32_f32_e32 v81, v81
	v_exp_f32_e32 v79, v79
	v_cmp_ngt_f32_e32 vcc, s66, v78
	v_mul_f32_e32 v106, v66, v16
	v_ldexp_f32 v79, v79, v81
	s_nop 0
	v_cndmask_b32_e32 v79, 0, v79, vcc
	v_mul_f32_e32 v106, v106, v79
	v_cndmask_b32_e64 v106, 0, v106, s[22:23]
	s_movk_i32 s1, -17
	v_sub_f32_e32 v78, v51, v74
	v_cmp_lt_i32_e64 s[22:23], s1, v76
	v_mul_f32_e32 v79, 0x3fb8aa3b, v78
	v_fma_f32 v80, v78, s9, -v79
	v_rndne_f32_e32 v81, v79
	v_fmac_f32_e32 v80, 0x32a5705f, v78
	v_sub_f32_e32 v79, v79, v81
	v_add_f32_e32 v79, v79, v80
	v_cvt_i32_f32_e32 v81, v81
	v_exp_f32_e32 v79, v79
	v_cmp_ngt_f32_e32 vcc, s66, v78
	v_mul_f32_e32 v107, v67, v17
	v_ldexp_f32 v79, v79, v81
	s_nop 0
	v_cndmask_b32_e32 v79, 0, v79, vcc
	v_mul_f32_e32 v107, v107, v79
	v_cndmask_b32_e64 v107, 0, v107, s[22:23]
	s_movk_i32 s1, -18
	v_sub_f32_e32 v78, v52, v74
	v_cmp_lt_i32_e64 s[22:23], s1, v76
	v_mul_f32_e32 v79, 0x3fb8aa3b, v78
	v_fma_f32 v80, v78, s9, -v79
	v_rndne_f32_e32 v81, v79
	v_fmac_f32_e32 v80, 0x32a5705f, v78
	v_sub_f32_e32 v79, v79, v81
	v_add_f32_e32 v79, v79, v80
	v_cvt_i32_f32_e32 v81, v81
; DI bf16_t f2bf(float x) { unsigned u = __float_as_uint(x); u += 0x7fffu + ((u >> 16) & 1u); return (bf16_t)(u >> 16); }
; NI void dn_chunk_local(const P& p, int dh, int n, char* lds) {
;     ...
;   {
;     const float gc_c = gcS[c], beta_c = bS[c];
;     bf16_t* QKo = (bf16_t*)(ws + WS_DQK) + ((size_t)(dh * NCH + n) * 64 + c) * 64;
; #pragma unroll
;     for (int i = 0; i < 16; ++i) {
;       const int s = sg * 16 + i;
;       const float dec = (c >= s) ? expf(gc_c - gcS[s]) : 0.f;
;       Ls[c * 64 + s] = (c > s) ? beta_c * akk[i] * dec : 0.f;
;       QKo[s] = f2bf(aqk[i] * dec);
;     }
;   }
	v_exp_f32_e32 v79, v79
	v_cmp_ngt_f32_e32 vcc, s66, v78
	v_mul_f32_e32 v108, v68, v18
	v_ldexp_f32 v79, v79, v81
	s_nop 0
	v_cndmask_b32_e32 v79, 0, v79, vcc
	v_mul_f32_e32 v108, v108, v79
	v_cndmask_b32_e64 v108, 0, v108, s[22:23]
	s_movk_i32 s1, -19
	v_sub_f32_e32 v78, v53, v74
	v_cmp_lt_i32_e64 s[22:23], s1, v76
	v_mul_f32_e32 v79, 0x3fb8aa3b, v78
	v_fma_f32 v80, v78, s9, -v79
	v_rndne_f32_e32 v81, v79
	v_fmac_f32_e32 v80, 0x32a5705f, v78
	v_sub_f32_e32 v79, v79, v81
	v_add_f32_e32 v79, v79, v80
	v_cvt_i32_f32_e32 v81, v81
	v_exp_f32_e32 v79, v79
	v_cmp_ngt_f32_e32 vcc, s66, v78
	v_mul_f32_e32 v109, v69, v19
	v_ldexp_f32 v79, v79, v81
	s_nop 0
	v_cndmask_b32_e32 v79, 0, v79, vcc
	v_mul_f32_e32 v109, v109, v79
	v_cndmask_b32_e64 v109, 0, v109, s[22:23]
	s_movk_i32 s1, -24
	v_sub_f32_e32 v78, v54, v74
	v_cmp_lt_i32_e64 s[22:23], s1, v76
	v_mul_f32_e32 v79, 0x3fb8aa3b, v78
	v_fma_f32 v80, v78, s9, -v79
	v_rndne_f32_e32 v81, v79
	v_fmac_f32_e32 v80, 0x32a5705f, v78
	v_sub_f32_e32 v79, v79, v81
	v_add_f32_e32 v79, v79, v80
	v_cvt_i32_f32_e32 v81, v81
	v_exp_f32_e32 v79, v79
	v_cmp_ngt_f32_e32 vcc, s66, v78
	v_mul_f32_e32 v110, v70, v20
	v_ldexp_f32 v79, v79, v81
	s_nop 0
	v_cndmask_b32_e32 v79, 0, v79, vcc
	v_mul_f32_e32 v110, v110, v79
	v_cndmask_b32_e64 v110, 0, v110, s[22:23]
	s_movk_i32 s1, -25
	v_sub_f32_e32 v78, v55, v74
	v_cmp_lt_i32_e64 s[22:23], s1, v76
	v_mul_f32_e32 v79, 0x3fb8aa3b, v78
	v_fma_f32 v80, v78, s9, -v79
	v_rndne_f32_e32 v81, v79
	v_fmac_f32_e32 v80, 0x32a5705f, v78
	v_sub_f32_e32 v79, v79, v81
	v_add_f32_e32 v79, v79, v80
	v_cvt_i32_f32_e32 v81, v81
	v_exp_f32_e32 v79, v79
	v_cmp_ngt_f32_e32 vcc, s66, v78
	v_mul_f32_e32 v111, v71, v21
	v_ldexp_f32 v79, v79, v81
	s_nop 0
	v_cndmask_b32_e32 v79, 0, v79, vcc
	v_mul_f32_e32 v111, v111, v79
	v_cndmask_b32_e64 v111, 0, v111, s[22:23]
	s_movk_i32 s1, -26
	v_sub_f32_e32 v78, v56, v74
	v_cmp_lt_i32_e64 s[22:23], s1, v76
	v_mul_f32_e32 v79, 0x3fb8aa3b, v78
	v_fma_f32 v80, v78, s9, -v79
	v_rndne_f32_e32 v81, v79
	v_fmac_f32_e32 v80, 0x32a5705f, v78
	v_sub_f32_e32 v79, v79, v81
	v_add_f32_e32 v79, v79, v80
	v_cvt_i32_f32_e32 v81, v81
	v_exp_f32_e32 v79, v79
	v_cmp_ngt_f32_e32 vcc, s66, v78
	v_mul_f32_e32 v112, v72, v22
	v_ldexp_f32 v79, v79, v81
	s_nop 0
	v_cndmask_b32_e32 v79, 0, v79, vcc
	v_mul_f32_e32 v112, v112, v79
	v_cndmask_b32_e64 v112, 0, v112, s[22:23]
	s_movk_i32 s1, -27
	v_sub_f32_e32 v78, v57, v74
	v_cmp_lt_i32_e64 s[22:23], s1, v76
	v_mul_f32_e32 v79, 0x3fb8aa3b, v78
	v_fma_f32 v80, v78, s9, -v79
	v_rndne_f32_e32 v81, v79
	v_fmac_f32_e32 v80, 0x32a5705f, v78
	v_sub_f32_e32 v79, v79, v81
	v_add_f32_e32 v79, v79, v80
	v_cvt_i32_f32_e32 v81, v81
	v_exp_f32_e32 v79, v79
	v_cmp_ngt_f32_e32 vcc, s66, v78
	v_mul_f32_e32 v113, v73, v23
	v_ldexp_f32 v79, v79, v81
	s_nop 0
	v_cndmask_b32_e32 v79, 0, v79, vcc
	v_mul_f32_e32 v113, v113, v79
	v_cndmask_b32_e64 v113, 0, v113, s[22:23]
	s_movk_i32 s1, 0
	v_sub_f32_e32 v78, v42, v75
	v_cmp_lt_i32_e64 s[22:23], s1, v77
	v_mul_f32_e32 v79, 0x3fb8aa3b, v78
	v_fma_f32 v80, v78, s9, -v79
	v_rndne_f32_e32 v81, v79
	v_fmac_f32_e32 v80, 0x32a5705f, v78
	v_sub_f32_e32 v79, v79, v81
	v_add_f32_e32 v79, v79, v80
	v_cvt_i32_f32_e32 v81, v81
	v_exp_f32_e32 v79, v79
	v_cmp_ngt_f32_e32 vcc, s66, v78
	v_mul_f32_e32 v114, v58, v24
	v_ldexp_f32 v79, v79, v81
	s_nop 0
	v_cndmask_b32_e32 v79, 0, v79, vcc
	v_mul_f32_e32 v114, v114, v79
	v_cndmask_b32_e64 v114, 0, v114, s[22:23]
	s_movk_i32 s1, -1
	v_sub_f32_e32 v78, v43, v75
	v_cmp_lt_i32_e64 s[22:23], s1, v77
	v_mul_f32_e32 v79, 0x3fb8aa3b, v78
	v_fma_f32 v80, v78, s9, -v79
	v_rndne_f32_e32 v81, v79
	v_fmac_f32_e32 v80, 0x32a5705f, v78
	v_sub_f32_e32 v79, v79, v81
	v_add_f32_e32 v79, v79, v80
	v_cvt_i32_f32_e32 v81, v81
	v_exp_f32_e32 v79, v79
	v_cmp_ngt_f32_e32 vcc, s66, v78
	v_mul_f32_e32 v115, v59, v25
	v_ldexp_f32 v79, v79, v81
	s_nop 0
	v_cndmask_b32_e32 v79, 0, v79, vcc
	v_mul_f32_e32 v115, v115, v79
	v_cndmask_b32_e64 v115, 0, v115, s[22:23]
	s_movk_i32 s1, -2
	v_sub_f32_e32 v78, v44, v75
	v_cmp_lt_i32_e64 s[22:23], s1, v77
	v_mul_f32_e32 v79, 0x3fb8aa3b, v78
	v_fma_f32 v80, v78, s9, -v79
	v_rndne_f32_e32 v81, v79
	v_fmac_f32_e32 v80, 0x32a5705f, v78
	v_sub_f32_e32 v79, v79, v81
	v_add_f32_e32 v79, v79, v80
	v_cvt_i32_f32_e32 v81, v81
	v_exp_f32_e32 v79, v79
	v_cmp_ngt_f32_e32 vcc, s66, v78
	v_mul_f32_e32 v116, v60, v26
	v_ldexp_f32 v79, v79, v81
	s_nop 0
	v_cndmask_b32_e32 v79, 0, v79, vcc
	v_mul_f32_e32 v116, v116, v79
	v_cndmask_b32_e64 v116, 0, v116, s[22:23]
	s_movk_i32 s1, -3
	v_sub_f32_e32 v78, v45, v75
	v_cmp_lt_i32_e64 s[22:23], s1, v77
	v_mul_f32_e32 v79, 0x3fb8aa3b, v78
	v_fma_f32 v80, v78, s9, -v79
	v_rndne_f32_e32 v81, v79
	v_fmac_f32_e32 v80, 0x32a5705f, v78
	v_sub_f32_e32 v79, v79, v81
	v_add_f32_e32 v79, v79, v80
	v_cvt_i32_f32_e32 v81, v81
	v_exp_f32_e32 v79, v79
	v_cmp_ngt_f32_e32 vcc, s66, v78
	v_mul_f32_e32 v117, v61, v27
	v_ldexp_f32 v79, v79, v81
	s_nop 0
	v_cndmask_b32_e32 v79, 0, v79, vcc
	v_mul_f32_e32 v117, v117, v79
	v_cndmask_b32_e64 v117, 0, v117, s[22:23]
	s_movk_i32 s1, -8
	v_sub_f32_e32 v78, v46, v75
	v_cmp_lt_i32_e64 s[22:23], s1, v77
	v_mul_f32_e32 v79, 0x3fb8aa3b, v78
	v_fma_f32 v80, v78, s9, -v79
	v_rndne_f32_e32 v81, v79
	v_fmac_f32_e32 v80, 0x32a5705f, v78
	v_sub_f32_e32 v79, v79, v81
	v_add_f32_e32 v79, v79, v80
	v_cvt_i32_f32_e32 v81, v81
	v_exp_f32_e32 v79, v79
	v_cmp_ngt_f32_e32 vcc, s66, v78
	v_mul_f32_e32 v118, v62, v28
	v_ldexp_f32 v79, v79, v81
	s_nop 0
	v_cndmask_b32_e32 v79, 0, v79, vcc
	v_mul_f32_e32 v118, v118, v79
	v_cndmask_b32_e64 v118, 0, v118, s[22:23]
	s_movk_i32 s1, -9
	v_sub_f32_e32 v78, v47, v75
	v_cmp_lt_i32_e64 s[22:23], s1, v77
; DI bf16_t f2bf(float x) { unsigned u = __float_as_uint(x); u += 0x7fffu + ((u >> 16) & 1u); return (bf16_t)(u >> 16); }
; NI void dn_chunk_local(const P& p, int dh, int n, char* lds) {
;     ...
;   {
;     const float gc_c = gcS[c], beta_c = bS[c];
;     bf16_t* QKo = (bf16_t*)(ws + WS_DQK) + ((size_t)(dh * NCH + n) * 64 + c) * 64;
; #pragma unroll
;     for (int i = 0; i < 16; ++i) {
;       const int s = sg * 16 + i;
;       const float dec = (c >= s) ? expf(gc_c - gcS[s]) : 0.f;
;       Ls[c * 64 + s] = (c > s) ? beta_c * akk[i] * dec : 0.f;
;       QKo[s] = f2bf(aqk[i] * dec);
;     }
;   }
	v_mul_f32_e32 v79, 0x3fb8aa3b, v78
	v_fma_f32 v80, v78, s9, -v79
	v_rndne_f32_e32 v81, v79
	v_fmac_f32_e32 v80, 0x32a5705f, v78
	v_sub_f32_e32 v79, v79, v81
	v_add_f32_e32 v79, v79, v80
	v_cvt_i32_f32_e32 v81, v81
	v_exp_f32_e32 v79, v79
	v_cmp_ngt_f32_e32 vcc, s66, v78
	v_mul_f32_e32 v119, v63, v29
	v_ldexp_f32 v79, v79, v81
	s_nop 0
	v_cndmask_b32_e32 v79, 0, v79, vcc
	v_mul_f32_e32 v119, v119, v79
	v_cndmask_b32_e64 v119, 0, v119, s[22:23]
	s_movk_i32 s1, -10
	v_sub_f32_e32 v78, v48, v75
	v_cmp_lt_i32_e64 s[22:23], s1, v77
	v_mul_f32_e32 v79, 0x3fb8aa3b, v78
	v_fma_f32 v80, v78, s9, -v79
	v_rndne_f32_e32 v81, v79
	v_fmac_f32_e32 v80, 0x32a5705f, v78
	v_sub_f32_e32 v79, v79, v81
	v_add_f32_e32 v79, v79, v80
	v_cvt_i32_f32_e32 v81, v81
	v_exp_f32_e32 v79, v79
	v_cmp_ngt_f32_e32 vcc, s66, v78
	v_mul_f32_e32 v120, v64, v30
	v_ldexp_f32 v79, v79, v81
	s_nop 0
	v_cndmask_b32_e32 v79, 0, v79, vcc
	v_mul_f32_e32 v120, v120, v79
	v_cndmask_b32_e64 v120, 0, v120, s[22:23]
	s_movk_i32 s1, -11
	v_sub_f32_e32 v78, v49, v75
	v_cmp_lt_i32_e64 s[22:23], s1, v77
	v_mul_f32_e32 v79, 0x3fb8aa3b, v78
	v_fma_f32 v80, v78, s9, -v79
	v_rndne_f32_e32 v81, v79
	v_fmac_f32_e32 v80, 0x32a5705f, v78
	v_sub_f32_e32 v79, v79, v81
	v_add_f32_e32 v79, v79, v80
	v_cvt_i32_f32_e32 v81, v81
	v_exp_f32_e32 v79, v79
	v_cmp_ngt_f32_e32 vcc, s66, v78
	v_mul_f32_e32 v121, v65, v31
	v_ldexp_f32 v79, v79, v81
	s_nop 0
	v_cndmask_b32_e32 v79, 0, v79, vcc
	v_mul_f32_e32 v121, v121, v79
	v_cndmask_b32_e64 v121, 0, v121, s[22:23]
	s_movk_i32 s1, -16
	v_sub_f32_e32 v78, v50, v75
	v_cmp_lt_i32_e64 s[22:23], s1, v77
	v_mul_f32_e32 v79, 0x3fb8aa3b, v78
	v_fma_f32 v80, v78, s9, -v79
	v_rndne_f32_e32 v81, v79
	v_fmac_f32_e32 v80, 0x32a5705f, v78
	v_sub_f32_e32 v79, v79, v81
	v_add_f32_e32 v79, v79, v80
	v_cvt_i32_f32_e32 v81, v81
	v_exp_f32_e32 v79, v79
	v_cmp_ngt_f32_e32 vcc, s66, v78
	v_mul_f32_e32 v122, v66, v32
	v_ldexp_f32 v79, v79, v81
	s_nop 0
	v_cndmask_b32_e32 v79, 0, v79, vcc
	v_mul_f32_e32 v122, v122, v79
	v_cndmask_b32_e64 v122, 0, v122, s[22:23]
	s_movk_i32 s1, -17
	v_sub_f32_e32 v78, v51, v75
	v_cmp_lt_i32_e64 s[22:23], s1, v77
	v_mul_f32_e32 v79, 0x3fb8aa3b, v78
	v_fma_f32 v80, v78, s9, -v79
	v_rndne_f32_e32 v81, v79
	v_fmac_f32_e32 v80, 0x32a5705f, v78
	v_sub_f32_e32 v79, v79, v81
	v_add_f32_e32 v79, v79, v80
	v_cvt_i32_f32_e32 v81, v81
	v_exp_f32_e32 v79, v79
	v_cmp_ngt_f32_e32 vcc, s66, v78
	v_mul_f32_e32 v123, v67, v33
	v_ldexp_f32 v79, v79, v81
	s_nop 0
	v_cndmask_b32_e32 v79, 0, v79, vcc
	v_mul_f32_e32 v123, v123, v79
	v_cndmask_b32_e64 v123, 0, v123, s[22:23]
	s_movk_i32 s1, -18
	v_sub_f32_e32 v78, v52, v75
	v_cmp_lt_i32_e64 s[22:23], s1, v77
	v_mul_f32_e32 v79, 0x3fb8aa3b, v78
	v_fma_f32 v80, v78, s9, -v79
	v_rndne_f32_e32 v81, v79
	v_fmac_f32_e32 v80, 0x32a5705f, v78
	v_sub_f32_e32 v79, v79, v81
	v_add_f32_e32 v79, v79, v80
	v_cvt_i32_f32_e32 v81, v81
	v_exp_f32_e32 v79, v79
	v_cmp_ngt_f32_e32 vcc, s66, v78
	v_mul_f32_e32 v124, v68, v34
	v_ldexp_f32 v79, v79, v81
	s_nop 0
	v_cndmask_b32_e32 v79, 0, v79, vcc
	v_mul_f32_e32 v124, v124, v79
	v_cndmask_b32_e64 v124, 0, v124, s[22:23]
	s_movk_i32 s1, -19
	v_sub_f32_e32 v78, v53, v75
	v_cmp_lt_i32_e64 s[22:23], s1, v77
	v_mul_f32_e32 v79, 0x3fb8aa3b, v78
	v_fma_f32 v80, v78, s9, -v79
	v_rndne_f32_e32 v81, v79
	v_fmac_f32_e32 v80, 0x32a5705f, v78
	v_sub_f32_e32 v79, v79, v81
	v_add_f32_e32 v79, v79, v80
	v_cvt_i32_f32_e32 v81, v81
	v_exp_f32_e32 v79, v79
	v_cmp_ngt_f32_e32 vcc, s66, v78
	v_mul_f32_e32 v125, v69, v35
	v_ldexp_f32 v79, v79, v81
	s_nop 0
	v_cndmask_b32_e32 v79, 0, v79, vcc
	v_mul_f32_e32 v125, v125, v79
	v_cndmask_b32_e64 v125, 0, v125, s[22:23]
	s_movk_i32 s1, -24
	v_sub_f32_e32 v78, v54, v75
	v_cmp_lt_i32_e64 s[22:23], s1, v77
	v_mul_f32_e32 v79, 0x3fb8aa3b, v78
	v_fma_f32 v80, v78, s9, -v79
	v_rndne_f32_e32 v81, v79
	v_fmac_f32_e32 v80, 0x32a5705f, v78
	v_sub_f32_e32 v79, v79, v81
	v_add_f32_e32 v79, v79, v80
	v_cvt_i32_f32_e32 v81, v81
	v_exp_f32_e32 v79, v79
	v_cmp_ngt_f32_e32 vcc, s66, v78
	v_mul_f32_e32 v126, v70, v36
	v_ldexp_f32 v79, v79, v81
	s_nop 0
	v_cndmask_b32_e32 v79, 0, v79, vcc
	v_mul_f32_e32 v126, v126, v79
	v_cndmask_b32_e64 v126, 0, v126, s[22:23]
	s_movk_i32 s1, -25
	v_sub_f32_e32 v78, v55, v75
	v_cmp_lt_i32_e64 s[22:23], s1, v77
	v_mul_f32_e32 v79, 0x3fb8aa3b, v78
	v_fma_f32 v80, v78, s9, -v79
	v_rndne_f32_e32 v81, v79
	v_fmac_f32_e32 v80, 0x32a5705f, v78
	v_sub_f32_e32 v79, v79, v81
	v_add_f32_e32 v79, v79, v80
	v_cvt_i32_f32_e32 v81, v81
	v_exp_f32_e32 v79, v79
	v_cmp_ngt_f32_e32 vcc, s66, v78
	v_mul_f32_e32 v127, v71, v37
	v_ldexp_f32 v79, v79, v81
	s_nop 0
	v_cndmask_b32_e32 v79, 0, v79, vcc
	v_mul_f32_e32 v127, v127, v79
	v_cndmask_b32_e64 v127, 0, v127, s[22:23]
	s_movk_i32 s1, -26
	v_sub_f32_e32 v78, v56, v75
	v_cmp_lt_i32_e64 s[22:23], s1, v77
	v_mul_f32_e32 v79, 0x3fb8aa3b, v78
	v_fma_f32 v80, v78, s9, -v79
	v_rndne_f32_e32 v81, v79
	v_fmac_f32_e32 v80, 0x32a5705f, v78
	v_sub_f32_e32 v79, v79, v81
	v_add_f32_e32 v79, v79, v80
	v_cvt_i32_f32_e32 v81, v81
	v_exp_f32_e32 v79, v79
	v_cmp_ngt_f32_e32 vcc, s66, v78
	v_mul_f32_e32 v128, v72, v38
	v_ldexp_f32 v79, v79, v81
	s_nop 0
	v_cndmask_b32_e32 v79, 0, v79, vcc
	v_mul_f32_e32 v128, v128, v79
	v_cndmask_b32_e64 v128, 0, v128, s[22:23]
	s_movk_i32 s1, -27
	v_sub_f32_e32 v78, v57, v75
	v_cmp_lt_i32_e64 s[22:23], s1, v77
	v_mul_f32_e32 v79, 0x3fb8aa3b, v78
	v_fma_f32 v80, v78, s9, -v79
	v_rndne_f32_e32 v81, v79
	v_fmac_f32_e32 v80, 0x32a5705f, v78
	v_sub_f32_e32 v79, v79, v81
	v_add_f32_e32 v79, v79, v80
	v_cvt_i32_f32_e32 v81, v81
	v_exp_f32_e32 v79, v79
	v_cmp_ngt_f32_e32 vcc, s66, v78
	v_mul_f32_e32 v129, v73, v39
	v_ldexp_f32 v79, v79, v81
	s_nop 0
	v_cndmask_b32_e32 v79, 0, v79, vcc
	v_mul_f32_e32 v129, v129, v79
	v_cndmask_b32_e64 v129, 0, v129, s[22:23]
	s_cmp_eq_u32 s11, 0
	s_cbranch_scc0 .Ldn_akk_qk
; DI bf16_t f2bf(float x) { unsigned u = __float_as_uint(x); u += 0x7fffu + ((u >> 16) & 1u); return (bf16_t)(u >> 16); }
; NI void dn_chunk_local(const P& p, int dh, int n, char* lds) {
;     ...
;   {
;     const float gc_c = gcS[c], beta_c = bS[c];
;     bf16_t* QKo = (bf16_t*)(ws + WS_DQK) + ((size_t)(dh * NCH + n) * 64 + c) * 64;
; #pragma unroll
;     for (int i = 0; i < 16; ++i) {
;       const int s = sg * 16 + i;
;       const float dec = (c >= s) ? expf(gc_c - gcS[s]) : 0.f;
;       Ls[c * 64 + s] = (c > s) ? beta_c * akk[i] * dec : 0.f;
;       QKo[s] = f2bf(aqk[i] * dec);
;     }
;   }
	v_lshl_add_u32 v82, v91, 8, v93
	ds_write_b32 v82, v98 offset:16896
	ds_write_b32 v82, v99 offset:17152
	ds_write_b32 v82, v100 offset:17408
	ds_write_b32 v82, v101 offset:17664
	ds_write_b32 v82, v102 offset:18944
	ds_write_b32 v82, v103 offset:19200
	ds_write_b32 v82, v104 offset:19456
	ds_write_b32 v82, v105 offset:19712
	ds_write_b32 v82, v106 offset:20992
	ds_write_b32 v82, v107 offset:21248
	ds_write_b32 v82, v108 offset:21504
	ds_write_b32 v82, v109 offset:21760
	ds_write_b32 v82, v110 offset:23040
	ds_write_b32 v82, v111 offset:23296
	ds_write_b32 v82, v112 offset:23552
	ds_write_b32 v82, v113 offset:23808
	ds_write_b32 v82, v114 offset:17024
	ds_write_b32 v82, v115 offset:17280
	ds_write_b32 v82, v116 offset:17536
	ds_write_b32 v82, v117 offset:17792
	ds_write_b32 v82, v118 offset:19072
	ds_write_b32 v82, v119 offset:19328
	ds_write_b32 v82, v120 offset:19584
	ds_write_b32 v82, v121 offset:19840
	ds_write_b32 v82, v122 offset:21120
	ds_write_b32 v82, v123 offset:21376
	ds_write_b32 v82, v124 offset:21632
	ds_write_b32 v82, v125 offset:21888
	ds_write_b32 v82, v126 offset:23168
	ds_write_b32 v82, v127 offset:23424
	ds_write_b32 v82, v128 offset:23680
	ds_write_b32 v82, v129 offset:23936
	s_branch .Ldn_akk_done
.Ldn_akk_qk:
	s_ashr_i32 s81, s80, 31
	s_lshl_b64 s[10:11], s[80:81], 13
	v_readlane_b32 s1, v253, 8
	s_add_u32 s10, s1, s10
	v_readlane_b32 s1, v253, 9
	s_addc_u32 s11, s1, s11
	v_lshlrev_b32_e32 v82, 7, v91
	v_lshl_add_u32 v82, v5, 1, v82
	v_mov_b32_e32 v83, 0
	v_lshl_add_u64 v[82:83], s[10:11], 0, v[82:83]
	v_cvt_pk_bf16_f32 v98, v98, v98
	s_nop 0
	global_store_short v[82:83], v98, off offset:0
	v_cvt_pk_bf16_f32 v99, v99, v99
	s_nop 0
	global_store_short v[82:83], v99, off offset:128
	v_cvt_pk_bf16_f32 v100, v100, v100
	s_nop 0
	global_store_short v[82:83], v100, off offset:256
	v_cvt_pk_bf16_f32 v101, v101, v101
	s_nop 0
	global_store_short v[82:83], v101, off offset:384
	v_cvt_pk_bf16_f32 v102, v102, v102
	s_nop 0
	global_store_short v[82:83], v102, off offset:1024
	v_cvt_pk_bf16_f32 v103, v103, v103
	s_nop 0
	global_store_short v[82:83], v103, off offset:1152
	v_cvt_pk_bf16_f32 v104, v104, v104
	s_nop 0
	global_store_short v[82:83], v104, off offset:1280
	v_cvt_pk_bf16_f32 v105, v105, v105
	s_nop 0
	global_store_short v[82:83], v105, off offset:1408
	v_cvt_pk_bf16_f32 v106, v106, v106
	s_nop 0
	global_store_short v[82:83], v106, off offset:2048
	v_cvt_pk_bf16_f32 v107, v107, v107
	s_nop 0
	global_store_short v[82:83], v107, off offset:2176
	v_cvt_pk_bf16_f32 v108, v108, v108
	s_nop 0
	global_store_short v[82:83], v108, off offset:2304
	v_cvt_pk_bf16_f32 v109, v109, v109
	s_nop 0
	global_store_short v[82:83], v109, off offset:2432
	v_cvt_pk_bf16_f32 v110, v110, v110
	s_nop 0
	global_store_short v[82:83], v110, off offset:3072
	v_cvt_pk_bf16_f32 v111, v111, v111
	s_nop 0
	global_store_short v[82:83], v111, off offset:3200
	v_cvt_pk_bf16_f32 v112, v112, v112
	s_nop 0
	global_store_short v[82:83], v112, off offset:3328
	v_cvt_pk_bf16_f32 v113, v113, v113
	s_nop 0
	global_store_short v[82:83], v113, off offset:3456
	v_cvt_pk_bf16_f32 v114, v114, v114
	s_nop 0
	global_store_short v[82:83], v114, off offset:64
	v_cvt_pk_bf16_f32 v115, v115, v115
	s_nop 0
	global_store_short v[82:83], v115, off offset:192
	v_cvt_pk_bf16_f32 v116, v116, v116
	s_nop 0
	global_store_short v[82:83], v116, off offset:320
	v_cvt_pk_bf16_f32 v117, v117, v117
	s_nop 0
	global_store_short v[82:83], v117, off offset:448
	v_cvt_pk_bf16_f32 v118, v118, v118
	s_nop 0
	global_store_short v[82:83], v118, off offset:1088
	v_cvt_pk_bf16_f32 v119, v119, v119
	s_nop 0
	global_store_short v[82:83], v119, off offset:1216
	v_cvt_pk_bf16_f32 v120, v120, v120
	s_nop 0
	global_store_short v[82:83], v120, off offset:1344
	v_cvt_pk_bf16_f32 v121, v121, v121
	s_nop 0
	global_store_short v[82:83], v121, off offset:1472
	v_cvt_pk_bf16_f32 v122, v122, v122
	s_nop 0
	global_store_short v[82:83], v122, off offset:2112
	v_cvt_pk_bf16_f32 v123, v123, v123
	s_nop 0
	global_store_short v[82:83], v123, off offset:2240
	v_cvt_pk_bf16_f32 v124, v124, v124
	s_nop 0
	global_store_short v[82:83], v124, off offset:2368
	v_cvt_pk_bf16_f32 v125, v125, v125
	s_nop 0
	global_store_short v[82:83], v125, off offset:2496
	v_cvt_pk_bf16_f32 v126, v126, v126
	s_nop 0
	global_store_short v[82:83], v126, off offset:3136
	v_cvt_pk_bf16_f32 v127, v127, v127
	s_nop 0
	global_store_short v[82:83], v127, off offset:3264
	v_cvt_pk_bf16_f32 v128, v128, v128
	s_nop 0
	global_store_short v[82:83], v128, off offset:3392
	v_cvt_pk_bf16_f32 v129, v129, v129
	s_nop 0
	global_store_short v[82:83], v129, off offset:3520
; NI void dn_chunk_local(const P& p, int dh, int n, char* lds) {
;     ...
;   {
;     const int col = tid;
;     float x[64];
;     const float* src = CQ + (size_t)row0 * 1536 + hd * 128 + (col < 128 ? 1024 + col : 512 + (col - 128));
; #pragma unroll
;     for (int hb = 0; hb < 2; ++hb) {
; #pragma unroll
;       for (int i = hb * 32; i < hb * 32 + 32; ++i) {
;         const float f = (col < 128) ? bS[i] : bS[i] * egS[i];
;         x[i] = src[(long)i * rstride] * f;
;       }
;       __builtin_amdgcn_sched_barrier(0);
.Ldn_akk_done:
	s_ashr_i32 s81, s80, 31
	v_and_b32_e32 v50, 63, v4
	v_ashrrev_i32_e32 v51, 6, v4
	v_lshlrev_b32_e32 v40, 2, v50
	s_mul_i32 s18, s26, 0x600
	s_mul_i32 s10, s25, 0x1800
	s_ashr_i32 s19, s18, 31
	s_ashr_i32 s11, s10, 31
	s_add_u32 s10, s30, s10
	s_addc_u32 s11, s31, s11
	s_movk_i32 s1, 0x80
	v_cmp_gt_i32_e64 s[22:23], s1, v4
	v_mov_b32_e32 v0, 0x180
	s_add_u32 s10, s10, s74
	s_addc_u32 s11, s11, 0
	s_nop 0
	v_cndmask_b32_e64 v0, v0, v236, s[22:23]
	v_add_u32_e32 v0, v0, v4
	v_ashrrev_i32_e32 v1, 31, v0
	v_lshl_add_u64 v[6:7], v[0:1], 2, s[10:11]
	s_waitcnt lgkmcnt(0)
	s_barrier
	s_lshl_b64 s[10:11], s[18:19], 2
	global_load_dword v8, v[6:7], off
	v_lshl_add_u64 v[6:7], v[6:7], 0, s[10:11]
	global_load_dword v9, v[6:7], off
	v_lshl_add_u64 v[6:7], v[6:7], 0, s[10:11]
	global_load_dword v10, v[6:7], off
	v_lshl_add_u64 v[6:7], v[6:7], 0, s[10:11]
	global_load_dword v11, v[6:7], off
	v_lshl_add_u64 v[6:7], v[6:7], 0, s[10:11]
	global_load_dword v12, v[6:7], off
	v_lshl_add_u64 v[6:7], v[6:7], 0, s[10:11]
	global_load_dword v13, v[6:7], off
	v_lshl_add_u64 v[6:7], v[6:7], 0, s[10:11]
	global_load_dword v14, v[6:7], off
	v_lshl_add_u64 v[6:7], v[6:7], 0, s[10:11]
	global_load_dword v15, v[6:7], off
	v_lshl_add_u64 v[6:7], v[6:7], 0, s[10:11]
	global_load_dword v16, v[6:7], off
	v_lshl_add_u64 v[6:7], v[6:7], 0, s[10:11]
	global_load_dword v17, v[6:7], off
	v_lshl_add_u64 v[6:7], v[6:7], 0, s[10:11]
	global_load_dword v18, v[6:7], off
	v_lshl_add_u64 v[6:7], v[6:7], 0, s[10:11]
	global_load_dword v19, v[6:7], off
	v_lshl_add_u64 v[6:7], v[6:7], 0, s[10:11]
	global_load_dword v20, v[6:7], off
	v_lshl_add_u64 v[6:7], v[6:7], 0, s[10:11]
	global_load_dword v21, v[6:7], off
	v_lshl_add_u64 v[6:7], v[6:7], 0, s[10:11]
	global_load_dword v22, v[6:7], off
	v_lshl_add_u64 v[6:7], v[6:7], 0, s[10:11]
	global_load_dword v23, v[6:7], off
	v_lshl_add_u64 v[6:7], v[6:7], 0, s[10:11]
	global_load_dword v24, v[6:7], off
	v_lshl_add_u64 v[6:7], v[6:7], 0, s[10:11]
	global_load_dword v25, v[6:7], off
	v_lshl_add_u64 v[6:7], v[6:7], 0, s[10:11]
	global_load_dword v26, v[6:7], off
	v_lshl_add_u64 v[6:7], v[6:7], 0, s[10:11]
	global_load_dword v27, v[6:7], off
	v_lshl_add_u64 v[6:7], v[6:7], 0, s[10:11]
	global_load_dword v28, v[6:7], off
	v_lshl_add_u64 v[6:7], v[6:7], 0, s[10:11]
	global_load_dword v29, v[6:7], off
	v_lshl_add_u64 v[6:7], v[6:7], 0, s[10:11]
	global_load_dword v30, v[6:7], off
	v_lshl_add_u64 v[6:7], v[6:7], 0, s[10:11]
	global_load_dword v31, v[6:7], off
	v_lshl_add_u64 v[6:7], v[6:7], 0, s[10:11]
	global_load_dword v32, v[6:7], off
	v_lshl_add_u64 v[6:7], v[6:7], 0, s[10:11]
	global_load_dword v33, v[6:7], off
	v_lshl_add_u64 v[6:7], v[6:7], 0, s[10:11]
	global_load_dword v34, v[6:7], off
	v_lshl_add_u64 v[6:7], v[6:7], 0, s[10:11]
	global_load_dword v35, v[6:7], off
	v_lshl_add_u64 v[6:7], v[6:7], 0, s[10:11]
	global_load_dword v36, v[6:7], off
	v_lshl_add_u64 v[6:7], v[6:7], 0, s[10:11]
	global_load_dword v37, v[6:7], off
	v_lshl_add_u64 v[6:7], v[6:7], 0, s[10:11]
	global_load_dword v38, v[6:7], off
	v_lshl_add_u64 v[6:7], v[6:7], 0, s[10:11]
	global_load_dword v39, v[6:7], off
	v_lshl_add_u64 v[6:7], v[6:7], 0, s[10:11]
	global_load_dword v52, v[6:7], off
	v_lshl_add_u64 v[6:7], v[6:7], 0, s[10:11]
	global_load_dword v53, v[6:7], off
	v_lshl_add_u64 v[6:7], v[6:7], 0, s[10:11]
	global_load_dword v54, v[6:7], off
	v_lshl_add_u64 v[6:7], v[6:7], 0, s[10:11]
	global_load_dword v55, v[6:7], off
	v_lshl_add_u64 v[6:7], v[6:7], 0, s[10:11]
	global_load_dword v56, v[6:7], off
	v_lshl_add_u64 v[6:7], v[6:7], 0, s[10:11]
	global_load_dword v57, v[6:7], off
	v_lshl_add_u64 v[6:7], v[6:7], 0, s[10:11]
	global_load_dword v58, v[6:7], off
	v_lshl_add_u64 v[6:7], v[6:7], 0, s[10:11]
	global_load_dword v59, v[6:7], off
	v_lshl_add_u64 v[6:7], v[6:7], 0, s[10:11]
	global_load_dword v60, v[6:7], off
	v_lshl_add_u64 v[6:7], v[6:7], 0, s[10:11]
	global_load_dword v61, v[6:7], off
	v_lshl_add_u64 v[6:7], v[6:7], 0, s[10:11]
	global_load_dword v62, v[6:7], off
	v_lshl_add_u64 v[6:7], v[6:7], 0, s[10:11]
	global_load_dword v63, v[6:7], off
	v_lshl_add_u64 v[6:7], v[6:7], 0, s[10:11]
	global_load_dword v64, v[6:7], off
	v_lshl_add_u64 v[6:7], v[6:7], 0, s[10:11]
	global_load_dword v65, v[6:7], off
	v_lshl_add_u64 v[6:7], v[6:7], 0, s[10:11]
	global_load_dword v66, v[6:7], off
	v_lshl_add_u64 v[6:7], v[6:7], 0, s[10:11]
	global_load_dword v67, v[6:7], off
	v_lshl_add_u64 v[6:7], v[6:7], 0, s[10:11]
	global_load_dword v68, v[6:7], off
	v_lshl_add_u64 v[6:7], v[6:7], 0, s[10:11]
	global_load_dword v69, v[6:7], off
	v_lshl_add_u64 v[6:7], v[6:7], 0, s[10:11]
	global_load_dword v70, v[6:7], off
	v_lshl_add_u64 v[6:7], v[6:7], 0, s[10:11]
	global_load_dword v71, v[6:7], off
	v_lshl_add_u64 v[6:7], v[6:7], 0, s[10:11]
	global_load_dword v72, v[6:7], off
	v_lshl_add_u64 v[6:7], v[6:7], 0, s[10:11]
	global_load_dword v73, v[6:7], off
	v_lshl_add_u64 v[6:7], v[6:7], 0, s[10:11]
	global_load_dword v74, v[6:7], off
	v_lshl_add_u64 v[6:7], v[6:7], 0, s[10:11]
	global_load_dword v75, v[6:7], off
	v_lshl_add_u64 v[6:7], v[6:7], 0, s[10:11]
	global_load_dword v76, v[6:7], off
	v_lshl_add_u64 v[6:7], v[6:7], 0, s[10:11]
	global_load_dword v77, v[6:7], off
	v_lshl_add_u64 v[6:7], v[6:7], 0, s[10:11]
	global_load_dword v78, v[6:7], off
	v_lshl_add_u64 v[6:7], v[6:7], 0, s[10:11]
	global_load_dword v79, v[6:7], off
	v_lshl_add_u64 v[6:7], v[6:7], 0, s[10:11]
	global_load_dword v80, v[6:7], off
	v_lshl_add_u64 v[6:7], v[6:7], 0, s[10:11]
	global_load_dword v81, v[6:7], off
	v_lshl_add_u64 v[6:7], v[6:7], 0, s[10:11]
	global_load_dword v82, v[6:7], off
	v_lshl_add_u64 v[6:7], v[6:7], 0, s[10:11]
	global_load_dword v83, v[6:7], off
	ds_read_b128 v[84:87], v97 offset:33536
	ds_read_b128 v[102:105], v97 offset:33792
	ds_read_b128 v[88:91], v97 offset:33552
	ds_read_b128 v[106:109], v97 offset:33808
	ds_read_b128 v[92:95], v97 offset:33568
	ds_read_b128 v[110:113], v97 offset:33824
	ds_read_b128 v[98:101], v97 offset:33584
	ds_read_b128 v[114:117], v97 offset:33840
	s_waitcnt lgkmcnt(6)
; NI void dn_chunk_local(const P& p, int dh, int n, char* lds) {
;     ...
;     for (int hb = 0; hb < 2; ++hb) {
; #pragma unroll
;       for (int i = hb * 32; i < hb * 32 + 32; ++i) {
;         const float f = (col < 128) ? bS[i] : bS[i] * egS[i];
;         x[i] = src[(long)i * rstride] * f;
;       }
	v_mul_f32_e32 v102, v84, v102
	v_cndmask_b32_e64 v102, v102, v84, s[22:23]
	s_waitcnt vmcnt(63)
	v_mul_f32_e32 v8, v8, v102
	v_mul_f32_e32 v103, v85, v103
	v_cndmask_b32_e64 v103, v103, v85, s[22:23]
	s_waitcnt vmcnt(62)
	v_mul_f32_e32 v9, v9, v103
	v_mul_f32_e32 v104, v86, v104
	v_cndmask_b32_e64 v104, v104, v86, s[22:23]
	s_waitcnt vmcnt(61)
	v_mul_f32_e32 v10, v10, v104
	v_mul_f32_e32 v105, v87, v105
	v_cndmask_b32_e64 v105, v105, v87, s[22:23]
	s_waitcnt vmcnt(60)
	v_mul_f32_e32 v11, v11, v105
	s_waitcnt lgkmcnt(4)
	v_mul_f32_e32 v106, v88, v106
	v_cndmask_b32_e64 v106, v106, v88, s[22:23]
	s_waitcnt vmcnt(59)
	v_mul_f32_e32 v12, v12, v106
	v_mul_f32_e32 v107, v89, v107
	v_cndmask_b32_e64 v107, v107, v89, s[22:23]
	s_waitcnt vmcnt(58)
	v_mul_f32_e32 v13, v13, v107
	v_mul_f32_e32 v108, v90, v108
	v_cndmask_b32_e64 v108, v108, v90, s[22:23]
	s_waitcnt vmcnt(57)
	v_mul_f32_e32 v14, v14, v108
	v_mul_f32_e32 v109, v91, v109
	v_cndmask_b32_e64 v109, v109, v91, s[22:23]
	s_waitcnt vmcnt(56)
	v_mul_f32_e32 v15, v15, v109
	s_waitcnt lgkmcnt(2)
	v_mul_f32_e32 v110, v92, v110
	v_cndmask_b32_e64 v110, v110, v92, s[22:23]
	s_waitcnt vmcnt(55)
	v_mul_f32_e32 v16, v16, v110
	v_mul_f32_e32 v111, v93, v111
	v_cndmask_b32_e64 v111, v111, v93, s[22:23]
	s_waitcnt vmcnt(54)
	v_mul_f32_e32 v17, v17, v111
	v_mul_f32_e32 v112, v94, v112
	v_cndmask_b32_e64 v112, v112, v94, s[22:23]
	s_waitcnt vmcnt(53)
	v_mul_f32_e32 v18, v18, v112
	v_mul_f32_e32 v113, v95, v113
	v_cndmask_b32_e64 v113, v113, v95, s[22:23]
	s_waitcnt vmcnt(52)
	v_mul_f32_e32 v19, v19, v113
	s_waitcnt lgkmcnt(0)
	v_mul_f32_e32 v114, v98, v114
	v_cndmask_b32_e64 v114, v114, v98, s[22:23]
	s_waitcnt vmcnt(51)
	v_mul_f32_e32 v20, v20, v114
	v_mul_f32_e32 v115, v99, v115
	v_cndmask_b32_e64 v115, v115, v99, s[22:23]
	s_waitcnt vmcnt(50)
	v_mul_f32_e32 v21, v21, v115
	v_mul_f32_e32 v116, v100, v116
	v_cndmask_b32_e64 v116, v116, v100, s[22:23]
	s_waitcnt vmcnt(49)
	v_mul_f32_e32 v22, v22, v116
	v_mul_f32_e32 v117, v101, v117
	v_cndmask_b32_e64 v117, v117, v101, s[22:23]
	s_waitcnt vmcnt(48)
	v_mul_f32_e32 v23, v23, v117
	ds_read_b128 v[84:87], v97 offset:33600
	ds_read_b128 v[102:105], v97 offset:33856
	ds_read_b128 v[88:91], v97 offset:33616
	ds_read_b128 v[106:109], v97 offset:33872
	ds_read_b128 v[92:95], v97 offset:33632
	ds_read_b128 v[110:113], v97 offset:33888
	ds_read_b128 v[98:101], v97 offset:33648
	ds_read_b128 v[114:117], v97 offset:33904
	s_waitcnt lgkmcnt(6)
	v_mul_f32_e32 v102, v84, v102
	v_cndmask_b32_e64 v102, v102, v84, s[22:23]
	s_waitcnt vmcnt(47)
	v_mul_f32_e32 v24, v24, v102
	v_mul_f32_e32 v103, v85, v103
	v_cndmask_b32_e64 v103, v103, v85, s[22:23]
	s_waitcnt vmcnt(46)
	v_mul_f32_e32 v25, v25, v103
	v_mul_f32_e32 v104, v86, v104
	v_cndmask_b32_e64 v104, v104, v86, s[22:23]
	s_waitcnt vmcnt(45)
	v_mul_f32_e32 v26, v26, v104
	v_mul_f32_e32 v105, v87, v105
	v_cndmask_b32_e64 v105, v105, v87, s[22:23]
	s_waitcnt vmcnt(44)
	v_mul_f32_e32 v27, v27, v105
	s_waitcnt lgkmcnt(4)
	v_mul_f32_e32 v106, v88, v106
	v_cndmask_b32_e64 v106, v106, v88, s[22:23]
	s_waitcnt vmcnt(43)
	v_mul_f32_e32 v28, v28, v106
	v_mul_f32_e32 v107, v89, v107
	v_cndmask_b32_e64 v107, v107, v89, s[22:23]
	s_waitcnt vmcnt(42)
	v_mul_f32_e32 v29, v29, v107
	v_mul_f32_e32 v108, v90, v108
	v_cndmask_b32_e64 v108, v108, v90, s[22:23]
	s_waitcnt vmcnt(41)
	v_mul_f32_e32 v30, v30, v108
	v_mul_f32_e32 v109, v91, v109
	v_cndmask_b32_e64 v109, v109, v91, s[22:23]
	s_waitcnt vmcnt(40)
	v_mul_f32_e32 v31, v31, v109
	s_waitcnt lgkmcnt(2)
	v_mul_f32_e32 v110, v92, v110
	v_cndmask_b32_e64 v110, v110, v92, s[22:23]
	s_waitcnt vmcnt(39)
	v_mul_f32_e32 v32, v32, v110
	v_mul_f32_e32 v111, v93, v111
	v_cndmask_b32_e64 v111, v111, v93, s[22:23]
	s_waitcnt vmcnt(38)
	v_mul_f32_e32 v33, v33, v111
	v_mul_f32_e32 v112, v94, v112
	v_cndmask_b32_e64 v112, v112, v94, s[22:23]
	s_waitcnt vmcnt(37)
	v_mul_f32_e32 v34, v34, v112
	v_mul_f32_e32 v113, v95, v113
	v_cndmask_b32_e64 v113, v113, v95, s[22:23]
	s_waitcnt vmcnt(36)
	v_mul_f32_e32 v35, v35, v113
	s_waitcnt lgkmcnt(0)
	v_mul_f32_e32 v114, v98, v114
	v_cndmask_b32_e64 v114, v114, v98, s[22:23]
	s_waitcnt vmcnt(35)
	v_mul_f32_e32 v36, v36, v114
	v_mul_f32_e32 v115, v99, v115
	v_cndmask_b32_e64 v115, v115, v99, s[22:23]
	s_waitcnt vmcnt(34)
	v_mul_f32_e32 v37, v37, v115
	v_mul_f32_e32 v116, v100, v116
	v_cndmask_b32_e64 v116, v116, v100, s[22:23]
	s_waitcnt vmcnt(33)
	v_mul_f32_e32 v38, v38, v116
	v_mul_f32_e32 v117, v101, v117
	v_cndmask_b32_e64 v117, v117, v101, s[22:23]
	s_waitcnt vmcnt(32)
	v_mul_f32_e32 v39, v39, v117
	ds_read_b128 v[84:87], v97 offset:33664
	ds_read_b128 v[102:105], v97 offset:33920
	ds_read_b128 v[88:91], v97 offset:33680
	ds_read_b128 v[106:109], v97 offset:33936
	ds_read_b128 v[92:95], v97 offset:33696
	ds_read_b128 v[110:113], v97 offset:33952
	ds_read_b128 v[98:101], v97 offset:33712
	ds_read_b128 v[114:117], v97 offset:33968
	s_waitcnt lgkmcnt(6)
	v_mul_f32_e32 v102, v84, v102
	v_cndmask_b32_e64 v102, v102, v84, s[22:23]
	s_waitcnt vmcnt(31)
	v_mul_f32_e32 v52, v52, v102
	v_mul_f32_e32 v103, v85, v103
	v_cndmask_b32_e64 v103, v103, v85, s[22:23]
	s_waitcnt vmcnt(30)
	v_mul_f32_e32 v53, v53, v103
	v_mul_f32_e32 v104, v86, v104
	v_cndmask_b32_e64 v104, v104, v86, s[22:23]
	s_waitcnt vmcnt(29)
	v_mul_f32_e32 v54, v54, v104
	v_mul_f32_e32 v105, v87, v105
	v_cndmask_b32_e64 v105, v105, v87, s[22:23]
	s_waitcnt vmcnt(28)
	v_mul_f32_e32 v55, v55, v105
	s_waitcnt lgkmcnt(4)
	v_mul_f32_e32 v106, v88, v106
	v_cndmask_b32_e64 v106, v106, v88, s[22:23]
	s_waitcnt vmcnt(27)
	v_mul_f32_e32 v56, v56, v106
	v_mul_f32_e32 v107, v89, v107
	v_cndmask_b32_e64 v107, v107, v89, s[22:23]
	s_waitcnt vmcnt(26)
; NI void dn_chunk_local(const P& p, int dh, int n, char* lds) {
;     ...
;         const float f = (col < 128) ? bS[i] : bS[i] * egS[i];
;         x[i] = src[(long)i * rstride] * f;
;       }
;       __builtin_amdgcn_sched_barrier(0);
; #pragma unroll
;       for (int i = hb * 32; i < hb * 32 + 32; ++i) {
;         float a = x[i];
; #pragma unroll
;         for (int j = 0; j < i; ++j) a -= Ls[i * 64 + j] * x[j];
;         x[i] = a;
;         if ((i & 3) == 3) __builtin_amdgcn_sched_barrier(0);
;       }
;     }
	v_mul_f32_e32 v57, v57, v107
	v_mul_f32_e32 v108, v90, v108
	v_cndmask_b32_e64 v108, v108, v90, s[22:23]
	s_waitcnt vmcnt(25)
	v_mul_f32_e32 v58, v58, v108
	v_mul_f32_e32 v109, v91, v109
	v_cndmask_b32_e64 v109, v109, v91, s[22:23]
	s_waitcnt vmcnt(24)
	v_mul_f32_e32 v59, v59, v109
	s_waitcnt lgkmcnt(2)
	v_mul_f32_e32 v110, v92, v110
	v_cndmask_b32_e64 v110, v110, v92, s[22:23]
	s_waitcnt vmcnt(23)
	v_mul_f32_e32 v60, v60, v110
	v_mul_f32_e32 v111, v93, v111
	v_cndmask_b32_e64 v111, v111, v93, s[22:23]
	s_waitcnt vmcnt(22)
	v_mul_f32_e32 v61, v61, v111
	v_mul_f32_e32 v112, v94, v112
	v_cndmask_b32_e64 v112, v112, v94, s[22:23]
	s_waitcnt vmcnt(21)
	v_mul_f32_e32 v62, v62, v112
	v_mul_f32_e32 v113, v95, v113
	v_cndmask_b32_e64 v113, v113, v95, s[22:23]
	s_waitcnt vmcnt(20)
	v_mul_f32_e32 v63, v63, v113
	s_waitcnt lgkmcnt(0)
	v_mul_f32_e32 v114, v98, v114
	v_cndmask_b32_e64 v114, v114, v98, s[22:23]
	s_waitcnt vmcnt(19)
	v_mul_f32_e32 v64, v64, v114
	v_mul_f32_e32 v115, v99, v115
	v_cndmask_b32_e64 v115, v115, v99, s[22:23]
	s_waitcnt vmcnt(18)
	v_mul_f32_e32 v65, v65, v115
	v_mul_f32_e32 v116, v100, v116
	v_cndmask_b32_e64 v116, v116, v100, s[22:23]
	s_waitcnt vmcnt(17)
	v_mul_f32_e32 v66, v66, v116
	v_mul_f32_e32 v117, v101, v117
	v_cndmask_b32_e64 v117, v117, v101, s[22:23]
	s_waitcnt vmcnt(16)
	v_mul_f32_e32 v67, v67, v117
	ds_read_b128 v[84:87], v97 offset:33728
	ds_read_b128 v[102:105], v97 offset:33984
	ds_read_b128 v[88:91], v97 offset:33744
	ds_read_b128 v[106:109], v97 offset:34000
	ds_read_b128 v[92:95], v97 offset:33760
	ds_read_b128 v[110:113], v97 offset:34016
	ds_read_b128 v[98:101], v97 offset:33776
	ds_read_b128 v[114:117], v97 offset:34032
	s_waitcnt lgkmcnt(6)
	v_mul_f32_e32 v102, v84, v102
	v_cndmask_b32_e64 v102, v102, v84, s[22:23]
	s_waitcnt vmcnt(15)
	v_mul_f32_e32 v68, v68, v102
	v_mul_f32_e32 v103, v85, v103
	v_cndmask_b32_e64 v103, v103, v85, s[22:23]
	s_waitcnt vmcnt(14)
	v_mul_f32_e32 v69, v69, v103
	v_mul_f32_e32 v104, v86, v104
	v_cndmask_b32_e64 v104, v104, v86, s[22:23]
	s_waitcnt vmcnt(13)
	v_mul_f32_e32 v70, v70, v104
	v_mul_f32_e32 v105, v87, v105
	v_cndmask_b32_e64 v105, v105, v87, s[22:23]
	s_waitcnt vmcnt(12)
	v_mul_f32_e32 v71, v71, v105
	s_waitcnt lgkmcnt(4)
	v_mul_f32_e32 v106, v88, v106
	v_cndmask_b32_e64 v106, v106, v88, s[22:23]
	s_waitcnt vmcnt(11)
	v_mul_f32_e32 v72, v72, v106
	v_mul_f32_e32 v107, v89, v107
	v_cndmask_b32_e64 v107, v107, v89, s[22:23]
	s_waitcnt vmcnt(10)
	v_mul_f32_e32 v73, v73, v107
	v_mul_f32_e32 v108, v90, v108
	v_cndmask_b32_e64 v108, v108, v90, s[22:23]
	s_waitcnt vmcnt(9)
	v_mul_f32_e32 v74, v74, v108
	v_mul_f32_e32 v109, v91, v109
	v_cndmask_b32_e64 v109, v109, v91, s[22:23]
	s_waitcnt vmcnt(8)
	v_mul_f32_e32 v75, v75, v109
	s_waitcnt lgkmcnt(2)
	v_mul_f32_e32 v110, v92, v110
	v_cndmask_b32_e64 v110, v110, v92, s[22:23]
	s_waitcnt vmcnt(7)
	v_mul_f32_e32 v76, v76, v110
	v_mul_f32_e32 v111, v93, v111
	v_cndmask_b32_e64 v111, v111, v93, s[22:23]
	s_waitcnt vmcnt(6)
	v_mul_f32_e32 v77, v77, v111
	v_mul_f32_e32 v112, v94, v112
	v_cndmask_b32_e64 v112, v112, v94, s[22:23]
	s_waitcnt vmcnt(5)
	v_mul_f32_e32 v78, v78, v112
	v_mul_f32_e32 v113, v95, v113
	v_cndmask_b32_e64 v113, v113, v95, s[22:23]
	s_waitcnt vmcnt(4)
	v_mul_f32_e32 v79, v79, v113
	s_waitcnt lgkmcnt(0)
	v_mul_f32_e32 v114, v98, v114
	v_cndmask_b32_e64 v114, v114, v98, s[22:23]
	s_waitcnt vmcnt(3)
	v_mul_f32_e32 v80, v80, v114
	v_mul_f32_e32 v115, v99, v115
	v_cndmask_b32_e64 v115, v115, v99, s[22:23]
	s_waitcnt vmcnt(2)
	v_mul_f32_e32 v81, v81, v115
	v_mul_f32_e32 v116, v100, v116
	v_cndmask_b32_e64 v116, v116, v100, s[22:23]
	s_waitcnt vmcnt(1)
	v_mul_f32_e32 v82, v82, v116
	v_mul_f32_e32 v117, v101, v117
	v_cndmask_b32_e64 v117, v117, v101, s[22:23]
	s_waitcnt vmcnt(0)
	v_mul_f32_e32 v83, v83, v117
	ds_read_b128 v[84:87], v97 offset:17152
	ds_read_b128 v[88:91], v97 offset:17408
	ds_read_b128 v[92:95], v97 offset:17664
	ds_read_b128 v[98:101], v97 offset:17920
	ds_read_b128 v[102:105], v97 offset:18176
	ds_read_b128 v[106:109], v97 offset:18432
	ds_read_b128 v[110:113], v97 offset:18192
	ds_read_b128 v[114:117], v97 offset:18448
	ds_read_b128 v[42:45], v97 offset:18688
	ds_read_b128 v[46:49], v97 offset:18944
	s_waitcnt lgkmcnt(8)
	v_fma_f32 v9, -v8, v84, v9
	v_fma_f32 v10, -v8, v88, v10
	v_fma_f32 v10, -v9, v89, v10
	ds_read_b128 v[84:87], v97 offset:18704
	ds_read_b128 v[88:91], v97 offset:18960
	s_waitcnt lgkmcnt(8)
	v_fma_f32 v11, -v8, v92, v11
	v_fma_f32 v12, -v8, v98, v12
	v_fma_f32 v11, -v9, v93, v11
	v_fma_f32 v12, -v9, v99, v12
	v_fma_f32 v11, -v10, v94, v11
	v_fma_f32 v12, -v10, v100, v12
	v_fma_f32 v12, -v11, v101, v12
	ds_read_b128 v[92:95], v97 offset:19200
	ds_read_b128 v[98:101], v97 offset:19456
	s_waitcnt lgkmcnt(8)
	v_fma_f32 v13, -v8, v102, v13
	v_fma_f32 v14, -v8, v106, v14
	v_fma_f32 v13, -v9, v103, v13
	v_fma_f32 v14, -v9, v107, v14
	v_fma_f32 v13, -v10, v104, v13
	v_fma_f32 v14, -v10, v108, v14
	v_fma_f32 v13, -v11, v105, v13
	v_fma_f32 v14, -v11, v109, v14
	ds_read_b128 v[102:105], v97 offset:19216
	ds_read_b128 v[106:109], v97 offset:19472
	s_waitcnt lgkmcnt(8)
	v_fma_f32 v13, -v12, v110, v13
	v_fma_f32 v14, -v12, v114, v14
	v_fma_f32 v14, -v13, v115, v14
	ds_read_b128 v[110:113], v97 offset:19232
	ds_read_b128 v[114:117], v97 offset:19488
	s_waitcnt lgkmcnt(8)
	v_fma_f32 v15, -v8, v42, v15
	v_fma_f32 v16, -v8, v46, v16
	v_fma_f32 v15, -v9, v43, v15
	v_fma_f32 v16, -v9, v47, v16
	v_fma_f32 v15, -v10, v44, v15
	v_fma_f32 v16, -v10, v48, v16
	v_fma_f32 v15, -v11, v45, v15
	v_fma_f32 v16, -v11, v49, v16
	ds_read_b128 v[42:45], v97 offset:19712
	ds_read_b128 v[46:49], v97 offset:19968
	s_waitcnt lgkmcnt(8)
; NI void dn_chunk_local(const P& p, int dh, int n, char* lds) {
;     ...
;       for (int i = hb * 32; i < hb * 32 + 32; ++i) {
;         float a = x[i];
; #pragma unroll
;         for (int j = 0; j < i; ++j) a -= Ls[i * 64 + j] * x[j];
;         x[i] = a;
;         if ((i & 3) == 3) __builtin_amdgcn_sched_barrier(0);
;       }
	v_fma_f32 v15, -v12, v84, v15
	v_fma_f32 v16, -v12, v88, v16
	v_fma_f32 v15, -v13, v85, v15
	v_fma_f32 v16, -v13, v89, v16
	v_fma_f32 v15, -v14, v86, v15
	v_fma_f32 v16, -v14, v90, v16
	v_fma_f32 v16, -v15, v91, v16
	ds_read_b128 v[84:87], v97 offset:19728
	ds_read_b128 v[88:91], v97 offset:19984
	s_waitcnt lgkmcnt(8)
	v_fma_f32 v17, -v8, v92, v17
	v_fma_f32 v18, -v8, v98, v18
	v_fma_f32 v17, -v9, v93, v17
	v_fma_f32 v18, -v9, v99, v18
	v_fma_f32 v17, -v10, v94, v17
	v_fma_f32 v18, -v10, v100, v18
	v_fma_f32 v17, -v11, v95, v17
	v_fma_f32 v18, -v11, v101, v18
	ds_read_b128 v[92:95], v97 offset:19744
	ds_read_b128 v[98:101], v97 offset:20000
	s_waitcnt lgkmcnt(8)
	v_fma_f32 v17, -v12, v102, v17
	v_fma_f32 v18, -v12, v106, v18
	v_fma_f32 v17, -v13, v103, v17
	v_fma_f32 v18, -v13, v107, v18
	v_fma_f32 v17, -v14, v104, v17
	v_fma_f32 v18, -v14, v108, v18
	v_fma_f32 v17, -v15, v105, v17
	v_fma_f32 v18, -v15, v109, v18
	ds_read_b128 v[102:105], v97 offset:20224
	ds_read_b128 v[106:109], v97 offset:20480
	s_waitcnt lgkmcnt(8)
	v_fma_f32 v17, -v16, v110, v17
	v_fma_f32 v18, -v16, v114, v18
	v_fma_f32 v18, -v17, v115, v18
	ds_read_b128 v[110:113], v97 offset:20240
	ds_read_b128 v[114:117], v97 offset:20496
	s_waitcnt lgkmcnt(8)
	v_fma_f32 v19, -v8, v42, v19
	v_fma_f32 v20, -v8, v46, v20
	v_fma_f32 v19, -v9, v43, v19
	v_fma_f32 v20, -v9, v47, v20
	v_fma_f32 v19, -v10, v44, v19
	v_fma_f32 v20, -v10, v48, v20
	v_fma_f32 v19, -v11, v45, v19
	v_fma_f32 v20, -v11, v49, v20
	ds_read_b128 v[42:45], v97 offset:20256
	ds_read_b128 v[46:49], v97 offset:20512
	s_waitcnt lgkmcnt(8)
	v_fma_f32 v19, -v12, v84, v19
	v_fma_f32 v20, -v12, v88, v20
	v_fma_f32 v19, -v13, v85, v19
	v_fma_f32 v20, -v13, v89, v20
	v_fma_f32 v19, -v14, v86, v19
	v_fma_f32 v20, -v14, v90, v20
	v_fma_f32 v19, -v15, v87, v19
	v_fma_f32 v20, -v15, v91, v20
	ds_read_b128 v[84:87], v97 offset:20272
	ds_read_b128 v[88:91], v97 offset:20528
	s_waitcnt lgkmcnt(8)
	v_fma_f32 v19, -v16, v92, v19
	v_fma_f32 v20, -v16, v98, v20
	v_fma_f32 v19, -v17, v93, v19
	v_fma_f32 v20, -v17, v99, v20
	v_fma_f32 v19, -v18, v94, v19
	v_fma_f32 v20, -v18, v100, v20
	v_fma_f32 v20, -v19, v101, v20
	ds_read_b128 v[92:95], v97 offset:20736
	ds_read_b128 v[98:101], v97 offset:20992
	s_waitcnt lgkmcnt(8)
	v_fma_f32 v21, -v8, v102, v21
	v_fma_f32 v22, -v8, v106, v22
	v_fma_f32 v21, -v9, v103, v21
	v_fma_f32 v22, -v9, v107, v22
	v_fma_f32 v21, -v10, v104, v21
	v_fma_f32 v22, -v10, v108, v22
	v_fma_f32 v21, -v11, v105, v21
	v_fma_f32 v22, -v11, v109, v22
	ds_read_b128 v[102:105], v97 offset:20752
	ds_read_b128 v[106:109], v97 offset:21008
	s_waitcnt lgkmcnt(8)
	v_fma_f32 v21, -v12, v110, v21
	v_fma_f32 v22, -v12, v114, v22
	v_fma_f32 v21, -v13, v111, v21
	v_fma_f32 v22, -v13, v115, v22
	v_fma_f32 v21, -v14, v112, v21
	v_fma_f32 v22, -v14, v116, v22
	v_fma_f32 v21, -v15, v113, v21
	v_fma_f32 v22, -v15, v117, v22
	ds_read_b128 v[110:113], v97 offset:20768
	ds_read_b128 v[114:117], v97 offset:21024
	s_waitcnt lgkmcnt(8)
	v_fma_f32 v21, -v16, v42, v21
	v_fma_f32 v22, -v16, v46, v22
	v_fma_f32 v21, -v17, v43, v21
	v_fma_f32 v22, -v17, v47, v22
	v_fma_f32 v21, -v18, v44, v21
	v_fma_f32 v22, -v18, v48, v22
	v_fma_f32 v21, -v19, v45, v21
	v_fma_f32 v22, -v19, v49, v22
	ds_read_b128 v[42:45], v97 offset:20784
	ds_read_b128 v[46:49], v97 offset:21040
	s_waitcnt lgkmcnt(8)
	v_fma_f32 v21, -v20, v84, v21
	v_fma_f32 v22, -v20, v88, v22
	v_fma_f32 v22, -v21, v89, v22
	ds_read_b128 v[84:87], v97 offset:21248
	ds_read_b128 v[88:91], v97 offset:21504
	s_waitcnt lgkmcnt(8)
	v_fma_f32 v23, -v8, v92, v23
	v_fma_f32 v24, -v8, v98, v24
	v_fma_f32 v23, -v9, v93, v23
	v_fma_f32 v24, -v9, v99, v24
	v_fma_f32 v23, -v10, v94, v23
	v_fma_f32 v24, -v10, v100, v24
	v_fma_f32 v23, -v11, v95, v23
	v_fma_f32 v24, -v11, v101, v24
	ds_read_b128 v[92:95], v97 offset:21264
	ds_read_b128 v[98:101], v97 offset:21520
	s_waitcnt lgkmcnt(8)
	v_fma_f32 v23, -v12, v102, v23
	v_fma_f32 v24, -v12, v106, v24
	v_fma_f32 v23, -v13, v103, v23
	v_fma_f32 v24, -v13, v107, v24
	v_fma_f32 v23, -v14, v104, v23
	v_fma_f32 v24, -v14, v108, v24
	v_fma_f32 v23, -v15, v105, v23
	v_fma_f32 v24, -v15, v109, v24
	ds_read_b128 v[102:105], v97 offset:21280
	ds_read_b128 v[106:109], v97 offset:21536
	s_waitcnt lgkmcnt(8)
	v_fma_f32 v23, -v16, v110, v23
	v_fma_f32 v24, -v16, v114, v24
	v_fma_f32 v23, -v17, v111, v23
	v_fma_f32 v24, -v17, v115, v24
	v_fma_f32 v23, -v18, v112, v23
	v_fma_f32 v24, -v18, v116, v24
	v_fma_f32 v23, -v19, v113, v23
	v_fma_f32 v24, -v19, v117, v24
	ds_read_b128 v[110:113], v97 offset:21296
	ds_read_b128 v[114:117], v97 offset:21552
	s_waitcnt lgkmcnt(8)
	v_fma_f32 v23, -v20, v42, v23
	v_fma_f32 v24, -v20, v46, v24
	v_fma_f32 v23, -v21, v43, v23
	v_fma_f32 v24, -v21, v47, v24
	v_fma_f32 v23, -v22, v44, v23
	v_fma_f32 v24, -v22, v48, v24
	v_fma_f32 v24, -v23, v49, v24
	ds_read_b128 v[42:45], v97 offset:21312
	ds_read_b128 v[46:49], v97 offset:21568
	s_waitcnt lgkmcnt(8)
	v_fma_f32 v25, -v8, v84, v25
	v_fma_f32 v26, -v8, v88, v26
	v_fma_f32 v25, -v9, v85, v25
	v_fma_f32 v26, -v9, v89, v26
	v_fma_f32 v25, -v10, v86, v25
	v_fma_f32 v26, -v10, v90, v26
	v_fma_f32 v25, -v11, v87, v25
	v_fma_f32 v26, -v11, v91, v26
	ds_read_b128 v[84:87], v97 offset:21760
	ds_read_b128 v[88:91], v97 offset:22016
	s_waitcnt lgkmcnt(8)
	v_fma_f32 v25, -v12, v92, v25
	v_fma_f32 v26, -v12, v98, v26
	v_fma_f32 v25, -v13, v93, v25
	v_fma_f32 v26, -v13, v99, v26
	v_fma_f32 v25, -v14, v94, v25
	v_fma_f32 v26, -v14, v100, v26
	v_fma_f32 v25, -v15, v95, v25
	v_fma_f32 v26, -v15, v101, v26
	ds_read_b128 v[92:95], v97 offset:21776
	ds_read_b128 v[98:101], v97 offset:22032
	s_waitcnt lgkmcnt(8)
; NI void dn_chunk_local(const P& p, int dh, int n, char* lds) {
;     ...
;       for (int i = hb * 32; i < hb * 32 + 32; ++i) {
;         float a = x[i];
; #pragma unroll
;         for (int j = 0; j < i; ++j) a -= Ls[i * 64 + j] * x[j];
;         x[i] = a;
;         if ((i & 3) == 3) __builtin_amdgcn_sched_barrier(0);
;       }
	v_fma_f32 v25, -v16, v102, v25
	v_fma_f32 v26, -v16, v106, v26
	v_fma_f32 v25, -v17, v103, v25
	v_fma_f32 v26, -v17, v107, v26
	v_fma_f32 v25, -v18, v104, v25
	v_fma_f32 v26, -v18, v108, v26
	v_fma_f32 v25, -v19, v105, v25
	v_fma_f32 v26, -v19, v109, v26
	ds_read_b128 v[102:105], v97 offset:21792
	ds_read_b128 v[106:109], v97 offset:22048
	s_waitcnt lgkmcnt(8)
	v_fma_f32 v25, -v20, v110, v25
	v_fma_f32 v26, -v20, v114, v26
	v_fma_f32 v25, -v21, v111, v25
	v_fma_f32 v26, -v21, v115, v26
	v_fma_f32 v25, -v22, v112, v25
	v_fma_f32 v26, -v22, v116, v26
	v_fma_f32 v25, -v23, v113, v25
	v_fma_f32 v26, -v23, v117, v26
	ds_read_b128 v[110:113], v97 offset:21808
	ds_read_b128 v[114:117], v97 offset:22064
	s_waitcnt lgkmcnt(8)
	v_fma_f32 v25, -v24, v42, v25
	v_fma_f32 v26, -v24, v46, v26
	v_fma_f32 v26, -v25, v47, v26
	ds_read_b128 v[42:45], v97 offset:21824
	ds_read_b128 v[46:49], v97 offset:22080
	s_waitcnt lgkmcnt(8)
	v_fma_f32 v27, -v8, v84, v27
	v_fma_f32 v28, -v8, v88, v28
	v_fma_f32 v27, -v9, v85, v27
	v_fma_f32 v28, -v9, v89, v28
	v_fma_f32 v27, -v10, v86, v27
	v_fma_f32 v28, -v10, v90, v28
	v_fma_f32 v27, -v11, v87, v27
	v_fma_f32 v28, -v11, v91, v28
	ds_read_b128 v[84:87], v97 offset:22272
	ds_read_b128 v[88:91], v97 offset:22528
	s_waitcnt lgkmcnt(8)
	v_fma_f32 v27, -v12, v92, v27
	v_fma_f32 v28, -v12, v98, v28
	v_fma_f32 v27, -v13, v93, v27
	v_fma_f32 v28, -v13, v99, v28
	v_fma_f32 v27, -v14, v94, v27
	v_fma_f32 v28, -v14, v100, v28
	v_fma_f32 v27, -v15, v95, v27
	v_fma_f32 v28, -v15, v101, v28
	ds_read_b128 v[92:95], v97 offset:22288
	ds_read_b128 v[98:101], v97 offset:22544
	s_waitcnt lgkmcnt(8)
	v_fma_f32 v27, -v16, v102, v27
	v_fma_f32 v28, -v16, v106, v28
	v_fma_f32 v27, -v17, v103, v27
	v_fma_f32 v28, -v17, v107, v28
	v_fma_f32 v27, -v18, v104, v27
	v_fma_f32 v28, -v18, v108, v28
	v_fma_f32 v27, -v19, v105, v27
	v_fma_f32 v28, -v19, v109, v28
	ds_read_b128 v[102:105], v97 offset:22304
	ds_read_b128 v[106:109], v97 offset:22560
	s_waitcnt lgkmcnt(8)
	v_fma_f32 v27, -v20, v110, v27
	v_fma_f32 v28, -v20, v114, v28
	v_fma_f32 v27, -v21, v111, v27
	v_fma_f32 v28, -v21, v115, v28
	v_fma_f32 v27, -v22, v112, v27
	v_fma_f32 v28, -v22, v116, v28
	v_fma_f32 v27, -v23, v113, v27
	v_fma_f32 v28, -v23, v117, v28
	ds_read_b128 v[110:113], v97 offset:22320
	ds_read_b128 v[114:117], v97 offset:22576
	s_waitcnt lgkmcnt(8)
	v_fma_f32 v27, -v24, v42, v27
	v_fma_f32 v28, -v24, v46, v28
	v_fma_f32 v27, -v25, v43, v27
	v_fma_f32 v28, -v25, v47, v28
	v_fma_f32 v27, -v26, v44, v27
	v_fma_f32 v28, -v26, v48, v28
	v_fma_f32 v28, -v27, v49, v28
	ds_read_b128 v[42:45], v97 offset:22336
	ds_read_b128 v[46:49], v97 offset:22592
	s_waitcnt lgkmcnt(8)
	v_fma_f32 v29, -v8, v84, v29
	v_fma_f32 v30, -v8, v88, v30
	v_fma_f32 v29, -v9, v85, v29
	v_fma_f32 v30, -v9, v89, v30
	v_fma_f32 v29, -v10, v86, v29
	v_fma_f32 v30, -v10, v90, v30
	v_fma_f32 v29, -v11, v87, v29
	v_fma_f32 v30, -v11, v91, v30
	ds_read_b128 v[84:87], v97 offset:22352
	ds_read_b128 v[88:91], v97 offset:22608
	s_waitcnt lgkmcnt(8)
	v_fma_f32 v29, -v12, v92, v29
	v_fma_f32 v30, -v12, v98, v30
	v_fma_f32 v29, -v13, v93, v29
	v_fma_f32 v30, -v13, v99, v30
	v_fma_f32 v29, -v14, v94, v29
	v_fma_f32 v30, -v14, v100, v30
	v_fma_f32 v29, -v15, v95, v29
	v_fma_f32 v30, -v15, v101, v30
	ds_read_b128 v[92:95], v97 offset:22784
	ds_read_b128 v[98:101], v97 offset:23040
	s_waitcnt lgkmcnt(8)
	v_fma_f32 v29, -v16, v102, v29
	v_fma_f32 v30, -v16, v106, v30
	v_fma_f32 v29, -v17, v103, v29
	v_fma_f32 v30, -v17, v107, v30
	v_fma_f32 v29, -v18, v104, v29
	v_fma_f32 v30, -v18, v108, v30
	v_fma_f32 v29, -v19, v105, v29
	v_fma_f32 v30, -v19, v109, v30
	ds_read_b128 v[102:105], v97 offset:22800
	ds_read_b128 v[106:109], v97 offset:23056
	s_waitcnt lgkmcnt(8)
	v_fma_f32 v29, -v20, v110, v29
	v_fma_f32 v30, -v20, v114, v30
	v_fma_f32 v29, -v21, v111, v29
	v_fma_f32 v30, -v21, v115, v30
	v_fma_f32 v29, -v22, v112, v29
	v_fma_f32 v30, -v22, v116, v30
	v_fma_f32 v29, -v23, v113, v29
	v_fma_f32 v30, -v23, v117, v30
	ds_read_b128 v[110:113], v97 offset:22816
	ds_read_b128 v[114:117], v97 offset:23072
	s_waitcnt lgkmcnt(8)
	v_fma_f32 v29, -v24, v42, v29
	v_fma_f32 v30, -v24, v46, v30
	v_fma_f32 v29, -v25, v43, v29
	v_fma_f32 v30, -v25, v47, v30
	v_fma_f32 v29, -v26, v44, v29
	v_fma_f32 v30, -v26, v48, v30
	v_fma_f32 v29, -v27, v45, v29
	v_fma_f32 v30, -v27, v49, v30
	ds_read_b128 v[42:45], v97 offset:22832
	ds_read_b128 v[46:49], v97 offset:23088
	s_waitcnt lgkmcnt(8)
	v_fma_f32 v29, -v28, v84, v29
	v_fma_f32 v30, -v28, v88, v30
	v_fma_f32 v30, -v29, v89, v30
	ds_read_b128 v[84:87], v97 offset:22848
	ds_read_b128 v[88:91], v97 offset:23104
	s_waitcnt lgkmcnt(8)
	v_fma_f32 v31, -v8, v92, v31
	v_fma_f32 v32, -v8, v98, v32
	v_fma_f32 v31, -v9, v93, v31
	v_fma_f32 v32, -v9, v99, v32
	v_fma_f32 v31, -v10, v94, v31
	v_fma_f32 v32, -v10, v100, v32
	v_fma_f32 v31, -v11, v95, v31
	v_fma_f32 v32, -v11, v101, v32
	ds_read_b128 v[92:95], v97 offset:22864
	ds_read_b128 v[98:101], v97 offset:23120
	s_waitcnt lgkmcnt(8)
	v_fma_f32 v31, -v12, v102, v31
	v_fma_f32 v32, -v12, v106, v32
	v_fma_f32 v31, -v13, v103, v31
	v_fma_f32 v32, -v13, v107, v32
	v_fma_f32 v31, -v14, v104, v31
	v_fma_f32 v32, -v14, v108, v32
	v_fma_f32 v31, -v15, v105, v31
	v_fma_f32 v32, -v15, v109, v32
	ds_read_b128 v[102:105], v97 offset:23296
	ds_read_b128 v[106:109], v97 offset:23552
	s_waitcnt lgkmcnt(8)
	v_fma_f32 v31, -v16, v110, v31
	v_fma_f32 v32, -v16, v114, v32
	v_fma_f32 v31, -v17, v111, v31
	v_fma_f32 v32, -v17, v115, v32
	v_fma_f32 v31, -v18, v112, v31
	v_fma_f32 v32, -v18, v116, v32
	v_fma_f32 v31, -v19, v113, v31
	v_fma_f32 v32, -v19, v117, v32
	ds_read_b128 v[110:113], v97 offset:23312
	ds_read_b128 v[114:117], v97 offset:23568
	s_waitcnt lgkmcnt(8)
; NI void dn_chunk_local(const P& p, int dh, int n, char* lds) {
;     ...
;       for (int i = hb * 32; i < hb * 32 + 32; ++i) {
;         float a = x[i];
; #pragma unroll
;         for (int j = 0; j < i; ++j) a -= Ls[i * 64 + j] * x[j];
;         x[i] = a;
;         if ((i & 3) == 3) __builtin_amdgcn_sched_barrier(0);
;       }
	v_fma_f32 v31, -v20, v42, v31
	v_fma_f32 v32, -v20, v46, v32
	v_fma_f32 v31, -v21, v43, v31
	v_fma_f32 v32, -v21, v47, v32
	v_fma_f32 v31, -v22, v44, v31
	v_fma_f32 v32, -v22, v48, v32
	v_fma_f32 v31, -v23, v45, v31
	v_fma_f32 v32, -v23, v49, v32
	ds_read_b128 v[42:45], v97 offset:23328
	ds_read_b128 v[46:49], v97 offset:23584
	s_waitcnt lgkmcnt(8)
	v_fma_f32 v31, -v24, v84, v31
	v_fma_f32 v32, -v24, v88, v32
	v_fma_f32 v31, -v25, v85, v31
	v_fma_f32 v32, -v25, v89, v32
	v_fma_f32 v31, -v26, v86, v31
	v_fma_f32 v32, -v26, v90, v32
	v_fma_f32 v31, -v27, v87, v31
	v_fma_f32 v32, -v27, v91, v32
	ds_read_b128 v[84:87], v97 offset:23344
	ds_read_b128 v[88:91], v97 offset:23600
	s_waitcnt lgkmcnt(8)
	v_fma_f32 v31, -v28, v92, v31
	v_fma_f32 v32, -v28, v98, v32
	v_fma_f32 v31, -v29, v93, v31
	v_fma_f32 v32, -v29, v99, v32
	v_fma_f32 v31, -v30, v94, v31
	v_fma_f32 v32, -v30, v100, v32
	v_fma_f32 v32, -v31, v101, v32
	ds_read_b128 v[92:95], v97 offset:23360
	ds_read_b128 v[98:101], v97 offset:23616
	s_waitcnt lgkmcnt(8)
	v_fma_f32 v33, -v8, v102, v33
	v_fma_f32 v34, -v8, v106, v34
	v_fma_f32 v33, -v9, v103, v33
	v_fma_f32 v34, -v9, v107, v34
	v_fma_f32 v33, -v10, v104, v33
	v_fma_f32 v34, -v10, v108, v34
	v_fma_f32 v33, -v11, v105, v33
	v_fma_f32 v34, -v11, v109, v34
	ds_read_b128 v[102:105], v97 offset:23376
	ds_read_b128 v[106:109], v97 offset:23632
	s_waitcnt lgkmcnt(8)
	v_fma_f32 v33, -v12, v110, v33
	v_fma_f32 v34, -v12, v114, v34
	v_fma_f32 v33, -v13, v111, v33
	v_fma_f32 v34, -v13, v115, v34
	v_fma_f32 v33, -v14, v112, v33
	v_fma_f32 v34, -v14, v116, v34
	v_fma_f32 v33, -v15, v113, v33
	v_fma_f32 v34, -v15, v117, v34
	ds_read_b128 v[110:113], v97 offset:23392
	ds_read_b128 v[114:117], v97 offset:23648
	s_waitcnt lgkmcnt(8)
	v_fma_f32 v33, -v16, v42, v33
	v_fma_f32 v34, -v16, v46, v34
	v_fma_f32 v33, -v17, v43, v33
	v_fma_f32 v34, -v17, v47, v34
	v_fma_f32 v33, -v18, v44, v33
	v_fma_f32 v34, -v18, v48, v34
	v_fma_f32 v33, -v19, v45, v33
	v_fma_f32 v34, -v19, v49, v34
	ds_read_b128 v[42:45], v97 offset:23808
	ds_read_b128 v[46:49], v97 offset:24064
	s_waitcnt lgkmcnt(8)
	v_fma_f32 v33, -v20, v84, v33
	v_fma_f32 v34, -v20, v88, v34
	v_fma_f32 v33, -v21, v85, v33
	v_fma_f32 v34, -v21, v89, v34
	v_fma_f32 v33, -v22, v86, v33
	v_fma_f32 v34, -v22, v90, v34
	v_fma_f32 v33, -v23, v87, v33
	v_fma_f32 v34, -v23, v91, v34
	ds_read_b128 v[84:87], v97 offset:23824
	ds_read_b128 v[88:91], v97 offset:24080
	s_waitcnt lgkmcnt(8)
	v_fma_f32 v33, -v24, v92, v33
	v_fma_f32 v34, -v24, v98, v34
	v_fma_f32 v33, -v25, v93, v33
	v_fma_f32 v34, -v25, v99, v34
	v_fma_f32 v33, -v26, v94, v33
	v_fma_f32 v34, -v26, v100, v34
	v_fma_f32 v33, -v27, v95, v33
	v_fma_f32 v34, -v27, v101, v34
	ds_read_b128 v[92:95], v97 offset:23840
	ds_read_b128 v[98:101], v97 offset:24096
	s_waitcnt lgkmcnt(8)
	v_fma_f32 v33, -v28, v102, v33
	v_fma_f32 v34, -v28, v106, v34
	v_fma_f32 v33, -v29, v103, v33
	v_fma_f32 v34, -v29, v107, v34
	v_fma_f32 v33, -v30, v104, v33
	v_fma_f32 v34, -v30, v108, v34
	v_fma_f32 v33, -v31, v105, v33
	v_fma_f32 v34, -v31, v109, v34
	ds_read_b128 v[102:105], v97 offset:23856
	ds_read_b128 v[106:109], v97 offset:24112
	s_waitcnt lgkmcnt(8)
	v_fma_f32 v33, -v32, v110, v33
	v_fma_f32 v34, -v32, v114, v34
	v_fma_f32 v34, -v33, v115, v34
	ds_read_b128 v[110:113], v97 offset:23872
	ds_read_b128 v[114:117], v97 offset:24128
	s_waitcnt lgkmcnt(8)
	v_fma_f32 v35, -v8, v42, v35
	v_fma_f32 v36, -v8, v46, v36
	v_fma_f32 v35, -v9, v43, v35
	v_fma_f32 v36, -v9, v47, v36
	v_fma_f32 v35, -v10, v44, v35
	v_fma_f32 v36, -v10, v48, v36
	v_fma_f32 v35, -v11, v45, v35
	v_fma_f32 v36, -v11, v49, v36
	ds_read_b128 v[42:45], v97 offset:23888
	ds_read_b128 v[46:49], v97 offset:24144
	s_waitcnt lgkmcnt(8)
	v_fma_f32 v35, -v12, v84, v35
	v_fma_f32 v36, -v12, v88, v36
	v_fma_f32 v35, -v13, v85, v35
	v_fma_f32 v36, -v13, v89, v36
	v_fma_f32 v35, -v14, v86, v35
	v_fma_f32 v36, -v14, v90, v36
	v_fma_f32 v35, -v15, v87, v35
	v_fma_f32 v36, -v15, v91, v36
	ds_read_b128 v[84:87], v97 offset:23904
	ds_read_b128 v[88:91], v97 offset:24160
	s_waitcnt lgkmcnt(8)
	v_fma_f32 v35, -v16, v92, v35
	v_fma_f32 v36, -v16, v98, v36
	v_fma_f32 v35, -v17, v93, v35
	v_fma_f32 v36, -v17, v99, v36
	v_fma_f32 v35, -v18, v94, v35
	v_fma_f32 v36, -v18, v100, v36
	v_fma_f32 v35, -v19, v95, v35
	v_fma_f32 v36, -v19, v101, v36
	ds_read_b128 v[92:95], v97 offset:24320
	ds_read_b128 v[98:101], v97 offset:24576
	s_waitcnt lgkmcnt(8)
	v_fma_f32 v35, -v20, v102, v35
	v_fma_f32 v36, -v20, v106, v36
	v_fma_f32 v35, -v21, v103, v35
	v_fma_f32 v36, -v21, v107, v36
	v_fma_f32 v35, -v22, v104, v35
	v_fma_f32 v36, -v22, v108, v36
	v_fma_f32 v35, -v23, v105, v35
	v_fma_f32 v36, -v23, v109, v36
	ds_read_b128 v[102:105], v97 offset:24336
	ds_read_b128 v[106:109], v97 offset:24592
	s_waitcnt lgkmcnt(8)
	v_fma_f32 v35, -v24, v110, v35
	v_fma_f32 v36, -v24, v114, v36
	v_fma_f32 v35, -v25, v111, v35
	v_fma_f32 v36, -v25, v115, v36
	v_fma_f32 v35, -v26, v112, v35
	v_fma_f32 v36, -v26, v116, v36
	v_fma_f32 v35, -v27, v113, v35
	v_fma_f32 v36, -v27, v117, v36
	ds_read_b128 v[110:113], v97 offset:24352
	ds_read_b128 v[114:117], v97 offset:24608
	s_waitcnt lgkmcnt(8)
	v_fma_f32 v35, -v28, v42, v35
	v_fma_f32 v36, -v28, v46, v36
	v_fma_f32 v35, -v29, v43, v35
	v_fma_f32 v36, -v29, v47, v36
	v_fma_f32 v35, -v30, v44, v35
	v_fma_f32 v36, -v30, v48, v36
	v_fma_f32 v35, -v31, v45, v35
	v_fma_f32 v36, -v31, v49, v36
	ds_read_b128 v[42:45], v97 offset:24368
	ds_read_b128 v[46:49], v97 offset:24624
	s_waitcnt lgkmcnt(8)
; NI void dn_chunk_local(const P& p, int dh, int n, char* lds) {
;     ...
;       for (int i = hb * 32; i < hb * 32 + 32; ++i) {
;         float a = x[i];
; #pragma unroll
;         for (int j = 0; j < i; ++j) a -= Ls[i * 64 + j] * x[j];
;         x[i] = a;
;         if ((i & 3) == 3) __builtin_amdgcn_sched_barrier(0);
;       }
	v_fma_f32 v35, -v32, v84, v35
	v_fma_f32 v36, -v32, v88, v36
	v_fma_f32 v35, -v33, v85, v35
	v_fma_f32 v36, -v33, v89, v36
	v_fma_f32 v35, -v34, v86, v35
	v_fma_f32 v36, -v34, v90, v36
	v_fma_f32 v36, -v35, v91, v36
	ds_read_b128 v[84:87], v97 offset:24384
	ds_read_b128 v[88:91], v97 offset:24640
	s_waitcnt lgkmcnt(8)
	v_fma_f32 v37, -v8, v92, v37
	v_fma_f32 v38, -v8, v98, v38
	v_fma_f32 v37, -v9, v93, v37
	v_fma_f32 v38, -v9, v99, v38
	v_fma_f32 v37, -v10, v94, v37
	v_fma_f32 v38, -v10, v100, v38
	v_fma_f32 v37, -v11, v95, v37
	v_fma_f32 v38, -v11, v101, v38
	ds_read_b128 v[92:95], v97 offset:24400
	ds_read_b128 v[98:101], v97 offset:24656
	s_waitcnt lgkmcnt(8)
	v_fma_f32 v37, -v12, v102, v37
	v_fma_f32 v38, -v12, v106, v38
	v_fma_f32 v37, -v13, v103, v37
	v_fma_f32 v38, -v13, v107, v38
	v_fma_f32 v37, -v14, v104, v37
	v_fma_f32 v38, -v14, v108, v38
	v_fma_f32 v37, -v15, v105, v37
	v_fma_f32 v38, -v15, v109, v38
	ds_read_b128 v[102:105], v97 offset:24416
	ds_read_b128 v[106:109], v97 offset:24672
	s_waitcnt lgkmcnt(8)
	v_fma_f32 v37, -v16, v110, v37
	v_fma_f32 v38, -v16, v114, v38
	v_fma_f32 v37, -v17, v111, v37
	v_fma_f32 v38, -v17, v115, v38
	v_fma_f32 v37, -v18, v112, v37
	v_fma_f32 v38, -v18, v116, v38
	v_fma_f32 v37, -v19, v113, v37
	v_fma_f32 v38, -v19, v117, v38
	ds_read_b128 v[110:113], v97 offset:24432
	ds_read_b128 v[114:117], v97 offset:24688
	s_waitcnt lgkmcnt(8)
	v_fma_f32 v37, -v20, v42, v37
	v_fma_f32 v38, -v20, v46, v38
	v_fma_f32 v37, -v21, v43, v37
	v_fma_f32 v38, -v21, v47, v38
	v_fma_f32 v37, -v22, v44, v37
	v_fma_f32 v38, -v22, v48, v38
	v_fma_f32 v37, -v23, v45, v37
	v_fma_f32 v38, -v23, v49, v38
	ds_read_b128 v[42:45], v97 offset:24832
	ds_read_b128 v[46:49], v97 offset:25088
	s_waitcnt lgkmcnt(8)
	v_fma_f32 v37, -v24, v84, v37
	v_fma_f32 v38, -v24, v88, v38
	v_fma_f32 v37, -v25, v85, v37
	v_fma_f32 v38, -v25, v89, v38
	v_fma_f32 v37, -v26, v86, v37
	v_fma_f32 v38, -v26, v90, v38
	v_fma_f32 v37, -v27, v87, v37
	v_fma_f32 v38, -v27, v91, v38
	ds_read_b128 v[84:87], v97 offset:24848
	ds_read_b128 v[88:91], v97 offset:25104
	s_waitcnt lgkmcnt(8)
	v_fma_f32 v37, -v28, v92, v37
	v_fma_f32 v38, -v28, v98, v38
	v_fma_f32 v37, -v29, v93, v37
	v_fma_f32 v38, -v29, v99, v38
	v_fma_f32 v37, -v30, v94, v37
	v_fma_f32 v38, -v30, v100, v38
	v_fma_f32 v37, -v31, v95, v37
	v_fma_f32 v38, -v31, v101, v38
	ds_read_b128 v[92:95], v97 offset:24864
	ds_read_b128 v[98:101], v97 offset:25120
	s_waitcnt lgkmcnt(8)
	v_fma_f32 v37, -v32, v102, v37
	v_fma_f32 v38, -v32, v106, v38
	v_fma_f32 v37, -v33, v103, v37
	v_fma_f32 v38, -v33, v107, v38
	v_fma_f32 v37, -v34, v104, v37
	v_fma_f32 v38, -v34, v108, v38
	v_fma_f32 v37, -v35, v105, v37
	v_fma_f32 v38, -v35, v109, v38
	ds_read_b128 v[102:105], v97 offset:24880
	ds_read_b128 v[106:109], v97 offset:25136
	s_waitcnt lgkmcnt(8)
	v_fma_f32 v37, -v36, v110, v37
	v_fma_f32 v38, -v36, v114, v38
	v_fma_f32 v38, -v37, v115, v38
	ds_read_b128 v[110:113], v97 offset:24896
	ds_read_b128 v[114:117], v97 offset:25152
	s_waitcnt lgkmcnt(8)
	v_fma_f32 v39, -v8, v42, v39
	v_fma_f32 v52, -v8, v46, v52
	v_fma_f32 v39, -v9, v43, v39
	v_fma_f32 v52, -v9, v47, v52
	v_fma_f32 v39, -v10, v44, v39
	v_fma_f32 v52, -v10, v48, v52
	v_fma_f32 v39, -v11, v45, v39
	v_fma_f32 v52, -v11, v49, v52
	ds_read_b128 v[42:45], v97 offset:24912
	ds_read_b128 v[46:49], v97 offset:25168
	s_waitcnt lgkmcnt(8)
	v_fma_f32 v39, -v12, v84, v39
	v_fma_f32 v52, -v12, v88, v52
	v_fma_f32 v39, -v13, v85, v39
	v_fma_f32 v52, -v13, v89, v52
	v_fma_f32 v39, -v14, v86, v39
	v_fma_f32 v52, -v14, v90, v52
	v_fma_f32 v39, -v15, v87, v39
	v_fma_f32 v52, -v15, v91, v52
	ds_read_b128 v[84:87], v97 offset:24928
	ds_read_b128 v[88:91], v97 offset:25184
	s_waitcnt lgkmcnt(8)
	v_fma_f32 v39, -v16, v92, v39
	v_fma_f32 v52, -v16, v98, v52
	v_fma_f32 v39, -v17, v93, v39
	v_fma_f32 v52, -v17, v99, v52
	v_fma_f32 v39, -v18, v94, v39
	v_fma_f32 v52, -v18, v100, v52
	v_fma_f32 v39, -v19, v95, v39
	v_fma_f32 v52, -v19, v101, v52
	ds_read_b128 v[92:95], v97 offset:24944
	ds_read_b128 v[98:101], v97 offset:25200
	s_waitcnt lgkmcnt(8)
	v_fma_f32 v39, -v20, v102, v39
	v_fma_f32 v52, -v20, v106, v52
	v_fma_f32 v39, -v21, v103, v39
	v_fma_f32 v52, -v21, v107, v52
	v_fma_f32 v39, -v22, v104, v39
	v_fma_f32 v52, -v22, v108, v52
	v_fma_f32 v39, -v23, v105, v39
	v_fma_f32 v52, -v23, v109, v52
	ds_read_b128 v[102:105], v97 offset:25344
	ds_read_b128 v[106:109], v97 offset:25600
	s_waitcnt lgkmcnt(8)
	v_fma_f32 v39, -v24, v110, v39
	v_fma_f32 v52, -v24, v114, v52
	v_fma_f32 v39, -v25, v111, v39
	v_fma_f32 v52, -v25, v115, v52
	v_fma_f32 v39, -v26, v112, v39
	v_fma_f32 v52, -v26, v116, v52
	v_fma_f32 v39, -v27, v113, v39
	v_fma_f32 v52, -v27, v117, v52
	ds_read_b128 v[110:113], v97 offset:25360
	ds_read_b128 v[114:117], v97 offset:25616
	s_waitcnt lgkmcnt(8)
	v_fma_f32 v39, -v28, v42, v39
	v_fma_f32 v52, -v28, v46, v52
	v_fma_f32 v39, -v29, v43, v39
	v_fma_f32 v52, -v29, v47, v52
	v_fma_f32 v39, -v30, v44, v39
	v_fma_f32 v52, -v30, v48, v52
	v_fma_f32 v39, -v31, v45, v39
	v_fma_f32 v52, -v31, v49, v52
	ds_read_b128 v[42:45], v97 offset:25376
	ds_read_b128 v[46:49], v97 offset:25632
	s_waitcnt lgkmcnt(8)
	v_fma_f32 v39, -v32, v84, v39
	v_fma_f32 v52, -v32, v88, v52
	v_fma_f32 v39, -v33, v85, v39
	v_fma_f32 v52, -v33, v89, v52
	v_fma_f32 v39, -v34, v86, v39
	v_fma_f32 v52, -v34, v90, v52
	v_fma_f32 v39, -v35, v87, v39
	v_fma_f32 v52, -v35, v91, v52
	ds_read_b128 v[84:87], v97 offset:25392
	ds_read_b128 v[88:91], v97 offset:25648
	s_waitcnt lgkmcnt(8)
; NI void dn_chunk_local(const P& p, int dh, int n, char* lds) {
;     ...
;       for (int i = hb * 32; i < hb * 32 + 32; ++i) {
;         float a = x[i];
; #pragma unroll
;         for (int j = 0; j < i; ++j) a -= Ls[i * 64 + j] * x[j];
;         x[i] = a;
;         if ((i & 3) == 3) __builtin_amdgcn_sched_barrier(0);
;       }
	v_fma_f32 v39, -v36, v92, v39
	v_fma_f32 v52, -v36, v98, v52
	v_fma_f32 v39, -v37, v93, v39
	v_fma_f32 v52, -v37, v99, v52
	v_fma_f32 v39, -v38, v94, v39
	v_fma_f32 v52, -v38, v100, v52
	v_fma_f32 v52, -v39, v101, v52
	ds_read_b128 v[92:95], v97 offset:25408
	ds_read_b128 v[98:101], v97 offset:25664
	s_waitcnt lgkmcnt(8)
	v_fma_f32 v53, -v8, v102, v53
	v_fma_f32 v54, -v8, v106, v54
	v_fma_f32 v53, -v9, v103, v53
	v_fma_f32 v54, -v9, v107, v54
	v_fma_f32 v53, -v10, v104, v53
	v_fma_f32 v54, -v10, v108, v54
	v_fma_f32 v53, -v11, v105, v53
	v_fma_f32 v54, -v11, v109, v54
	ds_read_b128 v[102:105], v97 offset:25424
	ds_read_b128 v[106:109], v97 offset:25680
	s_waitcnt lgkmcnt(8)
	v_fma_f32 v53, -v12, v110, v53
	v_fma_f32 v54, -v12, v114, v54
	v_fma_f32 v53, -v13, v111, v53
	v_fma_f32 v54, -v13, v115, v54
	v_fma_f32 v53, -v14, v112, v53
	v_fma_f32 v54, -v14, v116, v54
	v_fma_f32 v53, -v15, v113, v53
	v_fma_f32 v54, -v15, v117, v54
	ds_read_b128 v[110:113], v97 offset:25440
	ds_read_b128 v[114:117], v97 offset:25696
	s_waitcnt lgkmcnt(8)
	v_fma_f32 v53, -v16, v42, v53
	v_fma_f32 v54, -v16, v46, v54
	v_fma_f32 v53, -v17, v43, v53
	v_fma_f32 v54, -v17, v47, v54
	v_fma_f32 v53, -v18, v44, v53
	v_fma_f32 v54, -v18, v48, v54
	v_fma_f32 v53, -v19, v45, v53
	v_fma_f32 v54, -v19, v49, v54
	ds_read_b128 v[42:45], v97 offset:25456
	ds_read_b128 v[46:49], v97 offset:25712
	s_waitcnt lgkmcnt(8)
	v_fma_f32 v53, -v20, v84, v53
	v_fma_f32 v54, -v20, v88, v54
	v_fma_f32 v53, -v21, v85, v53
	v_fma_f32 v54, -v21, v89, v54
	v_fma_f32 v53, -v22, v86, v53
	v_fma_f32 v54, -v22, v90, v54
	v_fma_f32 v53, -v23, v87, v53
	v_fma_f32 v54, -v23, v91, v54
	ds_read_b128 v[84:87], v97 offset:25472
	ds_read_b128 v[88:91], v97 offset:25728
	s_waitcnt lgkmcnt(8)
	v_fma_f32 v53, -v24, v92, v53
	v_fma_f32 v54, -v24, v98, v54
	v_fma_f32 v53, -v25, v93, v53
	v_fma_f32 v54, -v25, v99, v54
	v_fma_f32 v53, -v26, v94, v53
	v_fma_f32 v54, -v26, v100, v54
	v_fma_f32 v53, -v27, v95, v53
	v_fma_f32 v54, -v27, v101, v54
	ds_read_b128 v[92:95], v97 offset:25856
	ds_read_b128 v[98:101], v97 offset:26112
	s_waitcnt lgkmcnt(8)
	v_fma_f32 v53, -v28, v102, v53
	v_fma_f32 v54, -v28, v106, v54
	v_fma_f32 v53, -v29, v103, v53
	v_fma_f32 v54, -v29, v107, v54
	v_fma_f32 v53, -v30, v104, v53
	v_fma_f32 v54, -v30, v108, v54
	v_fma_f32 v53, -v31, v105, v53
	v_fma_f32 v54, -v31, v109, v54
	ds_read_b128 v[102:105], v97 offset:25872
	ds_read_b128 v[106:109], v97 offset:26128
	s_waitcnt lgkmcnt(8)
	v_fma_f32 v53, -v32, v110, v53
	v_fma_f32 v54, -v32, v114, v54
	v_fma_f32 v53, -v33, v111, v53
	v_fma_f32 v54, -v33, v115, v54
	v_fma_f32 v53, -v34, v112, v53
	v_fma_f32 v54, -v34, v116, v54
	v_fma_f32 v53, -v35, v113, v53
	v_fma_f32 v54, -v35, v117, v54
	ds_read_b128 v[110:113], v97 offset:25888
	ds_read_b128 v[114:117], v97 offset:26144
	s_waitcnt lgkmcnt(8)
	v_fma_f32 v53, -v36, v42, v53
	v_fma_f32 v54, -v36, v46, v54
	v_fma_f32 v53, -v37, v43, v53
	v_fma_f32 v54, -v37, v47, v54
	v_fma_f32 v53, -v38, v44, v53
	v_fma_f32 v54, -v38, v48, v54
	v_fma_f32 v53, -v39, v45, v53
	v_fma_f32 v54, -v39, v49, v54
	ds_read_b128 v[42:45], v97 offset:25904
	ds_read_b128 v[46:49], v97 offset:26160
	s_waitcnt lgkmcnt(8)
	v_fma_f32 v53, -v52, v84, v53
	v_fma_f32 v54, -v52, v88, v54
	v_fma_f32 v54, -v53, v89, v54
	ds_read_b128 v[84:87], v97 offset:25920
	ds_read_b128 v[88:91], v97 offset:26176
	s_waitcnt lgkmcnt(8)
	v_fma_f32 v55, -v8, v92, v55
	v_fma_f32 v56, -v8, v98, v56
	v_fma_f32 v55, -v9, v93, v55
	v_fma_f32 v56, -v9, v99, v56
	v_fma_f32 v55, -v10, v94, v55
	v_fma_f32 v56, -v10, v100, v56
	v_fma_f32 v55, -v11, v95, v55
	v_fma_f32 v56, -v11, v101, v56
	ds_read_b128 v[92:95], v97 offset:25936
	ds_read_b128 v[98:101], v97 offset:26192
	s_waitcnt lgkmcnt(8)
	v_fma_f32 v55, -v12, v102, v55
	v_fma_f32 v56, -v12, v106, v56
	v_fma_f32 v55, -v13, v103, v55
	v_fma_f32 v56, -v13, v107, v56
	v_fma_f32 v55, -v14, v104, v55
	v_fma_f32 v56, -v14, v108, v56
	v_fma_f32 v55, -v15, v105, v55
	v_fma_f32 v56, -v15, v109, v56
	ds_read_b128 v[102:105], v97 offset:25952
	ds_read_b128 v[106:109], v97 offset:26208
	s_waitcnt lgkmcnt(8)
	v_fma_f32 v55, -v16, v110, v55
	v_fma_f32 v56, -v16, v114, v56
	v_fma_f32 v55, -v17, v111, v55
	v_fma_f32 v56, -v17, v115, v56
	v_fma_f32 v55, -v18, v112, v55
	v_fma_f32 v56, -v18, v116, v56
	v_fma_f32 v55, -v19, v113, v55
	v_fma_f32 v56, -v19, v117, v56
	ds_read_b128 v[110:113], v97 offset:25968
	ds_read_b128 v[114:117], v97 offset:26224
	s_waitcnt lgkmcnt(8)
	v_fma_f32 v55, -v20, v42, v55
	v_fma_f32 v56, -v20, v46, v56
	v_fma_f32 v55, -v21, v43, v55
	v_fma_f32 v56, -v21, v47, v56
	v_fma_f32 v55, -v22, v44, v55
	v_fma_f32 v56, -v22, v48, v56
	v_fma_f32 v55, -v23, v45, v55
	v_fma_f32 v56, -v23, v49, v56
	ds_read_b128 v[42:45], v97 offset:25984
	ds_read_b128 v[46:49], v97 offset:26240
	s_waitcnt lgkmcnt(8)
	v_fma_f32 v55, -v24, v84, v55
	v_fma_f32 v56, -v24, v88, v56
	v_fma_f32 v55, -v25, v85, v55
	v_fma_f32 v56, -v25, v89, v56
	v_fma_f32 v55, -v26, v86, v55
	v_fma_f32 v56, -v26, v90, v56
	v_fma_f32 v55, -v27, v87, v55
	v_fma_f32 v56, -v27, v91, v56
	ds_read_b128 v[84:87], v97 offset:26368
	ds_read_b128 v[88:91], v97 offset:26624
	s_waitcnt lgkmcnt(8)
	v_fma_f32 v55, -v28, v92, v55
	v_fma_f32 v56, -v28, v98, v56
	v_fma_f32 v55, -v29, v93, v55
	v_fma_f32 v56, -v29, v99, v56
	v_fma_f32 v55, -v30, v94, v55
	v_fma_f32 v56, -v30, v100, v56
	v_fma_f32 v55, -v31, v95, v55
	v_fma_f32 v56, -v31, v101, v56
	ds_read_b128 v[92:95], v97 offset:26384
	ds_read_b128 v[98:101], v97 offset:26640
	s_waitcnt lgkmcnt(8)
; NI void dn_chunk_local(const P& p, int dh, int n, char* lds) {
;     ...
;       for (int i = hb * 32; i < hb * 32 + 32; ++i) {
;         float a = x[i];
; #pragma unroll
;         for (int j = 0; j < i; ++j) a -= Ls[i * 64 + j] * x[j];
;         x[i] = a;
;         if ((i & 3) == 3) __builtin_amdgcn_sched_barrier(0);
;       }
	v_fma_f32 v55, -v32, v102, v55
	v_fma_f32 v56, -v32, v106, v56
	v_fma_f32 v55, -v33, v103, v55
	v_fma_f32 v56, -v33, v107, v56
	v_fma_f32 v55, -v34, v104, v55
	v_fma_f32 v56, -v34, v108, v56
	v_fma_f32 v55, -v35, v105, v55
	v_fma_f32 v56, -v35, v109, v56
	ds_read_b128 v[102:105], v97 offset:26400
	ds_read_b128 v[106:109], v97 offset:26656
	s_waitcnt lgkmcnt(8)
	v_fma_f32 v55, -v36, v110, v55
	v_fma_f32 v56, -v36, v114, v56
	v_fma_f32 v55, -v37, v111, v55
	v_fma_f32 v56, -v37, v115, v56
	v_fma_f32 v55, -v38, v112, v55
	v_fma_f32 v56, -v38, v116, v56
	v_fma_f32 v55, -v39, v113, v55
	v_fma_f32 v56, -v39, v117, v56
	ds_read_b128 v[110:113], v97 offset:26416
	ds_read_b128 v[114:117], v97 offset:26672
	s_waitcnt lgkmcnt(8)
	v_fma_f32 v55, -v52, v42, v55
	v_fma_f32 v56, -v52, v46, v56
	v_fma_f32 v55, -v53, v43, v55
	v_fma_f32 v56, -v53, v47, v56
	v_fma_f32 v55, -v54, v44, v55
	v_fma_f32 v56, -v54, v48, v56
	v_fma_f32 v56, -v55, v49, v56
	ds_read_b128 v[42:45], v97 offset:26432
	ds_read_b128 v[46:49], v97 offset:26688
	s_waitcnt lgkmcnt(8)
	v_fma_f32 v57, -v8, v84, v57
	v_fma_f32 v58, -v8, v88, v58
	v_fma_f32 v57, -v9, v85, v57
	v_fma_f32 v58, -v9, v89, v58
	v_fma_f32 v57, -v10, v86, v57
	v_fma_f32 v58, -v10, v90, v58
	v_fma_f32 v57, -v11, v87, v57
	v_fma_f32 v58, -v11, v91, v58
	ds_read_b128 v[84:87], v97 offset:26448
	ds_read_b128 v[88:91], v97 offset:26704
	s_waitcnt lgkmcnt(8)
	v_fma_f32 v57, -v12, v92, v57
	v_fma_f32 v58, -v12, v98, v58
	v_fma_f32 v57, -v13, v93, v57
	v_fma_f32 v58, -v13, v99, v58
	v_fma_f32 v57, -v14, v94, v57
	v_fma_f32 v58, -v14, v100, v58
	v_fma_f32 v57, -v15, v95, v57
	v_fma_f32 v58, -v15, v101, v58
	ds_read_b128 v[92:95], v97 offset:26464
	ds_read_b128 v[98:101], v97 offset:26720
	s_waitcnt lgkmcnt(8)
	v_fma_f32 v57, -v16, v102, v57
	v_fma_f32 v58, -v16, v106, v58
	v_fma_f32 v57, -v17, v103, v57
	v_fma_f32 v58, -v17, v107, v58
	v_fma_f32 v57, -v18, v104, v57
	v_fma_f32 v58, -v18, v108, v58
	v_fma_f32 v57, -v19, v105, v57
	v_fma_f32 v58, -v19, v109, v58
	ds_read_b128 v[102:105], v97 offset:26480
	ds_read_b128 v[106:109], v97 offset:26736
	s_waitcnt lgkmcnt(8)
	v_fma_f32 v57, -v20, v110, v57
	v_fma_f32 v58, -v20, v114, v58
	v_fma_f32 v57, -v21, v111, v57
	v_fma_f32 v58, -v21, v115, v58
	v_fma_f32 v57, -v22, v112, v57
	v_fma_f32 v58, -v22, v116, v58
	v_fma_f32 v57, -v23, v113, v57
	v_fma_f32 v58, -v23, v117, v58
	ds_read_b128 v[110:113], v97 offset:26496
	ds_read_b128 v[114:117], v97 offset:26752
	s_waitcnt lgkmcnt(8)
	v_fma_f32 v57, -v24, v42, v57
	v_fma_f32 v58, -v24, v46, v58
	v_fma_f32 v57, -v25, v43, v57
	v_fma_f32 v58, -v25, v47, v58
	v_fma_f32 v57, -v26, v44, v57
	v_fma_f32 v58, -v26, v48, v58
	v_fma_f32 v57, -v27, v45, v57
	v_fma_f32 v58, -v27, v49, v58
	ds_read_b128 v[42:45], v97 offset:26512
	ds_read_b128 v[46:49], v97 offset:26768
	s_waitcnt lgkmcnt(8)
	v_fma_f32 v57, -v28, v84, v57
	v_fma_f32 v58, -v28, v88, v58
	v_fma_f32 v57, -v29, v85, v57
	v_fma_f32 v58, -v29, v89, v58
	v_fma_f32 v57, -v30, v86, v57
	v_fma_f32 v58, -v30, v90, v58
	v_fma_f32 v57, -v31, v87, v57
	v_fma_f32 v58, -v31, v91, v58
	ds_read_b128 v[84:87], v97 offset:26880
	ds_read_b128 v[88:91], v97 offset:27136
	s_waitcnt lgkmcnt(8)
	v_fma_f32 v57, -v32, v92, v57
	v_fma_f32 v58, -v32, v98, v58
	v_fma_f32 v57, -v33, v93, v57
	v_fma_f32 v58, -v33, v99, v58
	v_fma_f32 v57, -v34, v94, v57
	v_fma_f32 v58, -v34, v100, v58
	v_fma_f32 v57, -v35, v95, v57
	v_fma_f32 v58, -v35, v101, v58
	ds_read_b128 v[92:95], v97 offset:26896
	ds_read_b128 v[98:101], v97 offset:27152
	s_waitcnt lgkmcnt(8)
	v_fma_f32 v57, -v36, v102, v57
	v_fma_f32 v58, -v36, v106, v58
	v_fma_f32 v57, -v37, v103, v57
	v_fma_f32 v58, -v37, v107, v58
	v_fma_f32 v57, -v38, v104, v57
	v_fma_f32 v58, -v38, v108, v58
	v_fma_f32 v57, -v39, v105, v57
	v_fma_f32 v58, -v39, v109, v58
	ds_read_b128 v[102:105], v97 offset:26912
	ds_read_b128 v[106:109], v97 offset:27168
	s_waitcnt lgkmcnt(8)
	v_fma_f32 v57, -v52, v110, v57
	v_fma_f32 v58, -v52, v114, v58
	v_fma_f32 v57, -v53, v111, v57
	v_fma_f32 v58, -v53, v115, v58
	v_fma_f32 v57, -v54, v112, v57
	v_fma_f32 v58, -v54, v116, v58
	v_fma_f32 v57, -v55, v113, v57
	v_fma_f32 v58, -v55, v117, v58
	ds_read_b128 v[110:113], v97 offset:26928
	ds_read_b128 v[114:117], v97 offset:27184
	s_waitcnt lgkmcnt(8)
	v_fma_f32 v57, -v56, v42, v57
	v_fma_f32 v58, -v56, v46, v58
	v_fma_f32 v58, -v57, v47, v58
	ds_read_b128 v[42:45], v97 offset:26944
	ds_read_b128 v[46:49], v97 offset:27200
	s_waitcnt lgkmcnt(8)
	v_fma_f32 v59, -v8, v84, v59
	v_fma_f32 v60, -v8, v88, v60
	v_fma_f32 v59, -v9, v85, v59
	v_fma_f32 v60, -v9, v89, v60
	v_fma_f32 v59, -v10, v86, v59
	v_fma_f32 v60, -v10, v90, v60
	v_fma_f32 v59, -v11, v87, v59
	v_fma_f32 v60, -v11, v91, v60
	ds_read_b128 v[84:87], v97 offset:26960
	ds_read_b128 v[88:91], v97 offset:27216
	s_waitcnt lgkmcnt(8)
	v_fma_f32 v59, -v12, v92, v59
	v_fma_f32 v60, -v12, v98, v60
	v_fma_f32 v59, -v13, v93, v59
	v_fma_f32 v60, -v13, v99, v60
	v_fma_f32 v59, -v14, v94, v59
	v_fma_f32 v60, -v14, v100, v60
	v_fma_f32 v59, -v15, v95, v59
	v_fma_f32 v60, -v15, v101, v60
	ds_read_b128 v[92:95], v97 offset:26976
	ds_read_b128 v[98:101], v97 offset:27232
	s_waitcnt lgkmcnt(8)
	v_fma_f32 v59, -v16, v102, v59
	v_fma_f32 v60, -v16, v106, v60
	v_fma_f32 v59, -v17, v103, v59
	v_fma_f32 v60, -v17, v107, v60
	v_fma_f32 v59, -v18, v104, v59
	v_fma_f32 v60, -v18, v108, v60
	v_fma_f32 v59, -v19, v105, v59
	v_fma_f32 v60, -v19, v109, v60
	ds_read_b128 v[102:105], v97 offset:26992
	ds_read_b128 v[106:109], v97 offset:27248
	s_waitcnt lgkmcnt(8)
; NI void dn_chunk_local(const P& p, int dh, int n, char* lds) {
;     ...
;       for (int i = hb * 32; i < hb * 32 + 32; ++i) {
;         float a = x[i];
; #pragma unroll
;         for (int j = 0; j < i; ++j) a -= Ls[i * 64 + j] * x[j];
;         x[i] = a;
;         if ((i & 3) == 3) __builtin_amdgcn_sched_barrier(0);
;       }
	v_fma_f32 v59, -v20, v110, v59
	v_fma_f32 v60, -v20, v114, v60
	v_fma_f32 v59, -v21, v111, v59
	v_fma_f32 v60, -v21, v115, v60
	v_fma_f32 v59, -v22, v112, v59
	v_fma_f32 v60, -v22, v116, v60
	v_fma_f32 v59, -v23, v113, v59
	v_fma_f32 v60, -v23, v117, v60
	ds_read_b128 v[110:113], v97 offset:27008
	ds_read_b128 v[114:117], v97 offset:27264
	s_waitcnt lgkmcnt(8)
	v_fma_f32 v59, -v24, v42, v59
	v_fma_f32 v60, -v24, v46, v60
	v_fma_f32 v59, -v25, v43, v59
	v_fma_f32 v60, -v25, v47, v60
	v_fma_f32 v59, -v26, v44, v59
	v_fma_f32 v60, -v26, v48, v60
	v_fma_f32 v59, -v27, v45, v59
	v_fma_f32 v60, -v27, v49, v60
	ds_read_b128 v[42:45], v97 offset:27024
	ds_read_b128 v[46:49], v97 offset:27280
	s_waitcnt lgkmcnt(8)
	v_fma_f32 v59, -v28, v84, v59
	v_fma_f32 v60, -v28, v88, v60
	v_fma_f32 v59, -v29, v85, v59
	v_fma_f32 v60, -v29, v89, v60
	v_fma_f32 v59, -v30, v86, v59
	v_fma_f32 v60, -v30, v90, v60
	v_fma_f32 v59, -v31, v87, v59
	v_fma_f32 v60, -v31, v91, v60
	ds_read_b128 v[84:87], v97 offset:27392
	ds_read_b128 v[88:91], v97 offset:27648
	s_waitcnt lgkmcnt(8)
	v_fma_f32 v59, -v32, v92, v59
	v_fma_f32 v60, -v32, v98, v60
	v_fma_f32 v59, -v33, v93, v59
	v_fma_f32 v60, -v33, v99, v60
	v_fma_f32 v59, -v34, v94, v59
	v_fma_f32 v60, -v34, v100, v60
	v_fma_f32 v59, -v35, v95, v59
	v_fma_f32 v60, -v35, v101, v60
	ds_read_b128 v[92:95], v97 offset:27408
	ds_read_b128 v[98:101], v97 offset:27664
	s_waitcnt lgkmcnt(8)
	v_fma_f32 v59, -v36, v102, v59
	v_fma_f32 v60, -v36, v106, v60
	v_fma_f32 v59, -v37, v103, v59
	v_fma_f32 v60, -v37, v107, v60
	v_fma_f32 v59, -v38, v104, v59
	v_fma_f32 v60, -v38, v108, v60
	v_fma_f32 v59, -v39, v105, v59
	v_fma_f32 v60, -v39, v109, v60
	ds_read_b128 v[102:105], v97 offset:27424
	ds_read_b128 v[106:109], v97 offset:27680
	s_waitcnt lgkmcnt(8)
	v_fma_f32 v59, -v52, v110, v59
	v_fma_f32 v60, -v52, v114, v60
	v_fma_f32 v59, -v53, v111, v59
	v_fma_f32 v60, -v53, v115, v60
	v_fma_f32 v59, -v54, v112, v59
	v_fma_f32 v60, -v54, v116, v60
	v_fma_f32 v59, -v55, v113, v59
	v_fma_f32 v60, -v55, v117, v60
	ds_read_b128 v[110:113], v97 offset:27440
	ds_read_b128 v[114:117], v97 offset:27696
	s_waitcnt lgkmcnt(8)
	v_fma_f32 v59, -v56, v42, v59
	v_fma_f32 v60, -v56, v46, v60
	v_fma_f32 v59, -v57, v43, v59
	v_fma_f32 v60, -v57, v47, v60
	v_fma_f32 v59, -v58, v44, v59
	v_fma_f32 v60, -v58, v48, v60
	v_fma_f32 v60, -v59, v49, v60
	ds_read_b128 v[42:45], v97 offset:27456
	ds_read_b128 v[46:49], v97 offset:27712
	s_waitcnt lgkmcnt(8)
	v_fma_f32 v61, -v8, v84, v61
	v_fma_f32 v62, -v8, v88, v62
	v_fma_f32 v61, -v9, v85, v61
	v_fma_f32 v62, -v9, v89, v62
	v_fma_f32 v61, -v10, v86, v61
	v_fma_f32 v62, -v10, v90, v62
	v_fma_f32 v61, -v11, v87, v61
	v_fma_f32 v62, -v11, v91, v62
	ds_read_b128 v[84:87], v97 offset:27472
	ds_read_b128 v[88:91], v97 offset:27728
	s_waitcnt lgkmcnt(8)
	v_fma_f32 v61, -v12, v92, v61
	v_fma_f32 v62, -v12, v98, v62
	v_fma_f32 v61, -v13, v93, v61
	v_fma_f32 v62, -v13, v99, v62
	v_fma_f32 v61, -v14, v94, v61
	v_fma_f32 v62, -v14, v100, v62
	v_fma_f32 v61, -v15, v95, v61
	v_fma_f32 v62, -v15, v101, v62
	ds_read_b128 v[92:95], v97 offset:27488
	ds_read_b128 v[98:101], v97 offset:27744
	s_waitcnt lgkmcnt(8)
	v_fma_f32 v61, -v16, v102, v61
	v_fma_f32 v62, -v16, v106, v62
	v_fma_f32 v61, -v17, v103, v61
	v_fma_f32 v62, -v17, v107, v62
	v_fma_f32 v61, -v18, v104, v61
	v_fma_f32 v62, -v18, v108, v62
	v_fma_f32 v61, -v19, v105, v61
	v_fma_f32 v62, -v19, v109, v62
	ds_read_b128 v[102:105], v97 offset:27504
	ds_read_b128 v[106:109], v97 offset:27760
	s_waitcnt lgkmcnt(8)
	v_fma_f32 v61, -v20, v110, v61
	v_fma_f32 v62, -v20, v114, v62
	v_fma_f32 v61, -v21, v111, v61
	v_fma_f32 v62, -v21, v115, v62
	v_fma_f32 v61, -v22, v112, v61
	v_fma_f32 v62, -v22, v116, v62
	v_fma_f32 v61, -v23, v113, v61
	v_fma_f32 v62, -v23, v117, v62
	ds_read_b128 v[110:113], v97 offset:27520
	ds_read_b128 v[114:117], v97 offset:27776
	s_waitcnt lgkmcnt(8)
	v_fma_f32 v61, -v24, v42, v61
	v_fma_f32 v62, -v24, v46, v62
	v_fma_f32 v61, -v25, v43, v61
	v_fma_f32 v62, -v25, v47, v62
	v_fma_f32 v61, -v26, v44, v61
	v_fma_f32 v62, -v26, v48, v62
	v_fma_f32 v61, -v27, v45, v61
	v_fma_f32 v62, -v27, v49, v62
	ds_read_b128 v[42:45], v97 offset:27536
	ds_read_b128 v[46:49], v97 offset:27792
	s_waitcnt lgkmcnt(8)
	v_fma_f32 v61, -v28, v84, v61
	v_fma_f32 v62, -v28, v88, v62
	v_fma_f32 v61, -v29, v85, v61
	v_fma_f32 v62, -v29, v89, v62
	v_fma_f32 v61, -v30, v86, v61
	v_fma_f32 v62, -v30, v90, v62
	v_fma_f32 v61, -v31, v87, v61
	v_fma_f32 v62, -v31, v91, v62
	ds_read_b128 v[84:87], v97 offset:27552
	ds_read_b128 v[88:91], v97 offset:27808
	s_waitcnt lgkmcnt(8)
	v_fma_f32 v61, -v32, v92, v61
	v_fma_f32 v62, -v32, v98, v62
	v_fma_f32 v61, -v33, v93, v61
	v_fma_f32 v62, -v33, v99, v62
	v_fma_f32 v61, -v34, v94, v61
	v_fma_f32 v62, -v34, v100, v62
	v_fma_f32 v61, -v35, v95, v61
	v_fma_f32 v62, -v35, v101, v62
	ds_read_b128 v[92:95], v97 offset:27904
	ds_read_b128 v[98:101], v97 offset:28160
	s_waitcnt lgkmcnt(8)
	v_fma_f32 v61, -v36, v102, v61
	v_fma_f32 v62, -v36, v106, v62
	v_fma_f32 v61, -v37, v103, v61
	v_fma_f32 v62, -v37, v107, v62
	v_fma_f32 v61, -v38, v104, v61
	v_fma_f32 v62, -v38, v108, v62
	v_fma_f32 v61, -v39, v105, v61
	v_fma_f32 v62, -v39, v109, v62
	ds_read_b128 v[102:105], v97 offset:27920
	ds_read_b128 v[106:109], v97 offset:28176
	s_waitcnt lgkmcnt(8)
	v_fma_f32 v61, -v52, v110, v61
	v_fma_f32 v62, -v52, v114, v62
	v_fma_f32 v61, -v53, v111, v61
	v_fma_f32 v62, -v53, v115, v62
	v_fma_f32 v61, -v54, v112, v61
	v_fma_f32 v62, -v54, v116, v62
	v_fma_f32 v61, -v55, v113, v61
	v_fma_f32 v62, -v55, v117, v62
	ds_read_b128 v[110:113], v97 offset:27936
	ds_read_b128 v[114:117], v97 offset:28192
	s_waitcnt lgkmcnt(8)
; NI void dn_chunk_local(const P& p, int dh, int n, char* lds) {
;     ...
;       for (int i = hb * 32; i < hb * 32 + 32; ++i) {
;         float a = x[i];
; #pragma unroll
;         for (int j = 0; j < i; ++j) a -= Ls[i * 64 + j] * x[j];
;         x[i] = a;
;         if ((i & 3) == 3) __builtin_amdgcn_sched_barrier(0);
;       }
	v_fma_f32 v61, -v56, v42, v61
	v_fma_f32 v62, -v56, v46, v62
	v_fma_f32 v61, -v57, v43, v61
	v_fma_f32 v62, -v57, v47, v62
	v_fma_f32 v61, -v58, v44, v61
	v_fma_f32 v62, -v58, v48, v62
	v_fma_f32 v61, -v59, v45, v61
	v_fma_f32 v62, -v59, v49, v62
	ds_read_b128 v[42:45], v97 offset:27952
	ds_read_b128 v[46:49], v97 offset:28208
	s_waitcnt lgkmcnt(8)
	v_fma_f32 v61, -v60, v84, v61
	v_fma_f32 v62, -v60, v88, v62
	v_fma_f32 v62, -v61, v89, v62
	ds_read_b128 v[84:87], v97 offset:27968
	ds_read_b128 v[88:91], v97 offset:28224
	s_waitcnt lgkmcnt(8)
	v_fma_f32 v63, -v8, v92, v63
	v_fma_f32 v64, -v8, v98, v64
	v_fma_f32 v63, -v9, v93, v63
	v_fma_f32 v64, -v9, v99, v64
	v_fma_f32 v63, -v10, v94, v63
	v_fma_f32 v64, -v10, v100, v64
	v_fma_f32 v63, -v11, v95, v63
	v_fma_f32 v64, -v11, v101, v64
	ds_read_b128 v[92:95], v97 offset:27984
	ds_read_b128 v[98:101], v97 offset:28240
	s_waitcnt lgkmcnt(8)
	v_fma_f32 v63, -v12, v102, v63
	v_fma_f32 v64, -v12, v106, v64
	v_fma_f32 v63, -v13, v103, v63
	v_fma_f32 v64, -v13, v107, v64
	v_fma_f32 v63, -v14, v104, v63
	v_fma_f32 v64, -v14, v108, v64
	v_fma_f32 v63, -v15, v105, v63
	v_fma_f32 v64, -v15, v109, v64
	ds_read_b128 v[102:105], v97 offset:28000
	ds_read_b128 v[106:109], v97 offset:28256
	s_waitcnt lgkmcnt(8)
	v_fma_f32 v63, -v16, v110, v63
	v_fma_f32 v64, -v16, v114, v64
	v_fma_f32 v63, -v17, v111, v63
	v_fma_f32 v64, -v17, v115, v64
	v_fma_f32 v63, -v18, v112, v63
	v_fma_f32 v64, -v18, v116, v64
	v_fma_f32 v63, -v19, v113, v63
	v_fma_f32 v64, -v19, v117, v64
	ds_read_b128 v[110:113], v97 offset:28016
	ds_read_b128 v[114:117], v97 offset:28272
	s_waitcnt lgkmcnt(8)
	v_fma_f32 v63, -v20, v42, v63
	v_fma_f32 v64, -v20, v46, v64
	v_fma_f32 v63, -v21, v43, v63
	v_fma_f32 v64, -v21, v47, v64
	v_fma_f32 v63, -v22, v44, v63
	v_fma_f32 v64, -v22, v48, v64
	v_fma_f32 v63, -v23, v45, v63
	v_fma_f32 v64, -v23, v49, v64
	ds_read_b128 v[42:45], v97 offset:28032
	ds_read_b128 v[46:49], v97 offset:28288
	s_waitcnt lgkmcnt(8)
	v_fma_f32 v63, -v24, v84, v63
	v_fma_f32 v64, -v24, v88, v64
	v_fma_f32 v63, -v25, v85, v63
	v_fma_f32 v64, -v25, v89, v64
	v_fma_f32 v63, -v26, v86, v63
	v_fma_f32 v64, -v26, v90, v64
	v_fma_f32 v63, -v27, v87, v63
	v_fma_f32 v64, -v27, v91, v64
	ds_read_b128 v[84:87], v97 offset:28048
	ds_read_b128 v[88:91], v97 offset:28304
	s_waitcnt lgkmcnt(8)
	v_fma_f32 v63, -v28, v92, v63
	v_fma_f32 v64, -v28, v98, v64
	v_fma_f32 v63, -v29, v93, v63
	v_fma_f32 v64, -v29, v99, v64
	v_fma_f32 v63, -v30, v94, v63
	v_fma_f32 v64, -v30, v100, v64
	v_fma_f32 v63, -v31, v95, v63
	v_fma_f32 v64, -v31, v101, v64
	ds_read_b128 v[92:95], v97 offset:28064
	ds_read_b128 v[98:101], v97 offset:28320
	s_waitcnt lgkmcnt(8)
	v_fma_f32 v63, -v32, v102, v63
	v_fma_f32 v64, -v32, v106, v64
	v_fma_f32 v63, -v33, v103, v63
	v_fma_f32 v64, -v33, v107, v64
	v_fma_f32 v63, -v34, v104, v63
	v_fma_f32 v64, -v34, v108, v64
	v_fma_f32 v63, -v35, v105, v63
	v_fma_f32 v64, -v35, v109, v64
	ds_read_b128 v[102:105], v97 offset:28416
	ds_read_b128 v[106:109], v97 offset:28672
	s_waitcnt lgkmcnt(8)
	v_fma_f32 v63, -v36, v110, v63
	v_fma_f32 v64, -v36, v114, v64
	v_fma_f32 v63, -v37, v111, v63
	v_fma_f32 v64, -v37, v115, v64
	v_fma_f32 v63, -v38, v112, v63
	v_fma_f32 v64, -v38, v116, v64
	v_fma_f32 v63, -v39, v113, v63
	v_fma_f32 v64, -v39, v117, v64
	ds_read_b128 v[110:113], v97 offset:28432
	ds_read_b128 v[114:117], v97 offset:28688
	s_waitcnt lgkmcnt(8)
	v_fma_f32 v63, -v52, v42, v63
	v_fma_f32 v64, -v52, v46, v64
	v_fma_f32 v63, -v53, v43, v63
	v_fma_f32 v64, -v53, v47, v64
	v_fma_f32 v63, -v54, v44, v63
	v_fma_f32 v64, -v54, v48, v64
	v_fma_f32 v63, -v55, v45, v63
	v_fma_f32 v64, -v55, v49, v64
	ds_read_b128 v[42:45], v97 offset:28448
	ds_read_b128 v[46:49], v97 offset:28704
	s_waitcnt lgkmcnt(8)
	v_fma_f32 v63, -v56, v84, v63
	v_fma_f32 v64, -v56, v88, v64
	v_fma_f32 v63, -v57, v85, v63
	v_fma_f32 v64, -v57, v89, v64
	v_fma_f32 v63, -v58, v86, v63
	v_fma_f32 v64, -v58, v90, v64
	v_fma_f32 v63, -v59, v87, v63
	v_fma_f32 v64, -v59, v91, v64
	ds_read_b128 v[84:87], v97 offset:28464
	ds_read_b128 v[88:91], v97 offset:28720
	s_waitcnt lgkmcnt(8)
	v_fma_f32 v63, -v60, v92, v63
	v_fma_f32 v64, -v60, v98, v64
	v_fma_f32 v63, -v61, v93, v63
	v_fma_f32 v64, -v61, v99, v64
	v_fma_f32 v63, -v62, v94, v63
	v_fma_f32 v64, -v62, v100, v64
	v_fma_f32 v64, -v63, v101, v64
	ds_read_b128 v[92:95], v97 offset:28480
	ds_read_b128 v[98:101], v97 offset:28736
	s_waitcnt lgkmcnt(8)
	v_fma_f32 v65, -v8, v102, v65
	v_fma_f32 v66, -v8, v106, v66
	v_fma_f32 v65, -v9, v103, v65
	v_fma_f32 v66, -v9, v107, v66
	v_fma_f32 v65, -v10, v104, v65
	v_fma_f32 v66, -v10, v108, v66
	v_fma_f32 v65, -v11, v105, v65
	v_fma_f32 v66, -v11, v109, v66
	ds_read_b128 v[102:105], v97 offset:28496
	ds_read_b128 v[106:109], v97 offset:28752
	s_waitcnt lgkmcnt(8)
	v_fma_f32 v65, -v12, v110, v65
	v_fma_f32 v66, -v12, v114, v66
	v_fma_f32 v65, -v13, v111, v65
	v_fma_f32 v66, -v13, v115, v66
	v_fma_f32 v65, -v14, v112, v65
	v_fma_f32 v66, -v14, v116, v66
	v_fma_f32 v65, -v15, v113, v65
	v_fma_f32 v66, -v15, v117, v66
	ds_read_b128 v[110:113], v97 offset:28512
	ds_read_b128 v[114:117], v97 offset:28768
	s_waitcnt lgkmcnt(8)
	v_fma_f32 v65, -v16, v42, v65
	v_fma_f32 v66, -v16, v46, v66
	v_fma_f32 v65, -v17, v43, v65
	v_fma_f32 v66, -v17, v47, v66
	v_fma_f32 v65, -v18, v44, v65
	v_fma_f32 v66, -v18, v48, v66
	v_fma_f32 v65, -v19, v45, v65
	v_fma_f32 v66, -v19, v49, v66
	ds_read_b128 v[42:45], v97 offset:28528
	ds_read_b128 v[46:49], v97 offset:28784
	s_waitcnt lgkmcnt(8)
; NI void dn_chunk_local(const P& p, int dh, int n, char* lds) {
;     ...
;       for (int i = hb * 32; i < hb * 32 + 32; ++i) {
;         float a = x[i];
; #pragma unroll
;         for (int j = 0; j < i; ++j) a -= Ls[i * 64 + j] * x[j];
;         x[i] = a;
;         if ((i & 3) == 3) __builtin_amdgcn_sched_barrier(0);
;       }
	v_fma_f32 v65, -v20, v84, v65
	v_fma_f32 v66, -v20, v88, v66
	v_fma_f32 v65, -v21, v85, v65
	v_fma_f32 v66, -v21, v89, v66
	v_fma_f32 v65, -v22, v86, v65
	v_fma_f32 v66, -v22, v90, v66
	v_fma_f32 v65, -v23, v87, v65
	v_fma_f32 v66, -v23, v91, v66
	ds_read_b128 v[84:87], v97 offset:28544
	ds_read_b128 v[88:91], v97 offset:28800
	s_waitcnt lgkmcnt(8)
	v_fma_f32 v65, -v24, v92, v65
	v_fma_f32 v66, -v24, v98, v66
	v_fma_f32 v65, -v25, v93, v65
	v_fma_f32 v66, -v25, v99, v66
	v_fma_f32 v65, -v26, v94, v65
	v_fma_f32 v66, -v26, v100, v66
	v_fma_f32 v65, -v27, v95, v65
	v_fma_f32 v66, -v27, v101, v66
	ds_read_b128 v[92:95], v97 offset:28560
	ds_read_b128 v[98:101], v97 offset:28816
	s_waitcnt lgkmcnt(8)
	v_fma_f32 v65, -v28, v102, v65
	v_fma_f32 v66, -v28, v106, v66
	v_fma_f32 v65, -v29, v103, v65
	v_fma_f32 v66, -v29, v107, v66
	v_fma_f32 v65, -v30, v104, v65
	v_fma_f32 v66, -v30, v108, v66
	v_fma_f32 v65, -v31, v105, v65
	v_fma_f32 v66, -v31, v109, v66
	ds_read_b128 v[102:105], v97 offset:28576
	ds_read_b128 v[106:109], v97 offset:28832
	s_waitcnt lgkmcnt(8)
	v_fma_f32 v65, -v32, v110, v65
	v_fma_f32 v66, -v32, v114, v66
	v_fma_f32 v65, -v33, v111, v65
	v_fma_f32 v66, -v33, v115, v66
	v_fma_f32 v65, -v34, v112, v65
	v_fma_f32 v66, -v34, v116, v66
	v_fma_f32 v65, -v35, v113, v65
	v_fma_f32 v66, -v35, v117, v66
	ds_read_b128 v[110:113], v97 offset:28592
	ds_read_b128 v[114:117], v97 offset:28848
	s_waitcnt lgkmcnt(8)
	v_fma_f32 v65, -v36, v42, v65
	v_fma_f32 v66, -v36, v46, v66
	v_fma_f32 v65, -v37, v43, v65
	v_fma_f32 v66, -v37, v47, v66
	v_fma_f32 v65, -v38, v44, v65
	v_fma_f32 v66, -v38, v48, v66
	v_fma_f32 v65, -v39, v45, v65
	v_fma_f32 v66, -v39, v49, v66
	ds_read_b128 v[42:45], v97 offset:28928
	ds_read_b128 v[46:49], v97 offset:29184
	s_waitcnt lgkmcnt(8)
	v_fma_f32 v65, -v52, v84, v65
	v_fma_f32 v66, -v52, v88, v66
	v_fma_f32 v65, -v53, v85, v65
	v_fma_f32 v66, -v53, v89, v66
	v_fma_f32 v65, -v54, v86, v65
	v_fma_f32 v66, -v54, v90, v66
	v_fma_f32 v65, -v55, v87, v65
	v_fma_f32 v66, -v55, v91, v66
	ds_read_b128 v[84:87], v97 offset:28944
	ds_read_b128 v[88:91], v97 offset:29200
	s_waitcnt lgkmcnt(8)
	v_fma_f32 v65, -v56, v92, v65
	v_fma_f32 v66, -v56, v98, v66
	v_fma_f32 v65, -v57, v93, v65
	v_fma_f32 v66, -v57, v99, v66
	v_fma_f32 v65, -v58, v94, v65
	v_fma_f32 v66, -v58, v100, v66
	v_fma_f32 v65, -v59, v95, v65
	v_fma_f32 v66, -v59, v101, v66
	ds_read_b128 v[92:95], v97 offset:28960
	ds_read_b128 v[98:101], v97 offset:29216
	s_waitcnt lgkmcnt(8)
	v_fma_f32 v65, -v60, v102, v65
	v_fma_f32 v66, -v60, v106, v66
	v_fma_f32 v65, -v61, v103, v65
	v_fma_f32 v66, -v61, v107, v66
	v_fma_f32 v65, -v62, v104, v65
	v_fma_f32 v66, -v62, v108, v66
	v_fma_f32 v65, -v63, v105, v65
	v_fma_f32 v66, -v63, v109, v66
	ds_read_b128 v[102:105], v97 offset:28976
	ds_read_b128 v[106:109], v97 offset:29232
	s_waitcnt lgkmcnt(8)
	v_fma_f32 v65, -v64, v110, v65
	v_fma_f32 v66, -v64, v114, v66
	v_fma_f32 v66, -v65, v115, v66
	ds_read_b128 v[110:113], v97 offset:28992
	ds_read_b128 v[114:117], v97 offset:29248
	s_waitcnt lgkmcnt(8)
	v_fma_f32 v67, -v8, v42, v67
	v_fma_f32 v68, -v8, v46, v68
	v_fma_f32 v67, -v9, v43, v67
	v_fma_f32 v68, -v9, v47, v68
	v_fma_f32 v67, -v10, v44, v67
	v_fma_f32 v68, -v10, v48, v68
	v_fma_f32 v67, -v11, v45, v67
	v_fma_f32 v68, -v11, v49, v68
	ds_read_b128 v[42:45], v97 offset:29008
	ds_read_b128 v[46:49], v97 offset:29264
	s_waitcnt lgkmcnt(8)
	v_fma_f32 v67, -v12, v84, v67
	v_fma_f32 v68, -v12, v88, v68
	v_fma_f32 v67, -v13, v85, v67
	v_fma_f32 v68, -v13, v89, v68
	v_fma_f32 v67, -v14, v86, v67
	v_fma_f32 v68, -v14, v90, v68
	v_fma_f32 v67, -v15, v87, v67
	v_fma_f32 v68, -v15, v91, v68
	ds_read_b128 v[84:87], v97 offset:29024
	ds_read_b128 v[88:91], v97 offset:29280
	s_waitcnt lgkmcnt(8)
	v_fma_f32 v67, -v16, v92, v67
	v_fma_f32 v68, -v16, v98, v68
	v_fma_f32 v67, -v17, v93, v67
	v_fma_f32 v68, -v17, v99, v68
	v_fma_f32 v67, -v18, v94, v67
	v_fma_f32 v68, -v18, v100, v68
	v_fma_f32 v67, -v19, v95, v67
	v_fma_f32 v68, -v19, v101, v68
	ds_read_b128 v[92:95], v97 offset:29040
	ds_read_b128 v[98:101], v97 offset:29296
	s_waitcnt lgkmcnt(8)
	v_fma_f32 v67, -v20, v102, v67
	v_fma_f32 v68, -v20, v106, v68
	v_fma_f32 v67, -v21, v103, v67
	v_fma_f32 v68, -v21, v107, v68
	v_fma_f32 v67, -v22, v104, v67
	v_fma_f32 v68, -v22, v108, v68
	v_fma_f32 v67, -v23, v105, v67
	v_fma_f32 v68, -v23, v109, v68
	ds_read_b128 v[102:105], v97 offset:29056
	ds_read_b128 v[106:109], v97 offset:29312
	s_waitcnt lgkmcnt(8)
	v_fma_f32 v67, -v24, v110, v67
	v_fma_f32 v68, -v24, v114, v68
	v_fma_f32 v67, -v25, v111, v67
	v_fma_f32 v68, -v25, v115, v68
	v_fma_f32 v67, -v26, v112, v67
	v_fma_f32 v68, -v26, v116, v68
	v_fma_f32 v67, -v27, v113, v67
	v_fma_f32 v68, -v27, v117, v68
	ds_read_b128 v[110:113], v97 offset:29072
	ds_read_b128 v[114:117], v97 offset:29328
	s_waitcnt lgkmcnt(8)
	v_fma_f32 v67, -v28, v42, v67
	v_fma_f32 v68, -v28, v46, v68
	v_fma_f32 v67, -v29, v43, v67
	v_fma_f32 v68, -v29, v47, v68
	v_fma_f32 v67, -v30, v44, v67
	v_fma_f32 v68, -v30, v48, v68
	v_fma_f32 v67, -v31, v45, v67
	v_fma_f32 v68, -v31, v49, v68
	ds_read_b128 v[42:45], v97 offset:29088
	ds_read_b128 v[46:49], v97 offset:29344
	s_waitcnt lgkmcnt(8)
	v_fma_f32 v67, -v32, v84, v67
	v_fma_f32 v68, -v32, v88, v68
	v_fma_f32 v67, -v33, v85, v67
	v_fma_f32 v68, -v33, v89, v68
	v_fma_f32 v67, -v34, v86, v67
	v_fma_f32 v68, -v34, v90, v68
	v_fma_f32 v67, -v35, v87, v67
	v_fma_f32 v68, -v35, v91, v68
	ds_read_b128 v[84:87], v97 offset:29104
	ds_read_b128 v[88:91], v97 offset:29360
	s_waitcnt lgkmcnt(8)
; NI void dn_chunk_local(const P& p, int dh, int n, char* lds) {
;     ...
;       for (int i = hb * 32; i < hb * 32 + 32; ++i) {
;         float a = x[i];
; #pragma unroll
;         for (int j = 0; j < i; ++j) a -= Ls[i * 64 + j] * x[j];
;         x[i] = a;
;         if ((i & 3) == 3) __builtin_amdgcn_sched_barrier(0);
;       }
	v_fma_f32 v67, -v36, v92, v67
	v_fma_f32 v68, -v36, v98, v68
	v_fma_f32 v67, -v37, v93, v67
	v_fma_f32 v68, -v37, v99, v68
	v_fma_f32 v67, -v38, v94, v67
	v_fma_f32 v68, -v38, v100, v68
	v_fma_f32 v67, -v39, v95, v67
	v_fma_f32 v68, -v39, v101, v68
	ds_read_b128 v[92:95], v97 offset:29440
	ds_read_b128 v[98:101], v97 offset:29696
	s_waitcnt lgkmcnt(8)
	v_fma_f32 v67, -v52, v102, v67
	v_fma_f32 v68, -v52, v106, v68
	v_fma_f32 v67, -v53, v103, v67
	v_fma_f32 v68, -v53, v107, v68
	v_fma_f32 v67, -v54, v104, v67
	v_fma_f32 v68, -v54, v108, v68
	v_fma_f32 v67, -v55, v105, v67
	v_fma_f32 v68, -v55, v109, v68
	ds_read_b128 v[102:105], v97 offset:29456
	ds_read_b128 v[106:109], v97 offset:29712
	s_waitcnt lgkmcnt(8)
	v_fma_f32 v67, -v56, v110, v67
	v_fma_f32 v68, -v56, v114, v68
	v_fma_f32 v67, -v57, v111, v67
	v_fma_f32 v68, -v57, v115, v68
	v_fma_f32 v67, -v58, v112, v67
	v_fma_f32 v68, -v58, v116, v68
	v_fma_f32 v67, -v59, v113, v67
	v_fma_f32 v68, -v59, v117, v68
	ds_read_b128 v[110:113], v97 offset:29472
	ds_read_b128 v[114:117], v97 offset:29728
	s_waitcnt lgkmcnt(8)
	v_fma_f32 v67, -v60, v42, v67
	v_fma_f32 v68, -v60, v46, v68
	v_fma_f32 v67, -v61, v43, v67
	v_fma_f32 v68, -v61, v47, v68
	v_fma_f32 v67, -v62, v44, v67
	v_fma_f32 v68, -v62, v48, v68
	v_fma_f32 v67, -v63, v45, v67
	v_fma_f32 v68, -v63, v49, v68
	ds_read_b128 v[42:45], v97 offset:29488
	ds_read_b128 v[46:49], v97 offset:29744
	s_waitcnt lgkmcnt(8)
	v_fma_f32 v67, -v64, v84, v67
	v_fma_f32 v68, -v64, v88, v68
	v_fma_f32 v67, -v65, v85, v67
	v_fma_f32 v68, -v65, v89, v68
	v_fma_f32 v67, -v66, v86, v67
	v_fma_f32 v68, -v66, v90, v68
	v_fma_f32 v68, -v67, v91, v68
	ds_read_b128 v[84:87], v97 offset:29504
	ds_read_b128 v[88:91], v97 offset:29760
	s_waitcnt lgkmcnt(8)
	v_fma_f32 v69, -v8, v92, v69
	v_fma_f32 v70, -v8, v98, v70
	v_fma_f32 v69, -v9, v93, v69
	v_fma_f32 v70, -v9, v99, v70
	v_fma_f32 v69, -v10, v94, v69
	v_fma_f32 v70, -v10, v100, v70
	v_fma_f32 v69, -v11, v95, v69
	v_fma_f32 v70, -v11, v101, v70
	ds_read_b128 v[92:95], v97 offset:29520
	ds_read_b128 v[98:101], v97 offset:29776
	s_waitcnt lgkmcnt(8)
	v_fma_f32 v69, -v12, v102, v69
	v_fma_f32 v70, -v12, v106, v70
	v_fma_f32 v69, -v13, v103, v69
	v_fma_f32 v70, -v13, v107, v70
	v_fma_f32 v69, -v14, v104, v69
	v_fma_f32 v70, -v14, v108, v70
	v_fma_f32 v69, -v15, v105, v69
	v_fma_f32 v70, -v15, v109, v70
	ds_read_b128 v[102:105], v97 offset:29536
	ds_read_b128 v[106:109], v97 offset:29792
	s_waitcnt lgkmcnt(8)
	v_fma_f32 v69, -v16, v110, v69
	v_fma_f32 v70, -v16, v114, v70
	v_fma_f32 v69, -v17, v111, v69
	v_fma_f32 v70, -v17, v115, v70
	v_fma_f32 v69, -v18, v112, v69
	v_fma_f32 v70, -v18, v116, v70
	v_fma_f32 v69, -v19, v113, v69
	v_fma_f32 v70, -v19, v117, v70
	ds_read_b128 v[110:113], v97 offset:29552
	ds_read_b128 v[114:117], v97 offset:29808
	s_waitcnt lgkmcnt(8)
	v_fma_f32 v69, -v20, v42, v69
	v_fma_f32 v70, -v20, v46, v70
	v_fma_f32 v69, -v21, v43, v69
	v_fma_f32 v70, -v21, v47, v70
	v_fma_f32 v69, -v22, v44, v69
	v_fma_f32 v70, -v22, v48, v70
	v_fma_f32 v69, -v23, v45, v69
	v_fma_f32 v70, -v23, v49, v70
	ds_read_b128 v[42:45], v97 offset:29568
	ds_read_b128 v[46:49], v97 offset:29824
	s_waitcnt lgkmcnt(8)
	v_fma_f32 v69, -v24, v84, v69
	v_fma_f32 v70, -v24, v88, v70
	v_fma_f32 v69, -v25, v85, v69
	v_fma_f32 v70, -v25, v89, v70
	v_fma_f32 v69, -v26, v86, v69
	v_fma_f32 v70, -v26, v90, v70
	v_fma_f32 v69, -v27, v87, v69
	v_fma_f32 v70, -v27, v91, v70
	ds_read_b128 v[84:87], v97 offset:29584
	ds_read_b128 v[88:91], v97 offset:29840
	s_waitcnt lgkmcnt(8)
	v_fma_f32 v69, -v28, v92, v69
	v_fma_f32 v70, -v28, v98, v70
	v_fma_f32 v69, -v29, v93, v69
	v_fma_f32 v70, -v29, v99, v70
	v_fma_f32 v69, -v30, v94, v69
	v_fma_f32 v70, -v30, v100, v70
	v_fma_f32 v69, -v31, v95, v69
	v_fma_f32 v70, -v31, v101, v70
	ds_read_b128 v[92:95], v97 offset:29600
	ds_read_b128 v[98:101], v97 offset:29856
	s_waitcnt lgkmcnt(8)
	v_fma_f32 v69, -v32, v102, v69
	v_fma_f32 v70, -v32, v106, v70
	v_fma_f32 v69, -v33, v103, v69
	v_fma_f32 v70, -v33, v107, v70
	v_fma_f32 v69, -v34, v104, v69
	v_fma_f32 v70, -v34, v108, v70
	v_fma_f32 v69, -v35, v105, v69
	v_fma_f32 v70, -v35, v109, v70
	ds_read_b128 v[102:105], v97 offset:29616
	ds_read_b128 v[106:109], v97 offset:29872
	s_waitcnt lgkmcnt(8)
	v_fma_f32 v69, -v36, v110, v69
	v_fma_f32 v70, -v36, v114, v70
	v_fma_f32 v69, -v37, v111, v69
	v_fma_f32 v70, -v37, v115, v70
	v_fma_f32 v69, -v38, v112, v69
	v_fma_f32 v70, -v38, v116, v70
	v_fma_f32 v69, -v39, v113, v69
	v_fma_f32 v70, -v39, v117, v70
	ds_read_b128 v[110:113], v97 offset:29632
	ds_read_b128 v[114:117], v97 offset:29888
	s_waitcnt lgkmcnt(8)
	v_fma_f32 v69, -v52, v42, v69
	v_fma_f32 v70, -v52, v46, v70
	v_fma_f32 v69, -v53, v43, v69
	v_fma_f32 v70, -v53, v47, v70
	v_fma_f32 v69, -v54, v44, v69
	v_fma_f32 v70, -v54, v48, v70
	v_fma_f32 v69, -v55, v45, v69
	v_fma_f32 v70, -v55, v49, v70
	ds_read_b128 v[42:45], v97 offset:29952
	ds_read_b128 v[46:49], v97 offset:30208
	s_waitcnt lgkmcnt(8)
	v_fma_f32 v69, -v56, v84, v69
	v_fma_f32 v70, -v56, v88, v70
	v_fma_f32 v69, -v57, v85, v69
	v_fma_f32 v70, -v57, v89, v70
	v_fma_f32 v69, -v58, v86, v69
	v_fma_f32 v70, -v58, v90, v70
	v_fma_f32 v69, -v59, v87, v69
	v_fma_f32 v70, -v59, v91, v70
	ds_read_b128 v[84:87], v97 offset:29968
	ds_read_b128 v[88:91], v97 offset:30224
	s_waitcnt lgkmcnt(8)
	v_fma_f32 v69, -v60, v92, v69
	v_fma_f32 v70, -v60, v98, v70
	v_fma_f32 v69, -v61, v93, v69
	v_fma_f32 v70, -v61, v99, v70
	v_fma_f32 v69, -v62, v94, v69
	v_fma_f32 v70, -v62, v100, v70
	v_fma_f32 v69, -v63, v95, v69
	v_fma_f32 v70, -v63, v101, v70
	ds_read_b128 v[92:95], v97 offset:29984
	ds_read_b128 v[98:101], v97 offset:30240
	s_waitcnt lgkmcnt(8)
; NI void dn_chunk_local(const P& p, int dh, int n, char* lds) {
;     ...
;       for (int i = hb * 32; i < hb * 32 + 32; ++i) {
;         float a = x[i];
; #pragma unroll
;         for (int j = 0; j < i; ++j) a -= Ls[i * 64 + j] * x[j];
;         x[i] = a;
;         if ((i & 3) == 3) __builtin_amdgcn_sched_barrier(0);
;       }
	v_fma_f32 v69, -v64, v102, v69
	v_fma_f32 v70, -v64, v106, v70
	v_fma_f32 v69, -v65, v103, v69
	v_fma_f32 v70, -v65, v107, v70
	v_fma_f32 v69, -v66, v104, v69
	v_fma_f32 v70, -v66, v108, v70
	v_fma_f32 v69, -v67, v105, v69
	v_fma_f32 v70, -v67, v109, v70
	ds_read_b128 v[102:105], v97 offset:30000
	ds_read_b128 v[106:109], v97 offset:30256
	s_waitcnt lgkmcnt(8)
	v_fma_f32 v69, -v68, v110, v69
	v_fma_f32 v70, -v68, v114, v70
	v_fma_f32 v70, -v69, v115, v70
	ds_read_b128 v[110:113], v97 offset:30016
	ds_read_b128 v[114:117], v97 offset:30272
	s_waitcnt lgkmcnt(8)
	v_fma_f32 v71, -v8, v42, v71
	v_fma_f32 v72, -v8, v46, v72
	v_fma_f32 v71, -v9, v43, v71
	v_fma_f32 v72, -v9, v47, v72
	v_fma_f32 v71, -v10, v44, v71
	v_fma_f32 v72, -v10, v48, v72
	v_fma_f32 v71, -v11, v45, v71
	v_fma_f32 v72, -v11, v49, v72
	ds_read_b128 v[42:45], v97 offset:30032
	ds_read_b128 v[46:49], v97 offset:30288
	s_waitcnt lgkmcnt(8)
	v_fma_f32 v71, -v12, v84, v71
	v_fma_f32 v72, -v12, v88, v72
	v_fma_f32 v71, -v13, v85, v71
	v_fma_f32 v72, -v13, v89, v72
	v_fma_f32 v71, -v14, v86, v71
	v_fma_f32 v72, -v14, v90, v72
	v_fma_f32 v71, -v15, v87, v71
	v_fma_f32 v72, -v15, v91, v72
	ds_read_b128 v[84:87], v97 offset:30048
	ds_read_b128 v[88:91], v97 offset:30304
	s_waitcnt lgkmcnt(8)
	v_fma_f32 v71, -v16, v92, v71
	v_fma_f32 v72, -v16, v98, v72
	v_fma_f32 v71, -v17, v93, v71
	v_fma_f32 v72, -v17, v99, v72
	v_fma_f32 v71, -v18, v94, v71
	v_fma_f32 v72, -v18, v100, v72
	v_fma_f32 v71, -v19, v95, v71
	v_fma_f32 v72, -v19, v101, v72
	ds_read_b128 v[92:95], v97 offset:30064
	ds_read_b128 v[98:101], v97 offset:30320
	s_waitcnt lgkmcnt(8)
	v_fma_f32 v71, -v20, v102, v71
	v_fma_f32 v72, -v20, v106, v72
	v_fma_f32 v71, -v21, v103, v71
	v_fma_f32 v72, -v21, v107, v72
	v_fma_f32 v71, -v22, v104, v71
	v_fma_f32 v72, -v22, v108, v72
	v_fma_f32 v71, -v23, v105, v71
	v_fma_f32 v72, -v23, v109, v72
	ds_read_b128 v[102:105], v97 offset:30080
	ds_read_b128 v[106:109], v97 offset:30336
	s_waitcnt lgkmcnt(8)
	v_fma_f32 v71, -v24, v110, v71
	v_fma_f32 v72, -v24, v114, v72
	v_fma_f32 v71, -v25, v111, v71
	v_fma_f32 v72, -v25, v115, v72
	v_fma_f32 v71, -v26, v112, v71
	v_fma_f32 v72, -v26, v116, v72
	v_fma_f32 v71, -v27, v113, v71
	v_fma_f32 v72, -v27, v117, v72
	ds_read_b128 v[110:113], v97 offset:30096
	ds_read_b128 v[114:117], v97 offset:30352
	s_waitcnt lgkmcnt(8)
	v_fma_f32 v71, -v28, v42, v71
	v_fma_f32 v72, -v28, v46, v72
	v_fma_f32 v71, -v29, v43, v71
	v_fma_f32 v72, -v29, v47, v72
	v_fma_f32 v71, -v30, v44, v71
	v_fma_f32 v72, -v30, v48, v72
	v_fma_f32 v71, -v31, v45, v71
	v_fma_f32 v72, -v31, v49, v72
	ds_read_b128 v[42:45], v97 offset:30112
	ds_read_b128 v[46:49], v97 offset:30368
	s_waitcnt lgkmcnt(8)
	v_fma_f32 v71, -v32, v84, v71
	v_fma_f32 v72, -v32, v88, v72
	v_fma_f32 v71, -v33, v85, v71
	v_fma_f32 v72, -v33, v89, v72
	v_fma_f32 v71, -v34, v86, v71
	v_fma_f32 v72, -v34, v90, v72
	v_fma_f32 v71, -v35, v87, v71
	v_fma_f32 v72, -v35, v91, v72
	ds_read_b128 v[84:87], v97 offset:30128
	ds_read_b128 v[88:91], v97 offset:30384
	s_waitcnt lgkmcnt(8)
	v_fma_f32 v71, -v36, v92, v71
	v_fma_f32 v72, -v36, v98, v72
	v_fma_f32 v71, -v37, v93, v71
	v_fma_f32 v72, -v37, v99, v72
	v_fma_f32 v71, -v38, v94, v71
	v_fma_f32 v72, -v38, v100, v72
	v_fma_f32 v71, -v39, v95, v71
	v_fma_f32 v72, -v39, v101, v72
	ds_read_b128 v[92:95], v97 offset:30144
	ds_read_b128 v[98:101], v97 offset:30400
	s_waitcnt lgkmcnt(8)
	v_fma_f32 v71, -v52, v102, v71
	v_fma_f32 v72, -v52, v106, v72
	v_fma_f32 v71, -v53, v103, v71
	v_fma_f32 v72, -v53, v107, v72
	v_fma_f32 v71, -v54, v104, v71
	v_fma_f32 v72, -v54, v108, v72
	v_fma_f32 v71, -v55, v105, v71
	v_fma_f32 v72, -v55, v109, v72
	ds_read_b128 v[102:105], v97 offset:30464
	ds_read_b128 v[106:109], v97 offset:30720
	s_waitcnt lgkmcnt(8)
	v_fma_f32 v71, -v56, v110, v71
	v_fma_f32 v72, -v56, v114, v72
	v_fma_f32 v71, -v57, v111, v71
	v_fma_f32 v72, -v57, v115, v72
	v_fma_f32 v71, -v58, v112, v71
	v_fma_f32 v72, -v58, v116, v72
	v_fma_f32 v71, -v59, v113, v71
	v_fma_f32 v72, -v59, v117, v72
	ds_read_b128 v[110:113], v97 offset:30480
	ds_read_b128 v[114:117], v97 offset:30736
	s_waitcnt lgkmcnt(8)
	v_fma_f32 v71, -v60, v42, v71
	v_fma_f32 v72, -v60, v46, v72
	v_fma_f32 v71, -v61, v43, v71
	v_fma_f32 v72, -v61, v47, v72
	v_fma_f32 v71, -v62, v44, v71
	v_fma_f32 v72, -v62, v48, v72
	v_fma_f32 v71, -v63, v45, v71
	v_fma_f32 v72, -v63, v49, v72
	ds_read_b128 v[42:45], v97 offset:30496
	ds_read_b128 v[46:49], v97 offset:30752
	s_waitcnt lgkmcnt(8)
	v_fma_f32 v71, -v64, v84, v71
	v_fma_f32 v72, -v64, v88, v72
	v_fma_f32 v71, -v65, v85, v71
	v_fma_f32 v72, -v65, v89, v72
	v_fma_f32 v71, -v66, v86, v71
	v_fma_f32 v72, -v66, v90, v72
	v_fma_f32 v71, -v67, v87, v71
	v_fma_f32 v72, -v67, v91, v72
	ds_read_b128 v[84:87], v97 offset:30512
	ds_read_b128 v[88:91], v97 offset:30768
	s_waitcnt lgkmcnt(8)
	v_fma_f32 v71, -v68, v92, v71
	v_fma_f32 v72, -v68, v98, v72
	v_fma_f32 v71, -v69, v93, v71
	v_fma_f32 v72, -v69, v99, v72
	v_fma_f32 v71, -v70, v94, v71
	v_fma_f32 v72, -v70, v100, v72
	v_fma_f32 v72, -v71, v101, v72
	ds_read_b128 v[92:95], v97 offset:30528
	ds_read_b128 v[98:101], v97 offset:30784
	s_waitcnt lgkmcnt(8)
	v_fma_f32 v73, -v8, v102, v73
	v_fma_f32 v74, -v8, v106, v74
	v_fma_f32 v73, -v9, v103, v73
	v_fma_f32 v74, -v9, v107, v74
	v_fma_f32 v73, -v10, v104, v73
	v_fma_f32 v74, -v10, v108, v74
	v_fma_f32 v73, -v11, v105, v73
	v_fma_f32 v74, -v11, v109, v74
	ds_read_b128 v[102:105], v97 offset:30544
	ds_read_b128 v[106:109], v97 offset:30800
	s_waitcnt lgkmcnt(8)
; NI void dn_chunk_local(const P& p, int dh, int n, char* lds) {
;     ...
;       for (int i = hb * 32; i < hb * 32 + 32; ++i) {
;         float a = x[i];
; #pragma unroll
;         for (int j = 0; j < i; ++j) a -= Ls[i * 64 + j] * x[j];
;         x[i] = a;
;         if ((i & 3) == 3) __builtin_amdgcn_sched_barrier(0);
;       }
	v_fma_f32 v73, -v12, v110, v73
	v_fma_f32 v74, -v12, v114, v74
	v_fma_f32 v73, -v13, v111, v73
	v_fma_f32 v74, -v13, v115, v74
	v_fma_f32 v73, -v14, v112, v73
	v_fma_f32 v74, -v14, v116, v74
	v_fma_f32 v73, -v15, v113, v73
	v_fma_f32 v74, -v15, v117, v74
	ds_read_b128 v[110:113], v97 offset:30560
	ds_read_b128 v[114:117], v97 offset:30816
	s_waitcnt lgkmcnt(8)
	v_fma_f32 v73, -v16, v42, v73
	v_fma_f32 v74, -v16, v46, v74
	v_fma_f32 v73, -v17, v43, v73
	v_fma_f32 v74, -v17, v47, v74
	v_fma_f32 v73, -v18, v44, v73
	v_fma_f32 v74, -v18, v48, v74
	v_fma_f32 v73, -v19, v45, v73
	v_fma_f32 v74, -v19, v49, v74
	ds_read_b128 v[42:45], v97 offset:30576
	ds_read_b128 v[46:49], v97 offset:30832
	s_waitcnt lgkmcnt(8)
	v_fma_f32 v73, -v20, v84, v73
	v_fma_f32 v74, -v20, v88, v74
	v_fma_f32 v73, -v21, v85, v73
	v_fma_f32 v74, -v21, v89, v74
	v_fma_f32 v73, -v22, v86, v73
	v_fma_f32 v74, -v22, v90, v74
	v_fma_f32 v73, -v23, v87, v73
	v_fma_f32 v74, -v23, v91, v74
	ds_read_b128 v[84:87], v97 offset:30592
	ds_read_b128 v[88:91], v97 offset:30848
	s_waitcnt lgkmcnt(8)
	v_fma_f32 v73, -v24, v92, v73
	v_fma_f32 v74, -v24, v98, v74
	v_fma_f32 v73, -v25, v93, v73
	v_fma_f32 v74, -v25, v99, v74
	v_fma_f32 v73, -v26, v94, v73
	v_fma_f32 v74, -v26, v100, v74
	v_fma_f32 v73, -v27, v95, v73
	v_fma_f32 v74, -v27, v101, v74
	ds_read_b128 v[92:95], v97 offset:30608
	ds_read_b128 v[98:101], v97 offset:30864
	s_waitcnt lgkmcnt(8)
	v_fma_f32 v73, -v28, v102, v73
	v_fma_f32 v74, -v28, v106, v74
	v_fma_f32 v73, -v29, v103, v73
	v_fma_f32 v74, -v29, v107, v74
	v_fma_f32 v73, -v30, v104, v73
	v_fma_f32 v74, -v30, v108, v74
	v_fma_f32 v73, -v31, v105, v73
	v_fma_f32 v74, -v31, v109, v74
	ds_read_b128 v[102:105], v97 offset:30624
	ds_read_b128 v[106:109], v97 offset:30880
	s_waitcnt lgkmcnt(8)
	v_fma_f32 v73, -v32, v110, v73
	v_fma_f32 v74, -v32, v114, v74
	v_fma_f32 v73, -v33, v111, v73
	v_fma_f32 v74, -v33, v115, v74
	v_fma_f32 v73, -v34, v112, v73
	v_fma_f32 v74, -v34, v116, v74
	v_fma_f32 v73, -v35, v113, v73
	v_fma_f32 v74, -v35, v117, v74
	ds_read_b128 v[110:113], v97 offset:30640
	ds_read_b128 v[114:117], v97 offset:30896
	s_waitcnt lgkmcnt(8)
	v_fma_f32 v73, -v36, v42, v73
	v_fma_f32 v74, -v36, v46, v74
	v_fma_f32 v73, -v37, v43, v73
	v_fma_f32 v74, -v37, v47, v74
	v_fma_f32 v73, -v38, v44, v73
	v_fma_f32 v74, -v38, v48, v74
	v_fma_f32 v73, -v39, v45, v73
	v_fma_f32 v74, -v39, v49, v74
	ds_read_b128 v[42:45], v97 offset:30656
	ds_read_b128 v[46:49], v97 offset:30912
	s_waitcnt lgkmcnt(8)
	v_fma_f32 v73, -v52, v84, v73
	v_fma_f32 v74, -v52, v88, v74
	v_fma_f32 v73, -v53, v85, v73
	v_fma_f32 v74, -v53, v89, v74
	v_fma_f32 v73, -v54, v86, v73
	v_fma_f32 v74, -v54, v90, v74
	v_fma_f32 v73, -v55, v87, v73
	v_fma_f32 v74, -v55, v91, v74
	ds_read_b128 v[84:87], v97 offset:30672
	ds_read_b128 v[88:91], v97 offset:30928
	s_waitcnt lgkmcnt(8)
	v_fma_f32 v73, -v56, v92, v73
	v_fma_f32 v74, -v56, v98, v74
	v_fma_f32 v73, -v57, v93, v73
	v_fma_f32 v74, -v57, v99, v74
	v_fma_f32 v73, -v58, v94, v73
	v_fma_f32 v74, -v58, v100, v74
	v_fma_f32 v73, -v59, v95, v73
	v_fma_f32 v74, -v59, v101, v74
	ds_read_b128 v[92:95], v97 offset:30976
	ds_read_b128 v[98:101], v97 offset:31232
	s_waitcnt lgkmcnt(8)
	v_fma_f32 v73, -v60, v102, v73
	v_fma_f32 v74, -v60, v106, v74
	v_fma_f32 v73, -v61, v103, v73
	v_fma_f32 v74, -v61, v107, v74
	v_fma_f32 v73, -v62, v104, v73
	v_fma_f32 v74, -v62, v108, v74
	v_fma_f32 v73, -v63, v105, v73
	v_fma_f32 v74, -v63, v109, v74
	ds_read_b128 v[102:105], v97 offset:30992
	ds_read_b128 v[106:109], v97 offset:31248
	s_waitcnt lgkmcnt(8)
	v_fma_f32 v73, -v64, v110, v73
	v_fma_f32 v74, -v64, v114, v74
	v_fma_f32 v73, -v65, v111, v73
	v_fma_f32 v74, -v65, v115, v74
	v_fma_f32 v73, -v66, v112, v73
	v_fma_f32 v74, -v66, v116, v74
	v_fma_f32 v73, -v67, v113, v73
	v_fma_f32 v74, -v67, v117, v74
	ds_read_b128 v[110:113], v97 offset:31008
	ds_read_b128 v[114:117], v97 offset:31264
	s_waitcnt lgkmcnt(8)
	v_fma_f32 v73, -v68, v42, v73
	v_fma_f32 v74, -v68, v46, v74
	v_fma_f32 v73, -v69, v43, v73
	v_fma_f32 v74, -v69, v47, v74
	v_fma_f32 v73, -v70, v44, v73
	v_fma_f32 v74, -v70, v48, v74
	v_fma_f32 v73, -v71, v45, v73
	v_fma_f32 v74, -v71, v49, v74
	ds_read_b128 v[42:45], v97 offset:31024
	ds_read_b128 v[46:49], v97 offset:31280
	s_waitcnt lgkmcnt(8)
	v_fma_f32 v73, -v72, v84, v73
	v_fma_f32 v74, -v72, v88, v74
	v_fma_f32 v74, -v73, v89, v74
	ds_read_b128 v[84:87], v97 offset:31040
	ds_read_b128 v[88:91], v97 offset:31296
	s_waitcnt lgkmcnt(8)
	v_fma_f32 v75, -v8, v92, v75
	v_fma_f32 v76, -v8, v98, v76
	v_fma_f32 v75, -v9, v93, v75
	v_fma_f32 v76, -v9, v99, v76
	v_fma_f32 v75, -v10, v94, v75
	v_fma_f32 v76, -v10, v100, v76
	v_fma_f32 v75, -v11, v95, v75
	v_fma_f32 v76, -v11, v101, v76
	ds_read_b128 v[92:95], v97 offset:31056
	ds_read_b128 v[98:101], v97 offset:31312
	s_waitcnt lgkmcnt(8)
	v_fma_f32 v75, -v12, v102, v75
	v_fma_f32 v76, -v12, v106, v76
	v_fma_f32 v75, -v13, v103, v75
	v_fma_f32 v76, -v13, v107, v76
	v_fma_f32 v75, -v14, v104, v75
	v_fma_f32 v76, -v14, v108, v76
	v_fma_f32 v75, -v15, v105, v75
	v_fma_f32 v76, -v15, v109, v76
	ds_read_b128 v[102:105], v97 offset:31072
	ds_read_b128 v[106:109], v97 offset:31328
	s_waitcnt lgkmcnt(8)
	v_fma_f32 v75, -v16, v110, v75
	v_fma_f32 v76, -v16, v114, v76
	v_fma_f32 v75, -v17, v111, v75
	v_fma_f32 v76, -v17, v115, v76
	v_fma_f32 v75, -v18, v112, v75
	v_fma_f32 v76, -v18, v116, v76
	v_fma_f32 v75, -v19, v113, v75
	v_fma_f32 v76, -v19, v117, v76
	ds_read_b128 v[110:113], v97 offset:31088
	ds_read_b128 v[114:117], v97 offset:31344
	s_waitcnt lgkmcnt(8)
; NI void dn_chunk_local(const P& p, int dh, int n, char* lds) {
;     ...
;       for (int i = hb * 32; i < hb * 32 + 32; ++i) {
;         float a = x[i];
; #pragma unroll
;         for (int j = 0; j < i; ++j) a -= Ls[i * 64 + j] * x[j];
;         x[i] = a;
;         if ((i & 3) == 3) __builtin_amdgcn_sched_barrier(0);
;       }
	v_fma_f32 v75, -v20, v42, v75
	v_fma_f32 v76, -v20, v46, v76
	v_fma_f32 v75, -v21, v43, v75
	v_fma_f32 v76, -v21, v47, v76
	v_fma_f32 v75, -v22, v44, v75
	v_fma_f32 v76, -v22, v48, v76
	v_fma_f32 v75, -v23, v45, v75
	v_fma_f32 v76, -v23, v49, v76
	ds_read_b128 v[42:45], v97 offset:31104
	ds_read_b128 v[46:49], v97 offset:31360
	s_waitcnt lgkmcnt(8)
	v_fma_f32 v75, -v24, v84, v75
	v_fma_f32 v76, -v24, v88, v76
	v_fma_f32 v75, -v25, v85, v75
	v_fma_f32 v76, -v25, v89, v76
	v_fma_f32 v75, -v26, v86, v75
	v_fma_f32 v76, -v26, v90, v76
	v_fma_f32 v75, -v27, v87, v75
	v_fma_f32 v76, -v27, v91, v76
	ds_read_b128 v[84:87], v97 offset:31120
	ds_read_b128 v[88:91], v97 offset:31376
	s_waitcnt lgkmcnt(8)
	v_fma_f32 v75, -v28, v92, v75
	v_fma_f32 v76, -v28, v98, v76
	v_fma_f32 v75, -v29, v93, v75
	v_fma_f32 v76, -v29, v99, v76
	v_fma_f32 v75, -v30, v94, v75
	v_fma_f32 v76, -v30, v100, v76
	v_fma_f32 v75, -v31, v95, v75
	v_fma_f32 v76, -v31, v101, v76
	ds_read_b128 v[92:95], v97 offset:31136
	ds_read_b128 v[98:101], v97 offset:31392
	s_waitcnt lgkmcnt(8)
	v_fma_f32 v75, -v32, v102, v75
	v_fma_f32 v76, -v32, v106, v76
	v_fma_f32 v75, -v33, v103, v75
	v_fma_f32 v76, -v33, v107, v76
	v_fma_f32 v75, -v34, v104, v75
	v_fma_f32 v76, -v34, v108, v76
	v_fma_f32 v75, -v35, v105, v75
	v_fma_f32 v76, -v35, v109, v76
	ds_read_b128 v[102:105], v97 offset:31152
	ds_read_b128 v[106:109], v97 offset:31408
	s_waitcnt lgkmcnt(8)
	v_fma_f32 v75, -v36, v110, v75
	v_fma_f32 v76, -v36, v114, v76
	v_fma_f32 v75, -v37, v111, v75
	v_fma_f32 v76, -v37, v115, v76
	v_fma_f32 v75, -v38, v112, v75
	v_fma_f32 v76, -v38, v116, v76
	v_fma_f32 v75, -v39, v113, v75
	v_fma_f32 v76, -v39, v117, v76
	ds_read_b128 v[110:113], v97 offset:31168
	ds_read_b128 v[114:117], v97 offset:31424
	s_waitcnt lgkmcnt(8)
	v_fma_f32 v75, -v52, v42, v75
	v_fma_f32 v76, -v52, v46, v76
	v_fma_f32 v75, -v53, v43, v75
	v_fma_f32 v76, -v53, v47, v76
	v_fma_f32 v75, -v54, v44, v75
	v_fma_f32 v76, -v54, v48, v76
	v_fma_f32 v75, -v55, v45, v75
	v_fma_f32 v76, -v55, v49, v76
	ds_read_b128 v[42:45], v97 offset:31184
	ds_read_b128 v[46:49], v97 offset:31440
	s_waitcnt lgkmcnt(8)
	v_fma_f32 v75, -v56, v84, v75
	v_fma_f32 v76, -v56, v88, v76
	v_fma_f32 v75, -v57, v85, v75
	v_fma_f32 v76, -v57, v89, v76
	v_fma_f32 v75, -v58, v86, v75
	v_fma_f32 v76, -v58, v90, v76
	v_fma_f32 v75, -v59, v87, v75
	v_fma_f32 v76, -v59, v91, v76
	ds_read_b128 v[84:87], v97 offset:31488
	ds_read_b128 v[88:91], v97 offset:31744
	s_waitcnt lgkmcnt(8)
	v_fma_f32 v75, -v60, v92, v75
	v_fma_f32 v76, -v60, v98, v76
	v_fma_f32 v75, -v61, v93, v75
	v_fma_f32 v76, -v61, v99, v76
	v_fma_f32 v75, -v62, v94, v75
	v_fma_f32 v76, -v62, v100, v76
	v_fma_f32 v75, -v63, v95, v75
	v_fma_f32 v76, -v63, v101, v76
	ds_read_b128 v[92:95], v97 offset:31504
	ds_read_b128 v[98:101], v97 offset:31760
	s_waitcnt lgkmcnt(8)
	v_fma_f32 v75, -v64, v102, v75
	v_fma_f32 v76, -v64, v106, v76
	v_fma_f32 v75, -v65, v103, v75
	v_fma_f32 v76, -v65, v107, v76
	v_fma_f32 v75, -v66, v104, v75
	v_fma_f32 v76, -v66, v108, v76
	v_fma_f32 v75, -v67, v105, v75
	v_fma_f32 v76, -v67, v109, v76
	ds_read_b128 v[102:105], v97 offset:31520
	ds_read_b128 v[106:109], v97 offset:31776
	s_waitcnt lgkmcnt(8)
	v_fma_f32 v75, -v68, v110, v75
	v_fma_f32 v76, -v68, v114, v76
	v_fma_f32 v75, -v69, v111, v75
	v_fma_f32 v76, -v69, v115, v76
	v_fma_f32 v75, -v70, v112, v75
	v_fma_f32 v76, -v70, v116, v76
	v_fma_f32 v75, -v71, v113, v75
	v_fma_f32 v76, -v71, v117, v76
	ds_read_b128 v[110:113], v97 offset:31536
	ds_read_b128 v[114:117], v97 offset:31792
	s_waitcnt lgkmcnt(8)
	v_fma_f32 v75, -v72, v42, v75
	v_fma_f32 v76, -v72, v46, v76
	v_fma_f32 v75, -v73, v43, v75
	v_fma_f32 v76, -v73, v47, v76
	v_fma_f32 v75, -v74, v44, v75
	v_fma_f32 v76, -v74, v48, v76
	v_fma_f32 v76, -v75, v49, v76
	ds_read_b128 v[42:45], v97 offset:31552
	ds_read_b128 v[46:49], v97 offset:31808
	s_waitcnt lgkmcnt(8)
	v_fma_f32 v77, -v8, v84, v77
	v_fma_f32 v78, -v8, v88, v78
	v_fma_f32 v77, -v9, v85, v77
	v_fma_f32 v78, -v9, v89, v78
	v_fma_f32 v77, -v10, v86, v77
	v_fma_f32 v78, -v10, v90, v78
	v_fma_f32 v77, -v11, v87, v77
	v_fma_f32 v78, -v11, v91, v78
	ds_read_b128 v[84:87], v97 offset:31568
	ds_read_b128 v[88:91], v97 offset:31824
	s_waitcnt lgkmcnt(8)
	v_fma_f32 v77, -v12, v92, v77
	v_fma_f32 v78, -v12, v98, v78
	v_fma_f32 v77, -v13, v93, v77
	v_fma_f32 v78, -v13, v99, v78
	v_fma_f32 v77, -v14, v94, v77
	v_fma_f32 v78, -v14, v100, v78
	v_fma_f32 v77, -v15, v95, v77
	v_fma_f32 v78, -v15, v101, v78
	ds_read_b128 v[92:95], v97 offset:31584
	ds_read_b128 v[98:101], v97 offset:31840
	s_waitcnt lgkmcnt(8)
	v_fma_f32 v77, -v16, v102, v77
	v_fma_f32 v78, -v16, v106, v78
	v_fma_f32 v77, -v17, v103, v77
	v_fma_f32 v78, -v17, v107, v78
	v_fma_f32 v77, -v18, v104, v77
	v_fma_f32 v78, -v18, v108, v78
	v_fma_f32 v77, -v19, v105, v77
	v_fma_f32 v78, -v19, v109, v78
	ds_read_b128 v[102:105], v97 offset:31600
	ds_read_b128 v[106:109], v97 offset:31856
	s_waitcnt lgkmcnt(8)
	v_fma_f32 v77, -v20, v110, v77
	v_fma_f32 v78, -v20, v114, v78
	v_fma_f32 v77, -v21, v111, v77
	v_fma_f32 v78, -v21, v115, v78
	v_fma_f32 v77, -v22, v112, v77
	v_fma_f32 v78, -v22, v116, v78
	v_fma_f32 v77, -v23, v113, v77
	v_fma_f32 v78, -v23, v117, v78
	ds_read_b128 v[110:113], v97 offset:31616
	ds_read_b128 v[114:117], v97 offset:31872
	s_waitcnt lgkmcnt(8)
	v_fma_f32 v77, -v24, v42, v77
	v_fma_f32 v78, -v24, v46, v78
	v_fma_f32 v77, -v25, v43, v77
	v_fma_f32 v78, -v25, v47, v78
	v_fma_f32 v77, -v26, v44, v77
	v_fma_f32 v78, -v26, v48, v78
	v_fma_f32 v77, -v27, v45, v77
	v_fma_f32 v78, -v27, v49, v78
	ds_read_b128 v[42:45], v97 offset:31632
	ds_read_b128 v[46:49], v97 offset:31888
	s_waitcnt lgkmcnt(8)
; NI void dn_chunk_local(const P& p, int dh, int n, char* lds) {
;     ...
;       for (int i = hb * 32; i < hb * 32 + 32; ++i) {
;         float a = x[i];
; #pragma unroll
;         for (int j = 0; j < i; ++j) a -= Ls[i * 64 + j] * x[j];
;         x[i] = a;
;         if ((i & 3) == 3) __builtin_amdgcn_sched_barrier(0);
;       }
	v_fma_f32 v77, -v28, v84, v77
	v_fma_f32 v78, -v28, v88, v78
	v_fma_f32 v77, -v29, v85, v77
	v_fma_f32 v78, -v29, v89, v78
	v_fma_f32 v77, -v30, v86, v77
	v_fma_f32 v78, -v30, v90, v78
	v_fma_f32 v77, -v31, v87, v77
	v_fma_f32 v78, -v31, v91, v78
	ds_read_b128 v[84:87], v97 offset:31648
	ds_read_b128 v[88:91], v97 offset:31904
	s_waitcnt lgkmcnt(8)
	v_fma_f32 v77, -v32, v92, v77
	v_fma_f32 v78, -v32, v98, v78
	v_fma_f32 v77, -v33, v93, v77
	v_fma_f32 v78, -v33, v99, v78
	v_fma_f32 v77, -v34, v94, v77
	v_fma_f32 v78, -v34, v100, v78
	v_fma_f32 v77, -v35, v95, v77
	v_fma_f32 v78, -v35, v101, v78
	ds_read_b128 v[92:95], v97 offset:31664
	ds_read_b128 v[98:101], v97 offset:31920
	s_waitcnt lgkmcnt(8)
	v_fma_f32 v77, -v36, v102, v77
	v_fma_f32 v78, -v36, v106, v78
	v_fma_f32 v77, -v37, v103, v77
	v_fma_f32 v78, -v37, v107, v78
	v_fma_f32 v77, -v38, v104, v77
	v_fma_f32 v78, -v38, v108, v78
	v_fma_f32 v77, -v39, v105, v77
	v_fma_f32 v78, -v39, v109, v78
	ds_read_b128 v[102:105], v97 offset:31680
	ds_read_b128 v[106:109], v97 offset:31936
	s_waitcnt lgkmcnt(8)
	v_fma_f32 v77, -v52, v110, v77
	v_fma_f32 v78, -v52, v114, v78
	v_fma_f32 v77, -v53, v111, v77
	v_fma_f32 v78, -v53, v115, v78
	v_fma_f32 v77, -v54, v112, v77
	v_fma_f32 v78, -v54, v116, v78
	v_fma_f32 v77, -v55, v113, v77
	v_fma_f32 v78, -v55, v117, v78
	ds_read_b128 v[110:113], v97 offset:31696
	ds_read_b128 v[114:117], v97 offset:31952
	s_waitcnt lgkmcnt(8)
	v_fma_f32 v77, -v56, v42, v77
	v_fma_f32 v78, -v56, v46, v78
	v_fma_f32 v77, -v57, v43, v77
	v_fma_f32 v78, -v57, v47, v78
	v_fma_f32 v77, -v58, v44, v77
	v_fma_f32 v78, -v58, v48, v78
	v_fma_f32 v77, -v59, v45, v77
	v_fma_f32 v78, -v59, v49, v78
	ds_read_b128 v[42:45], v97 offset:31712
	ds_read_b128 v[46:49], v97 offset:31968
	s_waitcnt lgkmcnt(8)
	v_fma_f32 v77, -v60, v84, v77
	v_fma_f32 v78, -v60, v88, v78
	v_fma_f32 v77, -v61, v85, v77
	v_fma_f32 v78, -v61, v89, v78
	v_fma_f32 v77, -v62, v86, v77
	v_fma_f32 v78, -v62, v90, v78
	v_fma_f32 v77, -v63, v87, v77
	v_fma_f32 v78, -v63, v91, v78
	ds_read_b128 v[84:87], v97 offset:32000
	ds_read_b128 v[88:91], v97 offset:32256
	s_waitcnt lgkmcnt(8)
	v_fma_f32 v77, -v64, v92, v77
	v_fma_f32 v78, -v64, v98, v78
	v_fma_f32 v77, -v65, v93, v77
	v_fma_f32 v78, -v65, v99, v78
	v_fma_f32 v77, -v66, v94, v77
	v_fma_f32 v78, -v66, v100, v78
	v_fma_f32 v77, -v67, v95, v77
	v_fma_f32 v78, -v67, v101, v78
	ds_read_b128 v[92:95], v97 offset:32016
	ds_read_b128 v[98:101], v97 offset:32272
	s_waitcnt lgkmcnt(8)
	v_fma_f32 v77, -v68, v102, v77
	v_fma_f32 v78, -v68, v106, v78
	v_fma_f32 v77, -v69, v103, v77
	v_fma_f32 v78, -v69, v107, v78
	v_fma_f32 v77, -v70, v104, v77
	v_fma_f32 v78, -v70, v108, v78
	v_fma_f32 v77, -v71, v105, v77
	v_fma_f32 v78, -v71, v109, v78
	ds_read_b128 v[102:105], v97 offset:32032
	ds_read_b128 v[106:109], v97 offset:32288
	s_waitcnt lgkmcnt(8)
	v_fma_f32 v77, -v72, v110, v77
	v_fma_f32 v78, -v72, v114, v78
	v_fma_f32 v77, -v73, v111, v77
	v_fma_f32 v78, -v73, v115, v78
	v_fma_f32 v77, -v74, v112, v77
	v_fma_f32 v78, -v74, v116, v78
	v_fma_f32 v77, -v75, v113, v77
	v_fma_f32 v78, -v75, v117, v78
	ds_read_b128 v[110:113], v97 offset:32048
	ds_read_b128 v[114:117], v97 offset:32304
	s_waitcnt lgkmcnt(8)
	v_fma_f32 v77, -v76, v42, v77
	v_fma_f32 v78, -v76, v46, v78
	v_fma_f32 v78, -v77, v47, v78
	ds_read_b128 v[42:45], v97 offset:32064
	ds_read_b128 v[46:49], v97 offset:32320
	s_waitcnt lgkmcnt(8)
	v_fma_f32 v79, -v8, v84, v79
	v_fma_f32 v80, -v8, v88, v80
	v_fma_f32 v79, -v9, v85, v79
	v_fma_f32 v80, -v9, v89, v80
	v_fma_f32 v79, -v10, v86, v79
	v_fma_f32 v80, -v10, v90, v80
	v_fma_f32 v79, -v11, v87, v79
	v_fma_f32 v80, -v11, v91, v80
	ds_read_b128 v[84:87], v97 offset:32080
	ds_read_b128 v[88:91], v97 offset:32336
	s_waitcnt lgkmcnt(8)
	v_fma_f32 v79, -v12, v92, v79
	v_fma_f32 v80, -v12, v98, v80
	v_fma_f32 v79, -v13, v93, v79
	v_fma_f32 v80, -v13, v99, v80
	v_fma_f32 v79, -v14, v94, v79
	v_fma_f32 v80, -v14, v100, v80
	v_fma_f32 v79, -v15, v95, v79
	v_fma_f32 v80, -v15, v101, v80
	ds_read_b128 v[92:95], v97 offset:32096
	ds_read_b128 v[98:101], v97 offset:32352
	s_waitcnt lgkmcnt(8)
	v_fma_f32 v79, -v16, v102, v79
	v_fma_f32 v80, -v16, v106, v80
	v_fma_f32 v79, -v17, v103, v79
	v_fma_f32 v80, -v17, v107, v80
	v_fma_f32 v79, -v18, v104, v79
	v_fma_f32 v80, -v18, v108, v80
	v_fma_f32 v79, -v19, v105, v79
	v_fma_f32 v80, -v19, v109, v80
	ds_read_b128 v[102:105], v97 offset:32112
	ds_read_b128 v[106:109], v97 offset:32368
	s_waitcnt lgkmcnt(8)
	v_fma_f32 v79, -v20, v110, v79
	v_fma_f32 v80, -v20, v114, v80
	v_fma_f32 v79, -v21, v111, v79
	v_fma_f32 v80, -v21, v115, v80
	v_fma_f32 v79, -v22, v112, v79
	v_fma_f32 v80, -v22, v116, v80
	v_fma_f32 v79, -v23, v113, v79
	v_fma_f32 v80, -v23, v117, v80
	ds_read_b128 v[110:113], v97 offset:32128
	ds_read_b128 v[114:117], v97 offset:32384
	s_waitcnt lgkmcnt(8)
	v_fma_f32 v79, -v24, v42, v79
	v_fma_f32 v80, -v24, v46, v80
	v_fma_f32 v79, -v25, v43, v79
	v_fma_f32 v80, -v25, v47, v80
	v_fma_f32 v79, -v26, v44, v79
	v_fma_f32 v80, -v26, v48, v80
	v_fma_f32 v79, -v27, v45, v79
	v_fma_f32 v80, -v27, v49, v80
	ds_read_b128 v[42:45], v97 offset:32144
	ds_read_b128 v[46:49], v97 offset:32400
	s_waitcnt lgkmcnt(8)
	v_fma_f32 v79, -v28, v84, v79
	v_fma_f32 v80, -v28, v88, v80
	v_fma_f32 v79, -v29, v85, v79
	v_fma_f32 v80, -v29, v89, v80
	v_fma_f32 v79, -v30, v86, v79
	v_fma_f32 v80, -v30, v90, v80
	v_fma_f32 v79, -v31, v87, v79
	v_fma_f32 v80, -v31, v91, v80
	ds_read_b128 v[84:87], v97 offset:32160
	ds_read_b128 v[88:91], v97 offset:32416
	s_waitcnt lgkmcnt(8)
; NI void dn_chunk_local(const P& p, int dh, int n, char* lds) {
;     ...
;       for (int i = hb * 32; i < hb * 32 + 32; ++i) {
;         float a = x[i];
; #pragma unroll
;         for (int j = 0; j < i; ++j) a -= Ls[i * 64 + j] * x[j];
;         x[i] = a;
;         if ((i & 3) == 3) __builtin_amdgcn_sched_barrier(0);
;       }
	v_fma_f32 v79, -v32, v92, v79
	v_fma_f32 v80, -v32, v98, v80
	v_fma_f32 v79, -v33, v93, v79
	v_fma_f32 v80, -v33, v99, v80
	v_fma_f32 v79, -v34, v94, v79
	v_fma_f32 v80, -v34, v100, v80
	v_fma_f32 v79, -v35, v95, v79
	v_fma_f32 v80, -v35, v101, v80
	ds_read_b128 v[92:95], v97 offset:32176
	ds_read_b128 v[98:101], v97 offset:32432
	s_waitcnt lgkmcnt(8)
	v_fma_f32 v79, -v36, v102, v79
	v_fma_f32 v80, -v36, v106, v80
	v_fma_f32 v79, -v37, v103, v79
	v_fma_f32 v80, -v37, v107, v80
	v_fma_f32 v79, -v38, v104, v79
	v_fma_f32 v80, -v38, v108, v80
	v_fma_f32 v79, -v39, v105, v79
	v_fma_f32 v80, -v39, v109, v80
	ds_read_b128 v[102:105], v97 offset:32192
	ds_read_b128 v[106:109], v97 offset:32448
	s_waitcnt lgkmcnt(8)
	v_fma_f32 v79, -v52, v110, v79
	v_fma_f32 v80, -v52, v114, v80
	v_fma_f32 v79, -v53, v111, v79
	v_fma_f32 v80, -v53, v115, v80
	v_fma_f32 v79, -v54, v112, v79
	v_fma_f32 v80, -v54, v116, v80
	v_fma_f32 v79, -v55, v113, v79
	v_fma_f32 v80, -v55, v117, v80
	ds_read_b128 v[110:113], v97 offset:32208
	ds_read_b128 v[114:117], v97 offset:32464
	s_waitcnt lgkmcnt(8)
	v_fma_f32 v79, -v56, v42, v79
	v_fma_f32 v80, -v56, v46, v80
	v_fma_f32 v79, -v57, v43, v79
	v_fma_f32 v80, -v57, v47, v80
	v_fma_f32 v79, -v58, v44, v79
	v_fma_f32 v80, -v58, v48, v80
	v_fma_f32 v79, -v59, v45, v79
	v_fma_f32 v80, -v59, v49, v80
	ds_read_b128 v[42:45], v97 offset:32224
	ds_read_b128 v[46:49], v97 offset:32480
	s_waitcnt lgkmcnt(8)
	v_fma_f32 v79, -v60, v84, v79
	v_fma_f32 v80, -v60, v88, v80
	v_fma_f32 v79, -v61, v85, v79
	v_fma_f32 v80, -v61, v89, v80
	v_fma_f32 v79, -v62, v86, v79
	v_fma_f32 v80, -v62, v90, v80
	v_fma_f32 v79, -v63, v87, v79
	v_fma_f32 v80, -v63, v91, v80
	ds_read_b128 v[84:87], v97 offset:32512
	ds_read_b128 v[88:91], v97 offset:32768
	s_waitcnt lgkmcnt(8)
	v_fma_f32 v79, -v64, v92, v79
	v_fma_f32 v80, -v64, v98, v80
	v_fma_f32 v79, -v65, v93, v79
	v_fma_f32 v80, -v65, v99, v80
	v_fma_f32 v79, -v66, v94, v79
	v_fma_f32 v80, -v66, v100, v80
	v_fma_f32 v79, -v67, v95, v79
	v_fma_f32 v80, -v67, v101, v80
	ds_read_b128 v[92:95], v97 offset:32528
	ds_read_b128 v[98:101], v97 offset:32784
	s_waitcnt lgkmcnt(8)
	v_fma_f32 v79, -v68, v102, v79
	v_fma_f32 v80, -v68, v106, v80
	v_fma_f32 v79, -v69, v103, v79
	v_fma_f32 v80, -v69, v107, v80
	v_fma_f32 v79, -v70, v104, v79
	v_fma_f32 v80, -v70, v108, v80
	v_fma_f32 v79, -v71, v105, v79
	v_fma_f32 v80, -v71, v109, v80
	ds_read_b128 v[102:105], v97 offset:32544
	ds_read_b128 v[106:109], v97 offset:32800
	s_waitcnt lgkmcnt(8)
	v_fma_f32 v79, -v72, v110, v79
	v_fma_f32 v80, -v72, v114, v80
	v_fma_f32 v79, -v73, v111, v79
	v_fma_f32 v80, -v73, v115, v80
	v_fma_f32 v79, -v74, v112, v79
	v_fma_f32 v80, -v74, v116, v80
	v_fma_f32 v79, -v75, v113, v79
	v_fma_f32 v80, -v75, v117, v80
	ds_read_b128 v[110:113], v97 offset:32560
	ds_read_b128 v[114:117], v97 offset:32816
	s_waitcnt lgkmcnt(8)
	v_fma_f32 v79, -v76, v42, v79
	v_fma_f32 v80, -v76, v46, v80
	v_fma_f32 v79, -v77, v43, v79
	v_fma_f32 v80, -v77, v47, v80
	v_fma_f32 v79, -v78, v44, v79
	v_fma_f32 v80, -v78, v48, v80
	v_fma_f32 v80, -v79, v49, v80
	ds_read_b128 v[42:45], v97 offset:32576
	ds_read_b128 v[46:49], v97 offset:32832
	s_waitcnt lgkmcnt(8)
	v_fma_f32 v81, -v8, v84, v81
	v_fma_f32 v82, -v8, v88, v82
	v_fma_f32 v81, -v9, v85, v81
	v_fma_f32 v82, -v9, v89, v82
	v_fma_f32 v81, -v10, v86, v81
	v_fma_f32 v82, -v10, v90, v82
	v_fma_f32 v81, -v11, v87, v81
	v_fma_f32 v82, -v11, v91, v82
	ds_read_b128 v[84:87], v97 offset:32592
	ds_read_b128 v[88:91], v97 offset:32848
	s_waitcnt lgkmcnt(8)
	v_fma_f32 v81, -v12, v92, v81
	v_fma_f32 v82, -v12, v98, v82
	v_fma_f32 v81, -v13, v93, v81
	v_fma_f32 v82, -v13, v99, v82
	v_fma_f32 v81, -v14, v94, v81
	v_fma_f32 v82, -v14, v100, v82
	v_fma_f32 v81, -v15, v95, v81
	v_fma_f32 v82, -v15, v101, v82
	ds_read_b128 v[92:95], v97 offset:32608
	ds_read_b128 v[98:101], v97 offset:32864
	s_waitcnt lgkmcnt(8)
	v_fma_f32 v81, -v16, v102, v81
	v_fma_f32 v82, -v16, v106, v82
	v_fma_f32 v81, -v17, v103, v81
	v_fma_f32 v82, -v17, v107, v82
	v_fma_f32 v81, -v18, v104, v81
	v_fma_f32 v82, -v18, v108, v82
	v_fma_f32 v81, -v19, v105, v81
	v_fma_f32 v82, -v19, v109, v82
	ds_read_b128 v[102:105], v97 offset:32624
	ds_read_b128 v[106:109], v97 offset:32880
	s_waitcnt lgkmcnt(8)
	v_fma_f32 v81, -v20, v110, v81
	v_fma_f32 v82, -v20, v114, v82
	v_fma_f32 v81, -v21, v111, v81
	v_fma_f32 v82, -v21, v115, v82
	v_fma_f32 v81, -v22, v112, v81
	v_fma_f32 v82, -v22, v116, v82
	v_fma_f32 v81, -v23, v113, v81
	v_fma_f32 v82, -v23, v117, v82
	ds_read_b128 v[110:113], v97 offset:32640
	ds_read_b128 v[114:117], v97 offset:32896
	s_waitcnt lgkmcnt(8)
	v_fma_f32 v81, -v24, v42, v81
	v_fma_f32 v82, -v24, v46, v82
	v_fma_f32 v81, -v25, v43, v81
	v_fma_f32 v82, -v25, v47, v82
	v_fma_f32 v81, -v26, v44, v81
	v_fma_f32 v82, -v26, v48, v82
	v_fma_f32 v81, -v27, v45, v81
	v_fma_f32 v82, -v27, v49, v82
	ds_read_b128 v[42:45], v97 offset:32656
	ds_read_b128 v[46:49], v97 offset:32912
	s_waitcnt lgkmcnt(8)
	v_fma_f32 v81, -v28, v84, v81
	v_fma_f32 v82, -v28, v88, v82
	v_fma_f32 v81, -v29, v85, v81
	v_fma_f32 v82, -v29, v89, v82
	v_fma_f32 v81, -v30, v86, v81
	v_fma_f32 v82, -v30, v90, v82
	v_fma_f32 v81, -v31, v87, v81
	v_fma_f32 v82, -v31, v91, v82
	ds_read_b128 v[84:87], v97 offset:32672
	ds_read_b128 v[88:91], v97 offset:32928
	s_waitcnt lgkmcnt(8)
	v_fma_f32 v81, -v32, v92, v81
	v_fma_f32 v82, -v32, v98, v82
	v_fma_f32 v81, -v33, v93, v81
	v_fma_f32 v82, -v33, v99, v82
	v_fma_f32 v81, -v34, v94, v81
	v_fma_f32 v82, -v34, v100, v82
	v_fma_f32 v81, -v35, v95, v81
	v_fma_f32 v82, -v35, v101, v82
	ds_read_b128 v[92:95], v97 offset:32688
	ds_read_b128 v[98:101], v97 offset:32944
	s_waitcnt lgkmcnt(8)
; NI void dn_chunk_local(const P& p, int dh, int n, char* lds) {
;     ...
;       for (int i = hb * 32; i < hb * 32 + 32; ++i) {
;         float a = x[i];
; #pragma unroll
;         for (int j = 0; j < i; ++j) a -= Ls[i * 64 + j] * x[j];
;         x[i] = a;
;         if ((i & 3) == 3) __builtin_amdgcn_sched_barrier(0);
;       }
;     }
;     if (col < 128) {
;       uint4* dst = (uint4*)((bf16_t*)(ws + WS_DU) + ((size_t)(dh * NCH + n) * 128 + col) * 64);
	v_fma_f32 v81, -v36, v102, v81
	v_fma_f32 v82, -v36, v106, v82
	v_fma_f32 v81, -v37, v103, v81
	v_fma_f32 v82, -v37, v107, v82
	v_fma_f32 v81, -v38, v104, v81
	v_fma_f32 v82, -v38, v108, v82
	v_fma_f32 v81, -v39, v105, v81
	v_fma_f32 v82, -v39, v109, v82
	ds_read_b128 v[102:105], v97 offset:32704
	ds_read_b128 v[106:109], v97 offset:32960
	s_waitcnt lgkmcnt(8)
	v_fma_f32 v81, -v52, v110, v81
	v_fma_f32 v82, -v52, v114, v82
	v_fma_f32 v81, -v53, v111, v81
	v_fma_f32 v82, -v53, v115, v82
	v_fma_f32 v81, -v54, v112, v81
	v_fma_f32 v82, -v54, v116, v82
	v_fma_f32 v81, -v55, v113, v81
	v_fma_f32 v82, -v55, v117, v82
	ds_read_b128 v[110:113], v97 offset:32720
	ds_read_b128 v[114:117], v97 offset:32976
	s_waitcnt lgkmcnt(8)
	v_fma_f32 v81, -v56, v42, v81
	v_fma_f32 v82, -v56, v46, v82
	v_fma_f32 v81, -v57, v43, v81
	v_fma_f32 v82, -v57, v47, v82
	v_fma_f32 v81, -v58, v44, v81
	v_fma_f32 v82, -v58, v48, v82
	v_fma_f32 v81, -v59, v45, v81
	v_fma_f32 v82, -v59, v49, v82
	ds_read_b128 v[42:45], v97 offset:32736
	ds_read_b128 v[46:49], v97 offset:32992
	s_waitcnt lgkmcnt(8)
	v_fma_f32 v81, -v60, v84, v81
	v_fma_f32 v82, -v60, v88, v82
	v_fma_f32 v81, -v61, v85, v81
	v_fma_f32 v82, -v61, v89, v82
	v_fma_f32 v81, -v62, v86, v81
	v_fma_f32 v82, -v62, v90, v82
	v_fma_f32 v81, -v63, v87, v81
	v_fma_f32 v82, -v63, v91, v82
	ds_read_b128 v[84:87], v97 offset:32752
	ds_read_b128 v[88:91], v97 offset:33008
	s_waitcnt lgkmcnt(8)
	v_fma_f32 v81, -v64, v92, v81
	v_fma_f32 v82, -v64, v98, v82
	v_fma_f32 v81, -v65, v93, v81
	v_fma_f32 v82, -v65, v99, v82
	v_fma_f32 v81, -v66, v94, v81
	v_fma_f32 v82, -v66, v100, v82
	v_fma_f32 v81, -v67, v95, v81
	v_fma_f32 v82, -v67, v101, v82
	ds_read_b128 v[92:95], v97 offset:33024
	ds_read_b128 v[98:101], v97 offset:33040
	s_waitcnt lgkmcnt(8)
	v_fma_f32 v81, -v68, v102, v81
	v_fma_f32 v82, -v68, v106, v82
	v_fma_f32 v81, -v69, v103, v81
	v_fma_f32 v82, -v69, v107, v82
	v_fma_f32 v81, -v70, v104, v81
	v_fma_f32 v82, -v70, v108, v82
	v_fma_f32 v81, -v71, v105, v81
	v_fma_f32 v82, -v71, v109, v82
	ds_read_b128 v[102:105], v97 offset:33056
	ds_read_b128 v[106:109], v97 offset:33072
	s_waitcnt lgkmcnt(8)
	v_fma_f32 v81, -v72, v110, v81
	v_fma_f32 v82, -v72, v114, v82
	v_fma_f32 v81, -v73, v111, v81
	v_fma_f32 v82, -v73, v115, v82
	v_fma_f32 v81, -v74, v112, v81
	v_fma_f32 v82, -v74, v116, v82
	v_fma_f32 v81, -v75, v113, v81
	v_fma_f32 v82, -v75, v117, v82
	ds_read_b128 v[110:113], v97 offset:33088
	ds_read_b128 v[114:117], v97 offset:33104
	s_waitcnt lgkmcnt(8)
	v_fma_f32 v81, -v76, v42, v81
	v_fma_f32 v82, -v76, v46, v82
	v_fma_f32 v81, -v77, v43, v81
	v_fma_f32 v82, -v77, v47, v82
	v_fma_f32 v81, -v78, v44, v81
	v_fma_f32 v82, -v78, v48, v82
	v_fma_f32 v81, -v79, v45, v81
	v_fma_f32 v82, -v79, v49, v82
	ds_read_b128 v[42:45], v97 offset:33120
	ds_read_b128 v[46:49], v97 offset:33136
	s_waitcnt lgkmcnt(8)
	v_fma_f32 v81, -v80, v84, v81
	v_fma_f32 v82, -v80, v88, v82
	v_fma_f32 v82, -v81, v89, v82
	ds_read_b128 v[84:87], v97 offset:33152
	ds_read_b128 v[88:91], v97 offset:33168
	s_waitcnt lgkmcnt(9)
	v_fma_f32 v83, -v8, v92, v83
	v_fma_f32 v83, -v9, v93, v83
	v_fma_f32 v83, -v10, v94, v83
	v_fma_f32 v83, -v11, v95, v83
	ds_read_b128 v[92:95], v97 offset:33184
	s_waitcnt lgkmcnt(9)
	v_fma_f32 v83, -v12, v98, v83
	v_fma_f32 v83, -v13, v99, v83
	v_fma_f32 v83, -v14, v100, v83
	v_fma_f32 v83, -v15, v101, v83
	ds_read_b128 v[98:101], v97 offset:33200
	s_waitcnt lgkmcnt(9)
	v_fma_f32 v83, -v16, v102, v83
	v_fma_f32 v83, -v17, v103, v83
	v_fma_f32 v83, -v18, v104, v83
	v_fma_f32 v83, -v19, v105, v83
	ds_read_b128 v[102:105], v97 offset:33216
	s_waitcnt lgkmcnt(9)
	v_fma_f32 v83, -v20, v106, v83
	v_fma_f32 v83, -v21, v107, v83
	v_fma_f32 v83, -v22, v108, v83
	v_fma_f32 v83, -v23, v109, v83
	ds_read_b128 v[106:109], v97 offset:33232
	s_waitcnt lgkmcnt(9)
	v_fma_f32 v83, -v24, v110, v83
	v_fma_f32 v83, -v25, v111, v83
	v_fma_f32 v83, -v26, v112, v83
	v_fma_f32 v83, -v27, v113, v83
	ds_read_b128 v[110:113], v97 offset:33248
	s_waitcnt lgkmcnt(9)
	v_fma_f32 v83, -v28, v114, v83
	v_fma_f32 v83, -v29, v115, v83
	v_fma_f32 v83, -v30, v116, v83
	v_fma_f32 v83, -v31, v117, v83
	ds_read_b128 v[114:117], v97 offset:33264
	s_waitcnt lgkmcnt(9)
	v_fma_f32 v83, -v32, v42, v83
	v_fma_f32 v83, -v33, v43, v83
	v_fma_f32 v83, -v34, v44, v83
	v_fma_f32 v83, -v35, v45, v83
	s_waitcnt lgkmcnt(8)
	v_fma_f32 v83, -v36, v46, v83
	v_fma_f32 v83, -v37, v47, v83
	v_fma_f32 v83, -v38, v48, v83
	v_fma_f32 v83, -v39, v49, v83
	s_waitcnt lgkmcnt(7)
	v_fma_f32 v83, -v52, v84, v83
	v_fma_f32 v83, -v53, v85, v83
	v_fma_f32 v83, -v54, v86, v83
	v_fma_f32 v83, -v55, v87, v83
	s_waitcnt lgkmcnt(6)
	v_fma_f32 v83, -v56, v88, v83
	v_fma_f32 v83, -v57, v89, v83
	v_fma_f32 v83, -v58, v90, v83
	v_fma_f32 v83, -v59, v91, v83
	s_waitcnt lgkmcnt(5)
	v_fma_f32 v83, -v60, v92, v83
	v_fma_f32 v83, -v61, v93, v83
	v_fma_f32 v83, -v62, v94, v83
	v_fma_f32 v83, -v63, v95, v83
	s_waitcnt lgkmcnt(4)
	v_fma_f32 v83, -v64, v98, v83
	v_fma_f32 v83, -v65, v99, v83
	v_fma_f32 v83, -v66, v100, v83
	v_fma_f32 v83, -v67, v101, v83
	s_waitcnt lgkmcnt(3)
	v_fma_f32 v83, -v68, v102, v83
	v_fma_f32 v83, -v69, v103, v83
	v_fma_f32 v83, -v70, v104, v83
	v_fma_f32 v83, -v71, v105, v83
	s_waitcnt lgkmcnt(2)
	v_fma_f32 v83, -v72, v106, v83
	v_fma_f32 v83, -v73, v107, v83
	v_fma_f32 v83, -v74, v108, v83
	v_fma_f32 v83, -v75, v109, v83
	s_waitcnt lgkmcnt(1)
	v_fma_f32 v83, -v76, v110, v83
	v_fma_f32 v83, -v77, v111, v83
	v_fma_f32 v83, -v78, v112, v83
	v_fma_f32 v83, -v79, v113, v83
	s_waitcnt lgkmcnt(0)
	v_fma_f32 v83, -v80, v114, v83
	v_fma_f32 v83, -v81, v115, v83
	v_fma_f32 v83, -v82, v116, v83
	s_mov_b64 s[28:29], exec
	s_mul_i32 s16, s0, 0x2100
	s_add_i32 s16, s16, s27
	s_mov_b32 s17, 0
	s_lshl_b64 s[16:17], s[16:17], 8
	s_and_b64 exec, s[28:29], s[22:23]
	s_cbranch_execz .Ldn_wstore
; DI unsigned pk2(float lo, float hi) { return (unsigned)f2bf(lo) | ((unsigned)f2bf(hi) << 16); }
; NI void dn_chunk_local(const P& p, int dh, int n, char* lds) {
;     ...
;     if (col < 128) {
;       uint4* dst = (uint4*)((bf16_t*)(ws + WS_DU) + ((size_t)(dh * NCH + n) * 128 + col) * 64);
; #pragma unroll
;       for (int i = 0; i < 8; ++i) dst[i] = make_uint4(pk2(x[8 * i], x[8 * i + 1]), pk2(x[8 * i + 2], x[8 * i + 3]), pk2(x[8 * i + 4], x[8 * i + 5]), pk2(x[8 * i + 6], x[8 * i + 7]));
	s_lshl_b64 s[36:37], s[80:81], 14
	v_readlane_b32 s1, v253, 6
	v_lshlrev_b32_e32 v118, 7, v4
	s_add_u32 s36, s1, s36
	v_readlane_b32 s1, v253, 7
	v_mov_b32_e32 v119, 0
	s_addc_u32 s37, s1, s37
	s_nop 0
	v_lshl_add_u64 v[118:119], s[36:37], 0, v[118:119]
	v_cvt_pk_bf16_f32 v84, v8, v9
	v_cvt_pk_bf16_f32 v85, v10, v11
	v_cvt_pk_bf16_f32 v86, v12, v13
	v_cvt_pk_bf16_f32 v87, v14, v15
	s_nop 0
	global_store_dwordx4 v[118:119], v[84:87], off offset:0
	v_cvt_pk_bf16_f32 v88, v16, v17
	v_cvt_pk_bf16_f32 v89, v18, v19
	v_cvt_pk_bf16_f32 v90, v20, v21
	v_cvt_pk_bf16_f32 v91, v22, v23
	s_nop 0
	global_store_dwordx4 v[118:119], v[88:91], off offset:16
	v_cvt_pk_bf16_f32 v92, v24, v25
	v_cvt_pk_bf16_f32 v93, v26, v27
	v_cvt_pk_bf16_f32 v94, v28, v29
	v_cvt_pk_bf16_f32 v95, v30, v31
	s_nop 0
	global_store_dwordx4 v[118:119], v[92:95], off offset:32
	v_cvt_pk_bf16_f32 v98, v32, v33
	v_cvt_pk_bf16_f32 v99, v34, v35
	v_cvt_pk_bf16_f32 v100, v36, v37
	v_cvt_pk_bf16_f32 v101, v38, v39
	s_nop 0
	global_store_dwordx4 v[118:119], v[98:101], off offset:48
	v_cvt_pk_bf16_f32 v102, v52, v53
	v_cvt_pk_bf16_f32 v103, v54, v55
	v_cvt_pk_bf16_f32 v104, v56, v57
	v_cvt_pk_bf16_f32 v105, v58, v59
	s_nop 0
	global_store_dwordx4 v[118:119], v[102:105], off offset:64
	v_cvt_pk_bf16_f32 v106, v60, v61
	v_cvt_pk_bf16_f32 v107, v62, v63
	v_cvt_pk_bf16_f32 v108, v64, v65
	v_cvt_pk_bf16_f32 v109, v66, v67
	s_nop 0
	global_store_dwordx4 v[118:119], v[106:109], off offset:80
	v_cvt_pk_bf16_f32 v110, v68, v69
	v_cvt_pk_bf16_f32 v111, v70, v71
	v_cvt_pk_bf16_f32 v112, v72, v73
	v_cvt_pk_bf16_f32 v113, v74, v75
	s_nop 0
	global_store_dwordx4 v[118:119], v[110:113], off offset:96
	v_cvt_pk_bf16_f32 v114, v76, v77
	v_cvt_pk_bf16_f32 v115, v78, v79
	v_cvt_pk_bf16_f32 v116, v80, v81
	v_cvt_pk_bf16_f32 v117, v82, v83
	s_nop 0
	global_store_dwordx4 v[118:119], v[114:117], off offset:112
